# attention: deep 8-slot LDS rings time-sharing the two 64KiB context images (images re-staged by LDS-DMA each round), V ring prologue issued ahead of the softmax; no static LDS growth
# baseline (speedup 1.0000x reference)
; #define LAS __attribute__((address_space(3)))
; __global__ void __launch_bounds__(NTHREADS, 2) mega(Args args) {
;     ...
;                     { const int oc0 = (ML + b * CTX) >> 3;
;                       for (int ci = tid; ci < 4096; ci += NTHREADS) { const int o = ci >> 7, wq = ci & 127;
;                           const u32x4 kv = *(const u32x4*)(KTp + ((size_t)((oc0 + o) * NH + h)) * 1024 + wq * 8);
;                           *(LAS u32x4*)(lds + o * 2048 + (wq & ~15) * 16 + ((wq & 15) ^ (o & 2)) * 16) = kv;
;                           const u32x4 vv = *(const u32x4*)(VTp + ((size_t)((oc0 + o) * NH + h)) * 1024 + wq * 8);
;                           *(LAS u32x4*)(lds + 65536 + o * 2048 + wq * 16) = vv; }
.LBB9_659:
	s_ashr_i32 s4, s70, 6
	s_lshl_b32 s71, s4, 8
	s_bfe_u32 s72, s70, 0x40002
	s_addk_i32 s71, 0x2000
	s_barrier
	s_ashr_i32 s54, s71, 3
	s_lshl_b32 s54, s54, 4
	s_add_i32 s54, s54, s72
	s_lshl_b32 s54, s54, 11
	s_lshr_b32 s55, s57, 1
	s_lshl_b32 s55, s55, 15
	s_add_i32 s54, s54, s55
	s_and_b32 s55, s57, 1
	s_lshl_b32 s55, s55, 10
	s_add_i32 s54, s54, s55
	s_lshr_b32 s55, s57, 2
	s_lshl_b32 s55, s55, 1
	v_xor_b32_e32 v218, s55, v164
	v_lshlrev_b32_e32 v218, 4, v218
	v_lshlrev_b32_e32 v219, 4, v164
	v_add_u32_e32 v218, s54, v218
	v_add_u32_e32 v219, s54, v219
	ds_read_b64 v[220:221], v241 offset:192
	s_waitcnt lgkmcnt(0)
	v_add_co_u32_e32 v234, vcc, 0x21f00000, v220
	s_nop 1
	v_addc_co_u32_e32 v235, vcc, 0, v221, vcc
	v_add_co_u32_e32 v236, vcc, 0x24300000, v220
	s_nop 1
	v_addc_co_u32_e32 v237, vcc, 0, v221, vcc
	v_add_co_u32_e32 v234, vcc, v234, v218
	s_nop 1
	v_addc_co_u32_e32 v235, vcc, 0, v235, vcc
	v_add_co_u32_e32 v236, vcc, v236, v219
	s_nop 1
	v_addc_co_u32_e32 v237, vcc, 0, v237, vcc
	v_mov_b32_e32 v222, v234
	v_mov_b32_e32 v223, v235
	s_lshl_b32 s55, s57, 10
	s_add_i32 m0, s55, 0
	s_nop 0
	global_load_lds_dwordx4 v[222:223], off
	v_add_co_u32_e32 v222, vcc, 0x20000, v222
	s_nop 1
	v_addc_co_u32_e32 v223, vcc, 0, v223, vcc
	s_add_i32 m0, s55, 8192
	s_nop 0
	global_load_lds_dwordx4 v[222:223], off
	v_add_co_u32_e32 v222, vcc, 0x20000, v222
	s_nop 1
	v_addc_co_u32_e32 v223, vcc, 0, v223, vcc
	s_add_i32 m0, s55, 16384
	s_nop 0
	global_load_lds_dwordx4 v[222:223], off
	v_add_co_u32_e32 v222, vcc, 0x20000, v222
	s_nop 1
	v_addc_co_u32_e32 v223, vcc, 0, v223, vcc
	s_add_i32 m0, s55, 24576
	s_nop 0
	global_load_lds_dwordx4 v[222:223], off
	v_add_co_u32_e32 v222, vcc, 0x20000, v222
	s_nop 1
	v_addc_co_u32_e32 v223, vcc, 0, v223, vcc
	s_add_i32 m0, s55, 32768
	s_nop 0
	global_load_lds_dwordx4 v[222:223], off
	v_add_co_u32_e32 v222, vcc, 0x20000, v222
	s_nop 1
	v_addc_co_u32_e32 v223, vcc, 0, v223, vcc
	s_add_i32 m0, s55, 40960
	s_nop 0
	global_load_lds_dwordx4 v[222:223], off
	v_add_co_u32_e32 v222, vcc, 0x20000, v222
	s_nop 1
	v_addc_co_u32_e32 v223, vcc, 0, v223, vcc
	s_add_i32 m0, s55, 49152
	s_nop 0
	global_load_lds_dwordx4 v[222:223], off
	v_add_co_u32_e32 v222, vcc, 0x20000, v222
	s_nop 1
	v_addc_co_u32_e32 v223, vcc, 0, v223, vcc
	s_add_i32 m0, s55, 57344
	s_nop 0
	global_load_lds_dwordx4 v[222:223], off
	s_waitcnt vmcnt(0)

; #define ATT_VLOAD(buf, p) do { const bf16_t* vp_ = vloc + (size_t)((p) * 8 * NH) * 1024; \
;         _Pragma("unroll") for (int df = 0; df < 8; ++df) va[buf][df] = *(const bf16x8*)(vp_ + df * 128); } while (0)
; template <bool LOCAL>
; __device__ __forceinline__ void attn_unit(const bf16_t* Q, const bf16_t* KT, const bf16_t* VT, bf16_t* O, LAS unsigned char* lds, int b, int h, int r, int w, int tq, int lane) {
;     ...
;     float mx = -INFINITY;
; #pragma unroll
;     for (int i = 0; i < 2 * NP; ++i) mx = fmaxf(mx, fmaxf(fmaxf(s[i][0], s[i][1]), fmaxf(s[i][2], s[i][3])));
;     mx = fmaxf(mx, __shfl_xor(mx, 16)); mx = fmaxf(mx, __shfl_xor(mx, 32));
;     ...
;     if (LOCAL) {
;         const bf16_t* vloc = VT + ((size_t)(((rgl >> 3) + g) * NH + h)) * 1024 + q * 8;
;         bf16x8 va[2][8];
;     ...
;         ATT_VLOAD(0, 0);
; #pragma unroll
;         for (int p = 0; p < 8; ++p) {
;             __builtin_amdgcn_s_barrier();
;             if (p + 1 < 8) ATT_VLOAD((p + 1) & 1, p + 1);
.LBB9_673:
	s_or_b64 exec, exec, s[34:35]
	s_barrier
	s_lshl_b32 s54, s57, 10
	s_add_i32 s59, s54, 0x0
	v_lshlrev_b32_e32 v218, 4, v164
	v_add_u32_e32 v218, s28, v218
	ds_read_b64 v[220:221], v241 offset:192
	s_waitcnt lgkmcnt(0)
	v_add_co_u32_e32 v220, vcc, 0x24300000, v220
	s_nop 1
	v_addc_co_u32_e32 v221, vcc, 0, v221, vcc
	v_add_co_u32_e32 v220, vcc, v220, v218
	s_nop 1
	v_addc_co_u32_e32 v221, vcc, 0, v221, vcc
	v_add_co_u32_e32 v226, vcc, 0x400, v220
	s_nop 1
	v_addc_co_u32_e32 v227, vcc, 0, v221, vcc
	s_and_b32 s55, s57, 3
	s_lshl_b32 s55, s55, 1
	s_add_i32 s55, s55, -1
	s_max_i32 s55, s55, 0
	s_min_i32 s55, s55, 4
	v_add_u32_e32 v219, s55, v165
	v_lshlrev_b32_e32 v224, 4, v166
	v_lshl_add_u32 v219, v219, 10, v224
	s_add_i32 m0, s59, 0
	s_nop 0
	global_load_lds_dwordx4 v[220:221], off
	s_add_i32 m0, s59, 8192
	s_nop 0
	global_load_lds_dwordx4 v[226:227], off
	s_add_i32 m0, s59, 16384
	v_add_co_u32_e32 v222, vcc, s6, v220
	s_nop 1
	v_addc_co_u32_e32 v223, vcc, 0, v221, vcc
	global_load_lds_dwordx4 v[222:223], off
	s_add_i32 m0, s59, 24576
	v_add_co_u32_e32 v222, vcc, s6, v226
	s_nop 1
	v_addc_co_u32_e32 v223, vcc, 0, v227, vcc
	global_load_lds_dwordx4 v[222:223], off
	s_add_i32 m0, s59, 32768
	v_add_co_u32_e32 v222, vcc, s7, v220
	s_nop 1
	v_addc_co_u32_e32 v223, vcc, 0, v221, vcc
	global_load_lds_dwordx4 v[222:223], off
	s_add_i32 m0, s59, 40960
	v_add_co_u32_e32 v222, vcc, s7, v226
	s_nop 1
	v_addc_co_u32_e32 v223, vcc, 0, v227, vcc
	global_load_lds_dwordx4 v[222:223], off
	s_add_i32 m0, s59, 49152
	v_add_co_u32_e32 v222, vcc, s2, v220
	s_nop 1
	v_addc_co_u32_e32 v223, vcc, 0, v221, vcc
	global_load_lds_dwordx4 v[222:223], off
	v_max_f32_e32 v66, v126, v126
	v_max_f32_e32 v67, v134, v134
	v_max_f32_e32 v66, v67, v66
	v_max_f32_e32 v67, v123, v123
	v_max_f32_e32 v68, v129, v129
	v_max_f32_e32 v67, v68, v67
	v_max3_f32 v66, v133, v132, v66
	v_max3_f32 v67, v128, v127, v67
	v_max3_f32 v66, v66, s16, v67
	v_max_f32_e32 v67, v118, v118
	v_max_f32_e32 v68, v125, v125
	v_max_f32_e32 v67, v68, v67
	v_max_f32_e32 v68, v115, v115
	v_max_f32_e32 v69, v121, v121
	v_max_f32_e32 v68, v69, v68
	v_max3_f32 v67, v124, v122, v67
	v_max3_f32 v68, v120, v119, v68
	v_max3_f32 v66, v66, v67, v68
	v_max_f32_e32 v67, v110, v110
	v_max_f32_e32 v68, v117, v117
	v_max_f32_e32 v67, v68, v67
	v_max_f32_e32 v68, v113, v113
	v_max_f32_e32 v69, v135, v135
	v_max_f32_e32 v68, v69, v68
	v_max3_f32 v67, v116, v114, v67
	v_max3_f32 v68, v112, v111, v68
	v_max3_f32 v66, v66, v67, v68
	v_max_f32_e32 v67, v102, v102
	v_max_f32_e32 v68, v109, v109
	v_max_f32_e32 v67, v68, v67
	v_max_f32_e32 v68, v99, v99
	v_max_f32_e32 v69, v105, v105
	v_max_f32_e32 v68, v69, v68
	v_max3_f32 v67, v108, v107, v67
	v_max3_f32 v68, v104, v103, v68
	v_max3_f32 v66, v66, v67, v68
	v_max_f32_e32 v67, v94, v94
	v_max_f32_e32 v68, v101, v101
	v_max_f32_e32 v67, v68, v67
	v_max_f32_e32 v68, v91, v91
	v_max_f32_e32 v69, v97, v97
	v_max_f32_e32 v68, v69, v68
	v_max3_f32 v67, v100, v98, v67
	v_max3_f32 v68, v96, v95, v68
	v_max3_f32 v66, v66, v67, v68
	v_max_f32_e32 v67, v86, v86
	v_max_f32_e32 v68, v93, v93
	v_max_f32_e32 v67, v68, v67
	v_max_f32_e32 v68, v89, v89
	v_max_f32_e32 v69, v138, v138
	v_max_f32_e32 v68, v69, v68
	v_max3_f32 v67, v92, v90, v67
	v_max3_f32 v68, v88, v87, v68
	v_max3_f32 v66, v66, v67, v68
	v_max_f32_e32 v67, v139, v139
	v_max_f32_e32 v68, v141, v141
	v_max_f32_e32 v67, v68, v67
	v_max_f32_e32 v68, v197, v197
	v_max_f32_e32 v69, v199, v199
	v_max_f32_e32 v68, v69, v68
	v_max3_f32 v67, v137, v136, v67
	v_max3_f32 v68, v195, v140, v68
	v_max3_f32 v66, v66, v67, v68
	v_max_f32_e32 v67, v200, v200
	v_max_f32_e32 v68, v202, v202
	v_max_f32_e32 v67, v68, v67
	v_max_f32_e32 v68, v204, v204
	v_max_f32_e32 v69, v205, v205
	v_max_f32_e32 v68, v69, v68
	v_max3_f32 v67, v198, v196, v67
	v_max3_f32 v68, v203, v201, v68
	v_max3_f32 v66, v66, v67, v68
	v_max_f32_e32 v67, v5, v5
	v_max_f32_e32 v68, v4, v4
	v_max_f32_e32 v67, v68, v67
	v_max_f32_e32 v68, v13, v13
	v_max_f32_e32 v69, v12, v12
	v_max_f32_e32 v68, v69, v68
	v_max3_f32 v67, v2, v3, v67
	v_max3_f32 v68, v10, v11, v68
	v_max3_f32 v66, v66, v67, v68
	v_max_f32_e32 v67, v9, v9
	v_max_f32_e32 v68, v8, v8
	v_max_f32_e32 v67, v68, v67
	v_max_f32_e32 v68, v21, v21
	v_max_f32_e32 v69, v20, v20
	v_max_f32_e32 v68, v69, v68
	v_max3_f32 v67, v6, v7, v67
	v_max3_f32 v68, v18, v19, v68
	v_max3_f32 v66, v66, v67, v68
	v_max_f32_e32 v67, v17, v17
	v_max_f32_e32 v68, v16, v16
	v_max_f32_e32 v67, v68, v67
	v_max_f32_e32 v68, v29, v29
	v_max_f32_e32 v69, v28, v28
	v_max_f32_e32 v68, v69, v68
	v_max3_f32 v67, v14, v15, v67
	v_max3_f32 v68, v26, v27, v68
	v_max3_f32 v66, v66, v67, v68
	v_max_f32_e32 v67, v25, v25
	v_max_f32_e32 v68, v24, v24
	v_max_f32_e32 v67, v68, v67
	v_max_f32_e32 v68, v37, v37
	v_max_f32_e32 v69, v36, v36
	v_max_f32_e32 v68, v69, v68
	v_max3_f32 v67, v22, v23, v67
	v_max3_f32 v68, v34, v35, v68
	v_max3_f32 v66, v66, v67, v68
	v_max_f32_e32 v67, v33, v33
	v_max_f32_e32 v68, v32, v32
	v_max_f32_e32 v67, v68, v67
	v_max_f32_e32 v68, v45, v45
	v_max_f32_e32 v69, v44, v44
	v_max_f32_e32 v68, v69, v68
	v_max3_f32 v67, v30, v31, v67
	v_max3_f32 v68, v42, v43, v68
	v_max3_f32 v66, v66, v67, v68
	v_max_f32_e32 v67, v41, v41
	v_max_f32_e32 v68, v40, v40
	v_max_f32_e32 v67, v68, v67
	v_max_f32_e32 v68, v53, v53
	v_max_f32_e32 v69, v52, v52
	v_max_f32_e32 v68, v69, v68
	v_max3_f32 v67, v38, v39, v67
	v_max3_f32 v68, v50, v51, v68
	v_max3_f32 v66, v66, v67, v68
	v_max_f32_e32 v67, v49, v49
	v_max_f32_e32 v68, v48, v48
	v_max_f32_e32 v67, v68, v67
	v_max_f32_e32 v68, v61, v61
	v_max_f32_e32 v69, v60, v60
	v_max_f32_e32 v68, v69, v68
	v_max3_f32 v67, v46, v47, v67
	v_max3_f32 v68, v58, v59, v68
	v_max3_f32 v66, v66, v67, v68
	v_max_f32_e32 v67, v57, v57
	v_max_f32_e32 v68, v56, v56
	v_max_f32_e32 v67, v68, v67
	v_max_f32_e32 v68, v65, v65
	v_max_f32_e32 v69, v64, v64
	v_max_f32_e32 v68, v69, v68
	v_max3_f32 v67, v54, v55, v67
	v_max3_f32 v68, v62, v63, v68
	v_max3_f32 v66, v66, v67, v68
	ds_bpermute_b32 v67, v181, v66
	v_lshlrev_b64 v[130:131], 11, v[162:163]
	s_waitcnt lgkmcnt(0)
; __device__ __forceinline__ unsigned cvt_pk_bf16(float lo, float hi) { unsigned r; asm volatile("v_cvt_pk_bf16_f32 %0, %1, %2" : "=v"(r) : "v"(lo), "v"(hi)); return r; }
; __device__ __forceinline__ float fast_exp2(float x) { return __builtin_amdgcn_exp2f(x); }
; template <bool LOCAL>
; __device__ __forceinline__ void attn_unit(const bf16_t* Q, const bf16_t* KT, const bf16_t* VT, bf16_t* O, LAS unsigned char* lds, int b, int h, int r, int w, int tq, int lane) {
;     ...
;     float sum = 0.f; const float mxl = mx * 1.4426950408889634f;
;     bf16x8 pb[NP];
; #pragma unroll
;     for (int p = 0; p < NP; ++p) { float e[8];
; #pragma unroll
;         for (int f = 0; f < 2; ++f)
; #pragma unroll
;             for (int j = 0; j < 4; ++j) { e[4 * f + j] = fast_exp2(fmaf(s[2 * p + f][j], 1.4426950408889634f, -mxl)); sum += e[4 * f + j]; }
;         u32x4 pw; pw.x = cvt_pk_bf16(e[0], e[1]); pw.y = cvt_pk_bf16(e[2], e[3]); pw.z = cvt_pk_bf16(e[4], e[5]); pw.w = cvt_pk_bf16(e[6], e[7]);
;         pb[p] = __builtin_bit_cast(bf16x8, pw); }
	v_max_f32_e32 v67, v67, v67
	v_max_f32_e32 v66, v66, v67
	ds_bpermute_b32 v67, v182, v66
	s_waitcnt lgkmcnt(0)
	v_max_f32_e32 v67, v67, v67
	v_max_f32_e32 v66, v66, v67
	v_mul_f32_e32 v106, 0xbfb8aa3b, v66
	v_fmamk_f32 v66, v133, 0x3fb8aa3b, v106
	v_exp_f32_e32 v66, v66
	v_fmamk_f32 v68, v132, 0x3fb8aa3b, v106
	v_exp_f32_e32 v68, v68
	v_fmamk_f32 v69, v134, 0x3fb8aa3b, v106
	v_exp_f32_e32 v69, v69
	v_fmamk_f32 v70, v126, 0x3fb8aa3b, v106
	v_exp_f32_e32 v70, v70
	v_fmamk_f32 v71, v128, 0x3fb8aa3b, v106
	v_add_f32_e32 v67, 0, v66
	v_exp_f32_e32 v71, v71
	v_fmamk_f32 v72, v127, 0x3fb8aa3b, v106
	v_add_f32_e32 v67, v68, v67
	v_exp_f32_e32 v72, v72
	v_fmamk_f32 v73, v129, 0x3fb8aa3b, v106
	v_add_f32_e32 v67, v69, v67
	v_exp_f32_e32 v73, v73
	v_fmamk_f32 v74, v123, 0x3fb8aa3b, v106
	v_add_f32_e32 v67, v70, v67
	v_exp_f32_e32 v74, v74
	v_add_f32_e32 v67, v71, v67
	v_add_f32_e32 v67, v72, v67
	v_add_f32_e32 v67, v73, v67
	v_add_f32_e32 v75, v74, v67
	v_cvt_pk_bf16_f32 v66, v66, v68
	v_cvt_pk_bf16_f32 v67, v69, v70
	v_fmamk_f32 v70, v124, 0x3fb8aa3b, v106
	v_exp_f32_e32 v70, v70
	v_cvt_pk_bf16_f32 v68, v71, v72
	v_fmamk_f32 v72, v122, 0x3fb8aa3b, v106
	v_cvt_pk_bf16_f32 v69, v73, v74
	v_exp_f32_e32 v72, v72
	v_fmamk_f32 v73, v125, 0x3fb8aa3b, v106
	v_exp_f32_e32 v73, v73
	v_fmamk_f32 v74, v118, 0x3fb8aa3b, v106
	v_add_f32_e32 v71, v70, v75
	v_exp_f32_e32 v74, v74
	v_fmamk_f32 v75, v120, 0x3fb8aa3b, v106
	v_exp_f32_e32 v75, v75
	v_fmamk_f32 v76, v119, 0x3fb8aa3b, v106
	v_add_f32_e32 v71, v72, v71
	v_exp_f32_e32 v76, v76
	v_fmamk_f32 v77, v121, 0x3fb8aa3b, v106
	v_add_f32_e32 v71, v73, v71
	v_exp_f32_e32 v77, v77
	v_fmamk_f32 v78, v115, 0x3fb8aa3b, v106
	v_add_f32_e32 v71, v74, v71
	v_exp_f32_e32 v78, v78
	v_add_f32_e32 v71, v75, v71
	v_add_f32_e32 v71, v76, v71
	v_add_f32_e32 v71, v77, v71
	v_add_f32_e32 v79, v78, v71
	v_cvt_pk_bf16_f32 v70, v70, v72
	v_cvt_pk_bf16_f32 v71, v73, v74
	v_fmamk_f32 v74, v116, 0x3fb8aa3b, v106
	v_exp_f32_e32 v74, v74
	v_cvt_pk_bf16_f32 v72, v75, v76
	v_fmamk_f32 v76, v114, 0x3fb8aa3b, v106
	v_cvt_pk_bf16_f32 v73, v77, v78
	v_exp_f32_e32 v76, v76
	v_fmamk_f32 v77, v117, 0x3fb8aa3b, v106
	v_exp_f32_e32 v77, v77
	v_fmamk_f32 v78, v110, 0x3fb8aa3b, v106
	v_add_f32_e32 v75, v74, v79
	v_exp_f32_e32 v78, v78
	v_fmamk_f32 v79, v112, 0x3fb8aa3b, v106
	v_exp_f32_e32 v79, v79
	v_fmamk_f32 v80, v111, 0x3fb8aa3b, v106
	v_add_f32_e32 v75, v76, v75
	v_exp_f32_e32 v80, v80
	v_fmamk_f32 v81, v135, 0x3fb8aa3b, v106
	v_add_f32_e32 v75, v77, v75
	v_exp_f32_e32 v81, v81
	v_fmamk_f32 v82, v113, 0x3fb8aa3b, v106
	v_add_f32_e32 v75, v78, v75
	v_exp_f32_e32 v82, v82
	v_add_f32_e32 v75, v79, v75
	v_add_f32_e32 v75, v80, v75
	v_add_f32_e32 v75, v81, v75
	v_add_f32_e32 v83, v82, v75
	v_cvt_pk_bf16_f32 v74, v74, v76
	v_cvt_pk_bf16_f32 v75, v77, v78
	v_fmamk_f32 v78, v108, 0x3fb8aa3b, v106
	v_exp_f32_e32 v78, v78
	v_cvt_pk_bf16_f32 v76, v79, v80
	v_fmamk_f32 v80, v107, 0x3fb8aa3b, v106
	v_cvt_pk_bf16_f32 v77, v81, v82
	v_exp_f32_e32 v80, v80
	v_fmamk_f32 v81, v109, 0x3fb8aa3b, v106
	v_exp_f32_e32 v81, v81
	v_fmamk_f32 v82, v102, 0x3fb8aa3b, v106
	v_add_f32_e32 v79, v78, v83
	v_exp_f32_e32 v82, v82
	v_fmamk_f32 v83, v104, 0x3fb8aa3b, v106
	v_exp_f32_e32 v83, v83
	v_fmamk_f32 v84, v103, 0x3fb8aa3b, v106
	v_add_f32_e32 v79, v80, v79
	v_exp_f32_e32 v84, v84
	v_fmamk_f32 v85, v105, 0x3fb8aa3b, v106
	v_add_f32_e32 v79, v81, v79
	v_exp_f32_e32 v85, v85
	v_fmamk_f32 v99, v99, 0x3fb8aa3b, v106
	v_add_f32_e32 v79, v82, v79
	v_exp_f32_e32 v99, v99
	v_add_f32_e32 v79, v83, v79
	v_add_f32_e32 v79, v84, v79
	v_add_f32_e32 v79, v85, v79
	v_add_f32_e32 v102, v99, v79
	v_cvt_pk_bf16_f32 v78, v78, v80
	v_cvt_pk_bf16_f32 v79, v81, v82
	v_fmamk_f32 v82, v100, 0x3fb8aa3b, v106
	v_cvt_pk_bf16_f32 v80, v83, v84
	v_exp_f32_e32 v82, v82
	v_fmamk_f32 v84, v98, 0x3fb8aa3b, v106
	v_cvt_pk_bf16_f32 v81, v85, v99
	v_exp_f32_e32 v84, v84
	v_fmamk_f32 v85, v101, 0x3fb8aa3b, v106
	v_exp_f32_e32 v85, v85
	v_fmamk_f32 v94, v94, 0x3fb8aa3b, v106
	v_exp_f32_e32 v94, v94
	v_fmamk_f32 v96, v96, 0x3fb8aa3b, v106
	v_add_f32_e32 v83, v82, v102
	v_exp_f32_e32 v96, v96
	v_fmamk_f32 v95, v95, 0x3fb8aa3b, v106
	v_add_f32_e32 v83, v84, v83
	v_exp_f32_e32 v95, v95
	v_fmamk_f32 v97, v97, 0x3fb8aa3b, v106
	v_add_f32_e32 v83, v85, v83
	v_exp_f32_e32 v97, v97
	v_fmamk_f32 v91, v91, 0x3fb8aa3b, v106
	v_add_f32_e32 v83, v94, v83
	v_exp_f32_e32 v91, v91
	v_add_f32_e32 v83, v96, v83
	v_add_f32_e32 v83, v95, v83
	v_add_f32_e32 v83, v97, v83
	v_add_f32_e32 v98, v91, v83
	v_cvt_pk_bf16_f32 v82, v82, v84
	v_cvt_pk_bf16_f32 v83, v85, v94
	v_cvt_pk_bf16_f32 v84, v96, v95
	v_cvt_pk_bf16_f32 v85, v97, v91
	v_fmamk_f32 v91, v92, 0x3fb8aa3b, v106
	v_exp_f32_e32 v91, v91
	v_fmamk_f32 v90, v90, 0x3fb8aa3b, v106
	v_exp_f32_e32 v90, v90
	v_fmamk_f32 v93, v93, 0x3fb8aa3b, v106
	v_exp_f32_e32 v93, v93
	v_fmamk_f32 v86, v86, 0x3fb8aa3b, v106
	v_exp_f32_e32 v94, v86
	v_add_f32_e32 v92, v91, v98
	v_add_f32_e32 v92, v90, v92
	v_fmamk_f32 v88, v88, 0x3fb8aa3b, v106
	v_add_f32_e32 v92, v93, v92
	v_exp_f32_e32 v88, v88
	v_fmamk_f32 v87, v87, 0x3fb8aa3b, v106
	v_add_f32_e32 v86, v94, v92
	v_exp_f32_e32 v92, v87
	v_fmamk_f32 v87, v138, 0x3fb8aa3b, v106
	v_exp_f32_e32 v95, v87
	v_fmamk_f32 v87, v89, 0x3fb8aa3b, v106
	v_exp_f32_e32 v89, v87
	v_add_f32_e32 v86, v88, v86
	v_add_f32_e32 v86, v92, v86
	v_add_f32_e32 v86, v95, v86
	v_add_f32_e32 v96, v89, v86
	v_cvt_pk_bf16_f32 v86, v91, v90
	v_fmamk_f32 v90, v137, 0x3fb8aa3b, v106
	v_cvt_pk_bf16_f32 v87, v93, v94
	v_cvt_pk_bf16_f32 v88, v88, v92
	v_exp_f32_e32 v90, v90
	v_fmamk_f32 v92, v136, 0x3fb8aa3b, v106
	v_exp_f32_e32 v92, v92
	v_fmamk_f32 v93, v141, 0x3fb8aa3b, v106
; __device__ __forceinline__ unsigned cvt_pk_bf16(float lo, float hi) { unsigned r; asm volatile("v_cvt_pk_bf16_f32 %0, %1, %2" : "=v"(r) : "v"(lo), "v"(hi)); return r; }
; __device__ __forceinline__ float fast_exp2(float x) { return __builtin_amdgcn_exp2f(x); }
; template <bool LOCAL>
; __device__ __forceinline__ void attn_unit(const bf16_t* Q, const bf16_t* KT, const bf16_t* VT, bf16_t* O, LAS unsigned char* lds, int b, int h, int r, int w, int tq, int lane) {
;     ...
;     float sum = 0.f; const float mxl = mx * 1.4426950408889634f;
;     bf16x8 pb[NP];
; #pragma unroll
;     for (int p = 0; p < NP; ++p) { float e[8];
; #pragma unroll
;         for (int f = 0; f < 2; ++f)
; #pragma unroll
;             for (int j = 0; j < 4; ++j) { e[4 * f + j] = fast_exp2(fmaf(s[2 * p + f][j], 1.4426950408889634f, -mxl)); sum += e[4 * f + j]; }
;         u32x4 pw; pw.x = cvt_pk_bf16(e[0], e[1]); pw.y = cvt_pk_bf16(e[2], e[3]); pw.z = cvt_pk_bf16(e[4], e[5]); pw.w = cvt_pk_bf16(e[6], e[7]);
;         pb[p] = __builtin_bit_cast(bf16x8, pw); }
	v_exp_f32_e32 v93, v93
	v_fmamk_f32 v94, v139, 0x3fb8aa3b, v106
	v_cvt_pk_bf16_f32 v89, v95, v89
	v_exp_f32_e32 v95, v94
	v_fmamk_f32 v94, v195, 0x3fb8aa3b, v106
	v_add_f32_e32 v91, v90, v96
	v_exp_f32_e32 v96, v94
	v_fmamk_f32 v94, v140, 0x3fb8aa3b, v106
	v_add_f32_e32 v91, v92, v91
	v_exp_f32_e32 v97, v94
	v_fmamk_f32 v94, v199, 0x3fb8aa3b, v106
	v_add_f32_e32 v91, v93, v91
	v_exp_f32_e32 v98, v94
	v_fmamk_f32 v94, v197, 0x3fb8aa3b, v106
	v_add_f32_e32 v91, v95, v91
	v_exp_f32_e32 v99, v94
	v_cvt_pk_bf16_f32 v94, v90, v92
	v_fmamk_f32 v90, v198, 0x3fb8aa3b, v106
	v_add_f32_e32 v91, v96, v91
	v_exp_f32_e32 v90, v90
	v_fmamk_f32 v92, v196, 0x3fb8aa3b, v106
	v_add_f32_e32 v91, v97, v91
	v_cvt_pk_bf16_f32 v95, v93, v95
	v_exp_f32_e32 v92, v92
	v_fmamk_f32 v93, v202, 0x3fb8aa3b, v106
	v_add_f32_e32 v91, v98, v91
	v_cvt_pk_bf16_f32 v96, v96, v97
	v_cvt_pk_bf16_f32 v97, v98, v99
	v_exp_f32_e32 v93, v93
	v_fmamk_f32 v98, v200, 0x3fb8aa3b, v106
	v_add_f32_e32 v91, v99, v91
	v_exp_f32_e32 v98, v98
	v_fmamk_f32 v99, v203, 0x3fb8aa3b, v106
	v_add_f32_e32 v91, v90, v91
	v_exp_f32_e32 v99, v99
	v_fmamk_f32 v100, v201, 0x3fb8aa3b, v106
	v_add_f32_e32 v91, v92, v91
	v_exp_f32_e32 v100, v100
	v_fmamk_f32 v101, v205, 0x3fb8aa3b, v106
	v_add_f32_e32 v91, v93, v91
	v_exp_f32_e32 v101, v101
	v_fmamk_f32 v102, v204, 0x3fb8aa3b, v106
	v_add_f32_e32 v91, v98, v91
	v_exp_f32_e32 v105, v102
	v_fmamk_f32 v2, v2, 0x3fb8aa3b, v106
	v_add_f32_e32 v91, v99, v91
	v_exp_f32_e32 v2, v2
	v_fmamk_f32 v3, v3, 0x3fb8aa3b, v106
	v_add_f32_e32 v91, v100, v91
	v_exp_f32_e32 v3, v3
	v_fmamk_f32 v4, v4, 0x3fb8aa3b, v106
	v_add_f32_e32 v91, v101, v91
	v_exp_f32_e32 v4, v4
	v_fmamk_f32 v5, v5, 0x3fb8aa3b, v106
	v_add_f32_e32 v91, v105, v91
	v_exp_f32_e32 v5, v5
	v_fmamk_f32 v10, v10, 0x3fb8aa3b, v106
	v_cvt_pk_bf16_f32 v102, v90, v92
	v_add_f32_e32 v90, v2, v91
	v_exp_f32_e32 v10, v10
	v_fmamk_f32 v11, v11, 0x3fb8aa3b, v106
	v_add_f32_e32 v90, v3, v90
	v_exp_f32_e32 v11, v11
	v_fmamk_f32 v12, v12, 0x3fb8aa3b, v106
	v_add_f32_e32 v90, v4, v90
	v_exp_f32_e32 v12, v12
	v_fmamk_f32 v13, v13, 0x3fb8aa3b, v106
	v_cvt_pk_bf16_f32 v103, v93, v98
	v_cvt_pk_bf16_f32 v104, v99, v100
	v_cvt_pk_bf16_f32 v105, v101, v105
	v_add_f32_e32 v90, v5, v90
	v_exp_f32_e32 v13, v13
	v_cvt_pk_bf16_f32 v98, v2, v3
	v_fmamk_f32 v2, v6, 0x3fb8aa3b, v106
	v_add_f32_e32 v90, v10, v90
	v_cvt_pk_bf16_f32 v99, v4, v5
	v_exp_f32_e32 v2, v2
	v_fmamk_f32 v4, v7, 0x3fb8aa3b, v106
	v_add_f32_e32 v90, v11, v90
	v_exp_f32_e32 v4, v4
	v_fmamk_f32 v5, v8, 0x3fb8aa3b, v106
	v_add_f32_e32 v90, v12, v90
	v_exp_f32_e32 v5, v5
	v_fmamk_f32 v6, v9, 0x3fb8aa3b, v106
	v_add_f32_e32 v90, v13, v90
	v_exp_f32_e32 v6, v6
	v_fmamk_f32 v7, v18, 0x3fb8aa3b, v106
	v_add_f32_e32 v3, v2, v90
	v_exp_f32_e32 v7, v7
	v_fmamk_f32 v8, v19, 0x3fb8aa3b, v106
	v_add_f32_e32 v3, v4, v3
	v_exp_f32_e32 v8, v8
	v_fmamk_f32 v9, v20, 0x3fb8aa3b, v106
	v_cvt_pk_bf16_f32 v100, v10, v11
	v_add_f32_e32 v3, v5, v3
	v_exp_f32_e32 v9, v9
	v_fmamk_f32 v10, v21, 0x3fb8aa3b, v106
	v_cvt_pk_bf16_f32 v101, v12, v13
	v_add_f32_e32 v3, v6, v3
	v_exp_f32_e32 v10, v10
	v_cvt_pk_bf16_f32 v90, v2, v4
	v_fmamk_f32 v2, v14, 0x3fb8aa3b, v106
	v_add_f32_e32 v3, v7, v3
	v_exp_f32_e32 v2, v2
	v_fmamk_f32 v4, v15, 0x3fb8aa3b, v106
	v_add_f32_e32 v3, v8, v3
	v_cvt_pk_bf16_f32 v91, v5, v6
	v_exp_f32_e32 v4, v4
	v_fmamk_f32 v5, v16, 0x3fb8aa3b, v106
	v_add_f32_e32 v3, v9, v3
	v_exp_f32_e32 v5, v5
	v_fmamk_f32 v6, v17, 0x3fb8aa3b, v106
	v_add_f32_e32 v3, v10, v3
	v_cvt_pk_bf16_f32 v92, v7, v8
	v_exp_f32_e32 v6, v6
	v_fmamk_f32 v7, v26, 0x3fb8aa3b, v106
	v_add_f32_e32 v3, v2, v3
	v_exp_f32_e32 v7, v7
	v_fmamk_f32 v8, v27, 0x3fb8aa3b, v106
	v_cvt_pk_bf16_f32 v93, v9, v10
	v_add_f32_e32 v3, v4, v3
	v_exp_f32_e32 v8, v8
	v_fmamk_f32 v9, v28, 0x3fb8aa3b, v106
	v_add_f32_e32 v3, v5, v3
	v_exp_f32_e32 v9, v9
	v_fmamk_f32 v10, v29, 0x3fb8aa3b, v106
	v_add_f32_e32 v3, v6, v3
	v_exp_f32_e32 v10, v10
	v_cvt_pk_bf16_f32 v26, v2, v4
	v_fmamk_f32 v2, v22, 0x3fb8aa3b, v106
	v_add_f32_e32 v3, v7, v3
	v_exp_f32_e32 v2, v2
	v_fmamk_f32 v4, v23, 0x3fb8aa3b, v106
	v_add_f32_e32 v3, v8, v3
	v_cvt_pk_bf16_f32 v27, v5, v6
	v_exp_f32_e32 v4, v4
	v_fmamk_f32 v5, v24, 0x3fb8aa3b, v106
	v_add_f32_e32 v3, v9, v3
	v_exp_f32_e32 v5, v5
	v_fmamk_f32 v6, v25, 0x3fb8aa3b, v106
	v_add_f32_e32 v3, v10, v3
	v_cvt_pk_bf16_f32 v28, v7, v8
	v_exp_f32_e32 v6, v6
	v_fmamk_f32 v7, v34, 0x3fb8aa3b, v106
	v_add_f32_e32 v3, v2, v3
	v_exp_f32_e32 v7, v7
	v_fmamk_f32 v8, v35, 0x3fb8aa3b, v106
	v_cvt_pk_bf16_f32 v29, v9, v10
	v_add_f32_e32 v3, v4, v3
	v_exp_f32_e32 v8, v8
	v_fmamk_f32 v9, v36, 0x3fb8aa3b, v106
	v_add_f32_e32 v3, v5, v3
	v_exp_f32_e32 v9, v9
	v_fmamk_f32 v10, v37, 0x3fb8aa3b, v106
	v_add_f32_e32 v3, v6, v3
	v_exp_f32_e32 v13, v10
	v_cvt_pk_bf16_f32 v10, v2, v4
	v_fmamk_f32 v2, v30, 0x3fb8aa3b, v106
	v_add_f32_e32 v3, v7, v3
	v_exp_f32_e32 v2, v2
	v_fmamk_f32 v4, v31, 0x3fb8aa3b, v106
	v_add_f32_e32 v3, v8, v3
	v_cvt_pk_bf16_f32 v11, v5, v6
	v_exp_f32_e32 v4, v4
	v_fmamk_f32 v5, v32, 0x3fb8aa3b, v106
	v_add_f32_e32 v3, v9, v3
	v_exp_f32_e32 v5, v5
	v_fmamk_f32 v6, v33, 0x3fb8aa3b, v106
	v_add_f32_e32 v3, v13, v3
	v_cvt_pk_bf16_f32 v12, v7, v8
	v_exp_f32_e32 v6, v6
	v_fmamk_f32 v7, v42, 0x3fb8aa3b, v106
	v_add_f32_e32 v3, v2, v3
	v_exp_f32_e32 v7, v7
	v_fmamk_f32 v8, v43, 0x3fb8aa3b, v106
	v_cvt_pk_bf16_f32 v13, v9, v13
	v_add_f32_e32 v3, v4, v3
	v_exp_f32_e32 v8, v8
	v_fmamk_f32 v9, v44, 0x3fb8aa3b, v106
	v_add_f32_e32 v3, v5, v3
	v_exp_f32_e32 v9, v9
	v_fmamk_f32 v14, v45, 0x3fb8aa3b, v106
	v_add_f32_e32 v3, v6, v3
	v_exp_f32_e32 v14, v14
	v_add_f32_e32 v3, v7, v3
	v_add_f32_e32 v3, v8, v3
	v_add_f32_e32 v3, v9, v3
; __device__ __forceinline__ unsigned cvt_pk_bf16(float lo, float hi) { unsigned r; asm volatile("v_cvt_pk_bf16_f32 %0, %1, %2" : "=v"(r) : "v"(lo), "v"(hi)); return r; }
; __device__ __forceinline__ float fast_exp2(float x) { return __builtin_amdgcn_exp2f(x); }
; #define ATT_VLOAD(buf, p) do { const bf16_t* vp_ = vloc + (size_t)((p) * 8 * NH) * 1024; \
;         _Pragma("unroll") for (int df = 0; df < 8; ++df) va[buf][df] = *(const bf16x8*)(vp_ + df * 128); } while (0)
; template <bool LOCAL>
; __device__ __forceinline__ void attn_unit(const bf16_t* Q, const bf16_t* KT, const bf16_t* VT, bf16_t* O, LAS unsigned char* lds, int b, int h, int r, int w, int tq, int lane) {
;     ...
;     float sum = 0.f; const float mxl = mx * 1.4426950408889634f;
;     bf16x8 pb[NP];
; #pragma unroll
;     for (int p = 0; p < NP; ++p) { float e[8];
; #pragma unroll
;         for (int f = 0; f < 2; ++f)
; #pragma unroll
;             for (int j = 0; j < 4; ++j) { e[4 * f + j] = fast_exp2(fmaf(s[2 * p + f][j], 1.4426950408889634f, -mxl)); sum += e[4 * f + j]; }
;         u32x4 pw; pw.x = cvt_pk_bf16(e[0], e[1]); pw.y = cvt_pk_bf16(e[2], e[3]); pw.z = cvt_pk_bf16(e[4], e[5]); pw.w = cvt_pk_bf16(e[6], e[7]);
;         pb[p] = __builtin_bit_cast(bf16x8, pw); }
;     sum += __shfl_xor(sum, 16); sum += __shfl_xor(sum, 32);
;     f32x4 o[8];
; #pragma unroll
;     for (int df = 0; df < 8; ++df) o[df] = (f32x4){0.f, 0.f, 0.f, 0.f};
;     if (LOCAL) {
;         const bf16_t* vloc = VT + ((size_t)(((rgl >> 3) + g) * NH + h)) * 1024 + q * 8;
;         bf16x8 va[2][8];
;     ...
;         ATT_VLOAD(0, 0);
; #pragma unroll
;         for (int p = 0; p < 8; ++p) {
;             __builtin_amdgcn_s_barrier();
;             if (p + 1 < 8) ATT_VLOAD((p + 1) & 1, p + 1);
;             __builtin_amdgcn_sched_barrier(0);
; #pragma unroll
;             for (int df = 0; df < 8; ++df) o[df] = __builtin_amdgcn_mfma_f32_16x16x32_bf16(va[p & 1][df], pb[p], o[df], 0, 0, 0);
;             __builtin_amdgcn_sched_barrier(0);
;         }
	v_add_f32_e32 v15, v14, v3
	v_cvt_pk_bf16_f32 v2, v2, v4
	v_cvt_pk_bf16_f32 v3, v5, v6
	v_fmamk_f32 v6, v38, 0x3fb8aa3b, v106
	v_exp_f32_e32 v6, v6
	v_cvt_pk_bf16_f32 v4, v7, v8
	v_fmamk_f32 v8, v39, 0x3fb8aa3b, v106
	v_cvt_pk_bf16_f32 v5, v9, v14
	v_exp_f32_e32 v8, v8
	v_fmamk_f32 v9, v40, 0x3fb8aa3b, v106
	v_exp_f32_e32 v9, v9
	v_fmamk_f32 v14, v41, 0x3fb8aa3b, v106
	v_add_f32_e32 v7, v6, v15
	v_exp_f32_e32 v14, v14
	v_fmamk_f32 v15, v50, 0x3fb8aa3b, v106
	v_exp_f32_e32 v15, v15
	v_fmamk_f32 v16, v51, 0x3fb8aa3b, v106
	v_add_f32_e32 v7, v8, v7
	v_exp_f32_e32 v16, v16
	v_fmamk_f32 v17, v52, 0x3fb8aa3b, v106
	v_add_f32_e32 v7, v9, v7
	v_exp_f32_e32 v17, v17
	v_fmamk_f32 v18, v53, 0x3fb8aa3b, v106
	v_add_f32_e32 v7, v14, v7
	v_exp_f32_e32 v18, v18
	v_add_f32_e32 v7, v15, v7
	v_add_f32_e32 v7, v16, v7
	v_add_f32_e32 v7, v17, v7
	v_add_f32_e32 v19, v18, v7
	v_cvt_pk_bf16_f32 v6, v6, v8
	v_cvt_pk_bf16_f32 v7, v9, v14
	v_fmamk_f32 v14, v46, 0x3fb8aa3b, v106
	v_exp_f32_e32 v14, v14
	v_cvt_pk_bf16_f32 v8, v15, v16
	v_fmamk_f32 v16, v47, 0x3fb8aa3b, v106
	v_cvt_pk_bf16_f32 v9, v17, v18
	v_exp_f32_e32 v16, v16
	v_fmamk_f32 v17, v48, 0x3fb8aa3b, v106
	v_exp_f32_e32 v17, v17
	v_fmamk_f32 v18, v49, 0x3fb8aa3b, v106
	v_add_f32_e32 v15, v14, v19
	v_exp_f32_e32 v18, v18
	v_fmamk_f32 v19, v58, 0x3fb8aa3b, v106
	v_exp_f32_e32 v19, v19
	v_fmamk_f32 v20, v59, 0x3fb8aa3b, v106
	v_add_f32_e32 v15, v16, v15
	v_exp_f32_e32 v20, v20
	v_fmamk_f32 v21, v60, 0x3fb8aa3b, v106
	v_add_f32_e32 v15, v17, v15
	v_exp_f32_e32 v21, v21
	v_fmamk_f32 v22, v61, 0x3fb8aa3b, v106
	v_add_f32_e32 v15, v18, v15
	v_exp_f32_e32 v22, v22
	v_add_f32_e32 v15, v19, v15
	v_add_f32_e32 v15, v20, v15
	v_add_f32_e32 v15, v21, v15
	v_add_f32_e32 v23, v22, v15
	v_cvt_pk_bf16_f32 v14, v14, v16
	v_cvt_pk_bf16_f32 v15, v17, v18
	v_fmamk_f32 v18, v54, 0x3fb8aa3b, v106
	v_exp_f32_e32 v18, v18
	v_cvt_pk_bf16_f32 v16, v19, v20
	v_fmamk_f32 v20, v55, 0x3fb8aa3b, v106
	v_cvt_pk_bf16_f32 v17, v21, v22
	v_exp_f32_e32 v20, v20
	v_fmamk_f32 v21, v56, 0x3fb8aa3b, v106
	v_exp_f32_e32 v21, v21
	v_fmamk_f32 v22, v57, 0x3fb8aa3b, v106
	v_add_f32_e32 v19, v18, v23
	v_exp_f32_e32 v22, v22
	v_fmamk_f32 v23, v62, 0x3fb8aa3b, v106
	v_exp_f32_e32 v23, v23
	v_fmamk_f32 v24, v63, 0x3fb8aa3b, v106
	v_add_f32_e32 v19, v20, v19
	v_exp_f32_e32 v24, v24
	v_fmamk_f32 v25, v64, 0x3fb8aa3b, v106
	v_add_f32_e32 v19, v21, v19
	v_exp_f32_e32 v25, v25
	v_fmac_f32_e32 v106, 0x3fb8aa3b, v65
	v_add_f32_e32 v19, v22, v19
	v_exp_f32_e32 v30, v106
	v_add_f32_e32 v19, v23, v19
	v_add_f32_e32 v19, v24, v19
	v_add_f32_e32 v19, v25, v19
	v_add_f32_e32 v31, v30, v19
	v_cvt_pk_bf16_f32 v18, v18, v20
	v_cvt_pk_bf16_f32 v19, v21, v22
	ds_bpermute_b32 v22, v181, v31
	v_cvt_pk_bf16_f32 v20, v23, v24
	v_cvt_pk_bf16_f32 v21, v25, v30
	s_waitcnt lgkmcnt(0)
	v_add_f32_e32 v134, v31, v22
	v_add_u32_e32 v22, v194, v165
	v_lshl_or_b32 v22, v22, 4, s72
	v_ashrrev_i32_e32 v23, 31, v22
	v_lshlrev_b64 v[22:23], 11, v[22:23]
	v_lshl_add_u64 v[132:133], v[148:149], 0, v[22:23]
	ds_bpermute_b32 v135, v182, v134
	s_cmp_eq_u32 s53, 0
	s_cbranch_scc0 .Lrg_v_B
	s_waitcnt vmcnt(6)
	s_barrier
	s_add_i32 m0, s59, 57344
	v_add_co_u32_e32 v222, vcc, s2, v226
	s_nop 1
	v_addc_co_u32_e32 v223, vcc, 0, v227, vcc
	global_load_lds_dwordx4 v[222:223], off
	ds_read_b128 v[106:109], v219 offset:0
	ds_read_b128 v[110:113], v219 offset:256
	ds_read_b128 v[114:117], v219 offset:512
	ds_read_b128 v[118:121], v219 offset:768
	s_waitcnt lgkmcnt(3)
	v_mfma_f32_16x16x32_bf16 v[22:25], v[106:109], v[66:69], 0
	s_waitcnt lgkmcnt(2)
	v_mfma_f32_16x16x32_bf16 v[30:33], v[110:113], v[66:69], 0
	s_waitcnt lgkmcnt(1)
	v_mfma_f32_16x16x32_bf16 v[34:37], v[114:117], v[66:69], 0
	s_waitcnt lgkmcnt(0)
	v_mfma_f32_16x16x32_bf16 v[38:41], v[118:121], v[66:69], 0
	s_waitcnt vmcnt(6)
	s_barrier
	s_add_i32 m0, s59, 0
	v_add_co_u32_e32 v222, vcc, s60, v220
	s_nop 1
	v_addc_co_u32_e32 v223, vcc, 0, v221, vcc
	global_load_lds_dwordx4 v[222:223], off
	ds_read_b128 v[122:125], v219 offset:8192
	ds_read_b128 v[126:129], v219 offset:8448
	ds_read_b128 v[58:61], v219 offset:8704
	ds_read_b128 v[62:65], v219 offset:8960
	s_waitcnt lgkmcnt(3)
	v_mfma_f32_16x16x32_bf16 v[42:45], v[122:125], v[66:69], 0
	s_waitcnt lgkmcnt(2)
	v_mfma_f32_16x16x32_bf16 v[46:49], v[126:129], v[66:69], 0
	s_waitcnt lgkmcnt(1)
	v_mfma_f32_16x16x32_bf16 v[50:53], v[58:61], v[66:69], 0
	s_waitcnt lgkmcnt(0)
	v_mfma_f32_16x16x32_bf16 v[54:57], v[62:65], v[66:69], 0
	s_waitcnt vmcnt(6)
	s_barrier
	s_add_i32 m0, s59, 8192
	v_add_co_u32_e32 v222, vcc, s60, v226
	s_nop 1
	v_addc_co_u32_e32 v223, vcc, 0, v227, vcc
	global_load_lds_dwordx4 v[222:223], off
	ds_read_b128 v[106:109], v219 offset:16384
	ds_read_b128 v[110:113], v219 offset:16640
	ds_read_b128 v[114:117], v219 offset:16896
	ds_read_b128 v[118:121], v219 offset:17152
	s_waitcnt lgkmcnt(3)
	v_mfma_f32_16x16x32_bf16 v[22:25], v[106:109], v[70:73], v[22:25]
	s_waitcnt lgkmcnt(2)
	v_mfma_f32_16x16x32_bf16 v[30:33], v[110:113], v[70:73], v[30:33]
	s_waitcnt lgkmcnt(1)
	v_mfma_f32_16x16x32_bf16 v[34:37], v[114:117], v[70:73], v[34:37]
	s_waitcnt lgkmcnt(0)
	v_mfma_f32_16x16x32_bf16 v[38:41], v[118:121], v[70:73], v[38:41]
	s_waitcnt vmcnt(6)
	s_barrier
	s_add_i32 m0, s59, 16384
	v_add_co_u32_e32 v222, vcc, s61, v220
	s_nop 1
	v_addc_co_u32_e32 v223, vcc, 0, v221, vcc
	global_load_lds_dwordx4 v[222:223], off
	ds_read_b128 v[122:125], v219 offset:24576
	ds_read_b128 v[126:129], v219 offset:24832
	ds_read_b128 v[58:61], v219 offset:25088
	ds_read_b128 v[62:65], v219 offset:25344
	s_waitcnt lgkmcnt(3)
	v_mfma_f32_16x16x32_bf16 v[42:45], v[122:125], v[70:73], v[42:45]
	s_waitcnt lgkmcnt(2)
	v_mfma_f32_16x16x32_bf16 v[46:49], v[126:129], v[70:73], v[46:49]
	s_waitcnt lgkmcnt(1)
	v_mfma_f32_16x16x32_bf16 v[50:53], v[58:61], v[70:73], v[50:53]
	s_waitcnt lgkmcnt(0)
	v_mfma_f32_16x16x32_bf16 v[54:57], v[62:65], v[70:73], v[54:57]
	s_waitcnt vmcnt(6)
	s_barrier
; #define ATT_VLOAD(buf, p) do { const bf16_t* vp_ = vloc + (size_t)((p) * 8 * NH) * 1024; \
;         _Pragma("unroll") for (int df = 0; df < 8; ++df) va[buf][df] = *(const bf16x8*)(vp_ + df * 128); } while (0)
; template <bool LOCAL>
; __device__ __forceinline__ void attn_unit(const bf16_t* Q, const bf16_t* KT, const bf16_t* VT, bf16_t* O, LAS unsigned char* lds, int b, int h, int r, int w, int tq, int lane) {
;     ...
;     if (LOCAL) {
;         const bf16_t* vloc = VT + ((size_t)(((rgl >> 3) + g) * NH + h)) * 1024 + q * 8;
;         bf16x8 va[2][8];
;     ...
;         ATT_VLOAD(0, 0);
; #pragma unroll
;         for (int p = 0; p < 8; ++p) {
;             __builtin_amdgcn_s_barrier();
;             if (p + 1 < 8) ATT_VLOAD((p + 1) & 1, p + 1);
;             __builtin_amdgcn_sched_barrier(0);
; #pragma unroll
;             for (int df = 0; df < 8; ++df) o[df] = __builtin_amdgcn_mfma_f32_16x16x32_bf16(va[p & 1][df], pb[p], o[df], 0, 0, 0);
;             __builtin_amdgcn_sched_barrier(0);
;         }
	s_add_i32 m0, s59, 24576
	v_add_co_u32_e32 v222, vcc, s61, v226
	s_nop 1
	v_addc_co_u32_e32 v223, vcc, 0, v227, vcc
	global_load_lds_dwordx4 v[222:223], off
	ds_read_b128 v[106:109], v219 offset:32768
	ds_read_b128 v[110:113], v219 offset:33024
	ds_read_b128 v[114:117], v219 offset:33280
	ds_read_b128 v[118:121], v219 offset:33536
	s_waitcnt lgkmcnt(3)
	v_mfma_f32_16x16x32_bf16 v[22:25], v[106:109], v[74:77], v[22:25]
	s_waitcnt lgkmcnt(2)
	v_mfma_f32_16x16x32_bf16 v[30:33], v[110:113], v[74:77], v[30:33]
	s_waitcnt lgkmcnt(1)
	v_mfma_f32_16x16x32_bf16 v[34:37], v[114:117], v[74:77], v[34:37]
	s_waitcnt lgkmcnt(0)
	v_mfma_f32_16x16x32_bf16 v[38:41], v[118:121], v[74:77], v[38:41]
	s_waitcnt vmcnt(6)
	s_barrier
	s_add_i32 m0, s59, 32768
	v_add_co_u32_e32 v222, vcc, s17, v220
	s_nop 1
	v_addc_co_u32_e32 v223, vcc, 0, v221, vcc
	global_load_lds_dwordx4 v[222:223], off
	ds_read_b128 v[122:125], v219 offset:40960
	ds_read_b128 v[126:129], v219 offset:41216
	ds_read_b128 v[58:61], v219 offset:41472
	ds_read_b128 v[62:65], v219 offset:41728
	s_waitcnt lgkmcnt(3)
	v_mfma_f32_16x16x32_bf16 v[42:45], v[122:125], v[74:77], v[42:45]
	s_waitcnt lgkmcnt(2)
	v_mfma_f32_16x16x32_bf16 v[46:49], v[126:129], v[74:77], v[46:49]
	s_waitcnt lgkmcnt(1)
	v_mfma_f32_16x16x32_bf16 v[50:53], v[58:61], v[74:77], v[50:53]
	s_waitcnt lgkmcnt(0)
	v_mfma_f32_16x16x32_bf16 v[54:57], v[62:65], v[74:77], v[54:57]
	s_waitcnt vmcnt(6)
	s_barrier
	s_add_i32 m0, s59, 40960
	v_add_co_u32_e32 v222, vcc, s17, v226
	s_nop 1
	v_addc_co_u32_e32 v223, vcc, 0, v227, vcc
	global_load_lds_dwordx4 v[222:223], off
	ds_read_b128 v[106:109], v219 offset:49152
	ds_read_b128 v[110:113], v219 offset:49408
	ds_read_b128 v[114:117], v219 offset:49664
	ds_read_b128 v[118:121], v219 offset:49920
	s_waitcnt lgkmcnt(3)
	v_mfma_f32_16x16x32_bf16 v[22:25], v[106:109], v[78:81], v[22:25]
	s_waitcnt lgkmcnt(2)
	v_mfma_f32_16x16x32_bf16 v[30:33], v[110:113], v[78:81], v[30:33]
	s_waitcnt lgkmcnt(1)
	v_mfma_f32_16x16x32_bf16 v[34:37], v[114:117], v[78:81], v[34:37]
	s_waitcnt lgkmcnt(0)
	v_mfma_f32_16x16x32_bf16 v[38:41], v[118:121], v[78:81], v[38:41]
	s_waitcnt vmcnt(6)
	s_barrier
	s_add_i32 m0, s59, 49152
	v_add_co_u32_e32 v222, vcc, s62, v220
	s_nop 1
	v_addc_co_u32_e32 v223, vcc, 0, v221, vcc
	global_load_lds_dwordx4 v[222:223], off
	ds_read_b128 v[122:125], v219 offset:57344
	ds_read_b128 v[126:129], v219 offset:57600
	ds_read_b128 v[58:61], v219 offset:57856
	ds_read_b128 v[62:65], v219 offset:58112
	s_waitcnt lgkmcnt(3)
	v_mfma_f32_16x16x32_bf16 v[42:45], v[122:125], v[78:81], v[42:45]
	s_waitcnt lgkmcnt(2)
	v_mfma_f32_16x16x32_bf16 v[46:49], v[126:129], v[78:81], v[46:49]
	s_waitcnt lgkmcnt(1)
	v_mfma_f32_16x16x32_bf16 v[50:53], v[58:61], v[78:81], v[50:53]
	s_waitcnt lgkmcnt(0)
	v_mfma_f32_16x16x32_bf16 v[54:57], v[62:65], v[78:81], v[54:57]
	s_waitcnt vmcnt(6)
	s_barrier
	s_add_i32 m0, s59, 57344
	v_add_co_u32_e32 v222, vcc, s62, v226
	s_nop 1
	v_addc_co_u32_e32 v223, vcc, 0, v227, vcc
	global_load_lds_dwordx4 v[222:223], off
	ds_read_b128 v[106:109], v219 offset:0
	ds_read_b128 v[110:113], v219 offset:256
	ds_read_b128 v[114:117], v219 offset:512
	ds_read_b128 v[118:121], v219 offset:768
	s_waitcnt lgkmcnt(3)
	v_mfma_f32_16x16x32_bf16 v[22:25], v[106:109], v[82:85], v[22:25]
	s_waitcnt lgkmcnt(2)
	v_mfma_f32_16x16x32_bf16 v[30:33], v[110:113], v[82:85], v[30:33]
	s_waitcnt lgkmcnt(1)
	v_mfma_f32_16x16x32_bf16 v[34:37], v[114:117], v[82:85], v[34:37]
	s_waitcnt lgkmcnt(0)
	v_mfma_f32_16x16x32_bf16 v[38:41], v[118:121], v[82:85], v[38:41]
	s_waitcnt vmcnt(6)
	s_barrier
	s_cmp_eq_u32 s73, 0
	s_cbranch_scc1 .Lrg_v_A_nd9
	s_add_i32 m0, s59, 0
	v_add_co_u32_e32 v222, vcc, s75, v220
	s_nop 1
	v_addc_co_u32_e32 v223, vcc, 0, v221, vcc
	global_load_lds_dwordx4 v[222:223], off
; #define ATT_VLOAD(buf, p) do { const bf16_t* vp_ = vloc + (size_t)((p) * 8 * NH) * 1024; \
;         _Pragma("unroll") for (int df = 0; df < 8; ++df) va[buf][df] = *(const bf16x8*)(vp_ + df * 128); } while (0)
; template <bool LOCAL>
; __device__ __forceinline__ void attn_unit(const bf16_t* Q, const bf16_t* KT, const bf16_t* VT, bf16_t* O, LAS unsigned char* lds, int b, int h, int r, int w, int tq, int lane) {
;     ...
;     if (LOCAL) {
;         const bf16_t* vloc = VT + ((size_t)(((rgl >> 3) + g) * NH + h)) * 1024 + q * 8;
;         bf16x8 va[2][8];
;     ...
;         ATT_VLOAD(0, 0);
; #pragma unroll
;         for (int p = 0; p < 8; ++p) {
;             __builtin_amdgcn_s_barrier();
;             if (p + 1 < 8) ATT_VLOAD((p + 1) & 1, p + 1);
;             __builtin_amdgcn_sched_barrier(0);
; #pragma unroll
;             for (int df = 0; df < 8; ++df) o[df] = __builtin_amdgcn_mfma_f32_16x16x32_bf16(va[p & 1][df], pb[p], o[df], 0, 0, 0);
;             __builtin_amdgcn_sched_barrier(0);
;         }
.Lrg_v_A_nd9:
	ds_read_b128 v[122:125], v219 offset:8192
	ds_read_b128 v[126:129], v219 offset:8448
	ds_read_b128 v[58:61], v219 offset:8704
	ds_read_b128 v[62:65], v219 offset:8960
	s_waitcnt lgkmcnt(3)
	v_mfma_f32_16x16x32_bf16 v[42:45], v[122:125], v[82:85], v[42:45]
	s_waitcnt lgkmcnt(2)
	v_mfma_f32_16x16x32_bf16 v[46:49], v[126:129], v[82:85], v[46:49]
	s_waitcnt lgkmcnt(1)
	v_mfma_f32_16x16x32_bf16 v[50:53], v[58:61], v[82:85], v[50:53]
	s_waitcnt lgkmcnt(0)
	v_mfma_f32_16x16x32_bf16 v[54:57], v[62:65], v[82:85], v[54:57]
	s_waitcnt vmcnt(5)
	s_barrier
	s_cmp_eq_u32 s73, 0
	s_cbranch_scc1 .Lrg_v_A_nd10
	s_add_i32 m0, s59, 8192
	v_add_co_u32_e32 v222, vcc, s75, v226
	s_nop 1
	v_addc_co_u32_e32 v223, vcc, 0, v227, vcc
	global_load_lds_dwordx4 v[222:223], off
.Lrg_v_A_nd10:
	ds_read_b128 v[106:109], v219 offset:16384
	ds_read_b128 v[110:113], v219 offset:16640
	ds_read_b128 v[114:117], v219 offset:16896
	ds_read_b128 v[118:121], v219 offset:17152
	s_waitcnt lgkmcnt(3)
	v_mfma_f32_16x16x32_bf16 v[22:25], v[106:109], v[86:89], v[22:25]
	s_waitcnt lgkmcnt(2)
	v_mfma_f32_16x16x32_bf16 v[30:33], v[110:113], v[86:89], v[30:33]
	s_waitcnt lgkmcnt(1)
	v_mfma_f32_16x16x32_bf16 v[34:37], v[114:117], v[86:89], v[34:37]
	s_waitcnt lgkmcnt(0)
	v_mfma_f32_16x16x32_bf16 v[38:41], v[118:121], v[86:89], v[38:41]
	s_waitcnt vmcnt(4)
	s_barrier
	ds_read_b128 v[122:125], v219 offset:24576
	ds_read_b128 v[126:129], v219 offset:24832
	ds_read_b128 v[58:61], v219 offset:25088
	ds_read_b128 v[62:65], v219 offset:25344
	s_waitcnt lgkmcnt(3)
	v_mfma_f32_16x16x32_bf16 v[42:45], v[122:125], v[86:89], v[42:45]
	s_waitcnt lgkmcnt(2)
	v_mfma_f32_16x16x32_bf16 v[46:49], v[126:129], v[86:89], v[46:49]
	s_waitcnt lgkmcnt(1)
	v_mfma_f32_16x16x32_bf16 v[50:53], v[58:61], v[86:89], v[50:53]
	s_waitcnt lgkmcnt(0)
	v_mfma_f32_16x16x32_bf16 v[54:57], v[62:65], v[86:89], v[54:57]
	s_waitcnt vmcnt(3)
	s_barrier
	ds_read_b128 v[106:109], v219 offset:32768
	ds_read_b128 v[110:113], v219 offset:33024
	ds_read_b128 v[114:117], v219 offset:33280
	ds_read_b128 v[118:121], v219 offset:33536
	s_waitcnt lgkmcnt(3)
	v_mfma_f32_16x16x32_bf16 v[22:25], v[106:109], v[94:97], v[22:25]
	s_waitcnt lgkmcnt(2)
	v_mfma_f32_16x16x32_bf16 v[30:33], v[110:113], v[94:97], v[30:33]
	s_waitcnt lgkmcnt(1)
	v_mfma_f32_16x16x32_bf16 v[34:37], v[114:117], v[94:97], v[34:37]
	s_waitcnt lgkmcnt(0)
	v_mfma_f32_16x16x32_bf16 v[38:41], v[118:121], v[94:97], v[38:41]
	s_waitcnt vmcnt(2)
	s_barrier
	ds_read_b128 v[122:125], v219 offset:40960
	ds_read_b128 v[126:129], v219 offset:41216
	ds_read_b128 v[58:61], v219 offset:41472
	ds_read_b128 v[62:65], v219 offset:41728
	s_waitcnt lgkmcnt(3)
	v_mfma_f32_16x16x32_bf16 v[42:45], v[122:125], v[94:97], v[42:45]
	s_waitcnt lgkmcnt(2)
	v_mfma_f32_16x16x32_bf16 v[46:49], v[126:129], v[94:97], v[46:49]
	s_waitcnt lgkmcnt(1)
	v_mfma_f32_16x16x32_bf16 v[50:53], v[58:61], v[94:97], v[50:53]
	s_waitcnt lgkmcnt(0)
	v_mfma_f32_16x16x32_bf16 v[54:57], v[62:65], v[94:97], v[54:57]
	s_waitcnt vmcnt(1)
	s_barrier
	ds_read_b128 v[106:109], v219 offset:49152
	ds_read_b128 v[110:113], v219 offset:49408
	ds_read_b128 v[114:117], v219 offset:49664
	ds_read_b128 v[118:121], v219 offset:49920
	s_waitcnt lgkmcnt(3)
	v_mfma_f32_16x16x32_bf16 v[22:25], v[106:109], v[102:105], v[22:25]
	s_waitcnt lgkmcnt(2)
	v_mfma_f32_16x16x32_bf16 v[30:33], v[110:113], v[102:105], v[30:33]
	s_waitcnt lgkmcnt(1)
	v_mfma_f32_16x16x32_bf16 v[34:37], v[114:117], v[102:105], v[34:37]
	s_waitcnt lgkmcnt(0)
	v_mfma_f32_16x16x32_bf16 v[38:41], v[118:121], v[102:105], v[38:41]
	s_waitcnt vmcnt(0)
	s_barrier
	ds_read_b128 v[122:125], v219 offset:57344
	ds_read_b128 v[126:129], v219 offset:57600
	ds_read_b128 v[58:61], v219 offset:57856
	ds_read_b128 v[62:65], v219 offset:58112
	s_waitcnt lgkmcnt(3)
	v_mfma_f32_16x16x32_bf16 v[42:45], v[122:125], v[102:105], v[42:45]
	s_waitcnt lgkmcnt(2)
	v_mfma_f32_16x16x32_bf16 v[46:49], v[126:129], v[102:105], v[46:49]
	s_waitcnt lgkmcnt(1)
	v_mfma_f32_16x16x32_bf16 v[50:53], v[58:61], v[102:105], v[50:53]
	s_waitcnt lgkmcnt(0)
	v_mfma_f32_16x16x32_bf16 v[54:57], v[62:65], v[102:105], v[54:57]
	s_cmp_eq_u32 s73, 0
	s_cbranch_scc1 .Lrg_v_A_end
	s_waitcnt vmcnt(1)
	s_barrier
	s_waitcnt vmcnt(0)
	s_barrier

; #define ATT_VLOAD(buf, p) do { const bf16_t* vp_ = vloc + (size_t)((p) * 8 * NH) * 1024; \
;         _Pragma("unroll") for (int df = 0; df < 8; ++df) va[buf][df] = *(const bf16x8*)(vp_ + df * 128); } while (0)
; template <bool LOCAL>
; __device__ __forceinline__ void attn_unit(const bf16_t* Q, const bf16_t* KT, const bf16_t* VT, bf16_t* O, LAS unsigned char* lds, int b, int h, int r, int w, int tq, int lane) {
;     ...
;     if (LOCAL) {
;         const bf16_t* vloc = VT + ((size_t)(((rgl >> 3) + g) * NH + h)) * 1024 + q * 8;
;         bf16x8 va[2][8];
;     ...
;         ATT_VLOAD(0, 0);
; #pragma unroll
;         for (int p = 0; p < 8; ++p) {
;             __builtin_amdgcn_s_barrier();
;             if (p + 1 < 8) ATT_VLOAD((p + 1) & 1, p + 1);
;             __builtin_amdgcn_sched_barrier(0);
; #pragma unroll
;             for (int df = 0; df < 8; ++df) o[df] = __builtin_amdgcn_mfma_f32_16x16x32_bf16(va[p & 1][df], pb[p], o[df], 0, 0, 0);
;             __builtin_amdgcn_sched_barrier(0);
;         }
.Lrg_v_B:
	s_waitcnt vmcnt(6)
	s_barrier
	s_add_i32 m0, s59, 57344
	v_add_co_u32_e32 v222, vcc, s2, v226
	s_nop 1
	v_addc_co_u32_e32 v223, vcc, 0, v227, vcc
	global_load_lds_dwordx4 v[222:223], off
	s_waitcnt vmcnt(6)
	s_barrier
	s_add_i32 m0, s59, 0
	v_add_co_u32_e32 v222, vcc, s60, v220
	s_nop 1
	v_addc_co_u32_e32 v223, vcc, 0, v221, vcc
	global_load_lds_dwordx4 v[222:223], off
	s_waitcnt vmcnt(6)
	s_barrier
	s_add_i32 m0, s59, 8192
	v_add_co_u32_e32 v222, vcc, s60, v226
	s_nop 1
	v_addc_co_u32_e32 v223, vcc, 0, v227, vcc
	global_load_lds_dwordx4 v[222:223], off
	ds_read_b128 v[106:109], v219 offset:16384
	ds_read_b128 v[110:113], v219 offset:16640
	ds_read_b128 v[114:117], v219 offset:16896
	ds_read_b128 v[118:121], v219 offset:17152
	s_waitcnt lgkmcnt(3)
	v_mfma_f32_16x16x32_bf16 v[22:25], v[106:109], v[66:69], 0
	s_waitcnt lgkmcnt(2)
	v_mfma_f32_16x16x32_bf16 v[30:33], v[110:113], v[66:69], 0
	s_waitcnt lgkmcnt(1)
	v_mfma_f32_16x16x32_bf16 v[34:37], v[114:117], v[66:69], 0
	s_waitcnt lgkmcnt(0)
	v_mfma_f32_16x16x32_bf16 v[38:41], v[118:121], v[66:69], 0
	s_waitcnt vmcnt(6)
	s_barrier
	s_add_i32 m0, s59, 16384
	v_add_co_u32_e32 v222, vcc, s61, v220
	s_nop 1
	v_addc_co_u32_e32 v223, vcc, 0, v221, vcc
	global_load_lds_dwordx4 v[222:223], off
	ds_read_b128 v[122:125], v219 offset:24576
	ds_read_b128 v[126:129], v219 offset:24832
	ds_read_b128 v[58:61], v219 offset:25088
	ds_read_b128 v[62:65], v219 offset:25344
	s_waitcnt lgkmcnt(3)
	v_mfma_f32_16x16x32_bf16 v[42:45], v[122:125], v[66:69], 0
	s_waitcnt lgkmcnt(2)
	v_mfma_f32_16x16x32_bf16 v[46:49], v[126:129], v[66:69], 0
	s_waitcnt lgkmcnt(1)
	v_mfma_f32_16x16x32_bf16 v[50:53], v[58:61], v[66:69], 0
	s_waitcnt lgkmcnt(0)
	v_mfma_f32_16x16x32_bf16 v[54:57], v[62:65], v[66:69], 0
	s_waitcnt vmcnt(6)
	s_barrier
	s_add_i32 m0, s59, 24576
	v_add_co_u32_e32 v222, vcc, s61, v226
	s_nop 1
	v_addc_co_u32_e32 v223, vcc, 0, v227, vcc
	global_load_lds_dwordx4 v[222:223], off
	ds_read_b128 v[106:109], v219 offset:32768
	ds_read_b128 v[110:113], v219 offset:33024
	ds_read_b128 v[114:117], v219 offset:33280
	ds_read_b128 v[118:121], v219 offset:33536
	s_waitcnt lgkmcnt(3)
	v_mfma_f32_16x16x32_bf16 v[22:25], v[106:109], v[70:73], v[22:25]
	s_waitcnt lgkmcnt(2)
	v_mfma_f32_16x16x32_bf16 v[30:33], v[110:113], v[70:73], v[30:33]
	s_waitcnt lgkmcnt(1)
	v_mfma_f32_16x16x32_bf16 v[34:37], v[114:117], v[70:73], v[34:37]
	s_waitcnt lgkmcnt(0)
	v_mfma_f32_16x16x32_bf16 v[38:41], v[118:121], v[70:73], v[38:41]
	s_waitcnt vmcnt(6)
	s_barrier
	s_add_i32 m0, s59, 32768
	v_add_co_u32_e32 v222, vcc, s17, v220
	s_nop 1
	v_addc_co_u32_e32 v223, vcc, 0, v221, vcc
	global_load_lds_dwordx4 v[222:223], off
	ds_read_b128 v[122:125], v219 offset:40960
	ds_read_b128 v[126:129], v219 offset:41216
	ds_read_b128 v[58:61], v219 offset:41472
	ds_read_b128 v[62:65], v219 offset:41728
	s_waitcnt lgkmcnt(3)
	v_mfma_f32_16x16x32_bf16 v[42:45], v[122:125], v[70:73], v[42:45]
	s_waitcnt lgkmcnt(2)
	v_mfma_f32_16x16x32_bf16 v[46:49], v[126:129], v[70:73], v[46:49]
	s_waitcnt lgkmcnt(1)
	v_mfma_f32_16x16x32_bf16 v[50:53], v[58:61], v[70:73], v[50:53]
	s_waitcnt lgkmcnt(0)
	v_mfma_f32_16x16x32_bf16 v[54:57], v[62:65], v[70:73], v[54:57]
	s_waitcnt vmcnt(6)
	s_barrier
	s_add_i32 m0, s59, 40960
	v_add_co_u32_e32 v222, vcc, s17, v226
	s_nop 1
	v_addc_co_u32_e32 v223, vcc, 0, v227, vcc
	global_load_lds_dwordx4 v[222:223], off
	ds_read_b128 v[106:109], v219 offset:49152
	ds_read_b128 v[110:113], v219 offset:49408
	ds_read_b128 v[114:117], v219 offset:49664
	ds_read_b128 v[118:121], v219 offset:49920
	s_waitcnt lgkmcnt(3)
	v_mfma_f32_16x16x32_bf16 v[22:25], v[106:109], v[74:77], v[22:25]
	s_waitcnt lgkmcnt(2)
	v_mfma_f32_16x16x32_bf16 v[30:33], v[110:113], v[74:77], v[30:33]
	s_waitcnt lgkmcnt(1)
	v_mfma_f32_16x16x32_bf16 v[34:37], v[114:117], v[74:77], v[34:37]
	s_waitcnt lgkmcnt(0)
	v_mfma_f32_16x16x32_bf16 v[38:41], v[118:121], v[74:77], v[38:41]
	s_waitcnt vmcnt(6)
	s_barrier
	s_add_i32 m0, s59, 49152
	v_add_co_u32_e32 v222, vcc, s62, v220
	s_nop 1
	v_addc_co_u32_e32 v223, vcc, 0, v221, vcc
	global_load_lds_dwordx4 v[222:223], off
	ds_read_b128 v[122:125], v219 offset:57344
	ds_read_b128 v[126:129], v219 offset:57600
	ds_read_b128 v[58:61], v219 offset:57856
	ds_read_b128 v[62:65], v219 offset:58112
	s_waitcnt lgkmcnt(3)
	v_mfma_f32_16x16x32_bf16 v[42:45], v[122:125], v[74:77], v[42:45]
	s_waitcnt lgkmcnt(2)
	v_mfma_f32_16x16x32_bf16 v[46:49], v[126:129], v[74:77], v[46:49]
	s_waitcnt lgkmcnt(1)
	v_mfma_f32_16x16x32_bf16 v[50:53], v[58:61], v[74:77], v[50:53]
	s_waitcnt lgkmcnt(0)
	v_mfma_f32_16x16x32_bf16 v[54:57], v[62:65], v[74:77], v[54:57]
	s_waitcnt vmcnt(6)
	s_barrier
	s_add_i32 m0, s59, 57344
	v_add_co_u32_e32 v222, vcc, s62, v226
	s_nop 1
	v_addc_co_u32_e32 v223, vcc, 0, v227, vcc
	global_load_lds_dwordx4 v[222:223], off
	ds_read_b128 v[106:109], v219 offset:0
	ds_read_b128 v[110:113], v219 offset:256
	ds_read_b128 v[114:117], v219 offset:512
	ds_read_b128 v[118:121], v219 offset:768
	s_waitcnt lgkmcnt(3)
	v_mfma_f32_16x16x32_bf16 v[22:25], v[106:109], v[78:81], v[22:25]
	s_waitcnt lgkmcnt(2)
	v_mfma_f32_16x16x32_bf16 v[30:33], v[110:113], v[78:81], v[30:33]
	s_waitcnt lgkmcnt(1)
	v_mfma_f32_16x16x32_bf16 v[34:37], v[114:117], v[78:81], v[34:37]
	s_waitcnt lgkmcnt(0)
	v_mfma_f32_16x16x32_bf16 v[38:41], v[118:121], v[78:81], v[38:41]
	s_waitcnt vmcnt(6)
	s_barrier
	s_cmp_eq_u32 s73, 0
	s_cbranch_scc1 .Lrg_v_B_nd9
	s_add_i32 m0, s59, 0
	v_add_co_u32_e32 v222, vcc, s75, v220
	s_nop 1
	v_addc_co_u32_e32 v223, vcc, 0, v221, vcc
	global_load_lds_dwordx4 v[222:223], off
; #define ATT_VLOAD(buf, p) do { const bf16_t* vp_ = vloc + (size_t)((p) * 8 * NH) * 1024; \
;         _Pragma("unroll") for (int df = 0; df < 8; ++df) va[buf][df] = *(const bf16x8*)(vp_ + df * 128); } while (0)
; template <bool LOCAL>
; __device__ __forceinline__ void attn_unit(const bf16_t* Q, const bf16_t* KT, const bf16_t* VT, bf16_t* O, LAS unsigned char* lds, int b, int h, int r, int w, int tq, int lane) {
;     ...
;     if (LOCAL) {
;         const bf16_t* vloc = VT + ((size_t)(((rgl >> 3) + g) * NH + h)) * 1024 + q * 8;
;         bf16x8 va[2][8];
;     ...
;         ATT_VLOAD(0, 0);
; #pragma unroll
;         for (int p = 0; p < 8; ++p) {
;             __builtin_amdgcn_s_barrier();
;             if (p + 1 < 8) ATT_VLOAD((p + 1) & 1, p + 1);
;             __builtin_amdgcn_sched_barrier(0);
; #pragma unroll
;             for (int df = 0; df < 8; ++df) o[df] = __builtin_amdgcn_mfma_f32_16x16x32_bf16(va[p & 1][df], pb[p], o[df], 0, 0, 0);
;             __builtin_amdgcn_sched_barrier(0);
;         }
.Lrg_v_B_nd9:
	ds_read_b128 v[122:125], v219 offset:8192
	ds_read_b128 v[126:129], v219 offset:8448
	ds_read_b128 v[58:61], v219 offset:8704
	ds_read_b128 v[62:65], v219 offset:8960
	s_waitcnt lgkmcnt(3)
	v_mfma_f32_16x16x32_bf16 v[42:45], v[122:125], v[78:81], v[42:45]
	s_waitcnt lgkmcnt(2)
	v_mfma_f32_16x16x32_bf16 v[46:49], v[126:129], v[78:81], v[46:49]
	s_waitcnt lgkmcnt(1)
	v_mfma_f32_16x16x32_bf16 v[50:53], v[58:61], v[78:81], v[50:53]
	s_waitcnt lgkmcnt(0)
	v_mfma_f32_16x16x32_bf16 v[54:57], v[62:65], v[78:81], v[54:57]
	s_waitcnt vmcnt(5)
	s_barrier
	s_cmp_eq_u32 s73, 0
	s_cbranch_scc1 .Lrg_v_B_nd10
	s_add_i32 m0, s59, 8192
	v_add_co_u32_e32 v222, vcc, s75, v226
	s_nop 1
	v_addc_co_u32_e32 v223, vcc, 0, v227, vcc
	global_load_lds_dwordx4 v[222:223], off
.Lrg_v_B_nd10:
	ds_read_b128 v[106:109], v219 offset:16384
	ds_read_b128 v[110:113], v219 offset:16640
	ds_read_b128 v[114:117], v219 offset:16896
	ds_read_b128 v[118:121], v219 offset:17152
	s_waitcnt lgkmcnt(3)
	v_mfma_f32_16x16x32_bf16 v[22:25], v[106:109], v[82:85], v[22:25]
	s_waitcnt lgkmcnt(2)
	v_mfma_f32_16x16x32_bf16 v[30:33], v[110:113], v[82:85], v[30:33]
	s_waitcnt lgkmcnt(1)
	v_mfma_f32_16x16x32_bf16 v[34:37], v[114:117], v[82:85], v[34:37]
	s_waitcnt lgkmcnt(0)
	v_mfma_f32_16x16x32_bf16 v[38:41], v[118:121], v[82:85], v[38:41]
	s_waitcnt vmcnt(4)
	s_barrier
	ds_read_b128 v[122:125], v219 offset:24576
	ds_read_b128 v[126:129], v219 offset:24832
	ds_read_b128 v[58:61], v219 offset:25088
	ds_read_b128 v[62:65], v219 offset:25344
	s_waitcnt lgkmcnt(3)
	v_mfma_f32_16x16x32_bf16 v[42:45], v[122:125], v[82:85], v[42:45]
	s_waitcnt lgkmcnt(2)
	v_mfma_f32_16x16x32_bf16 v[46:49], v[126:129], v[82:85], v[46:49]
	s_waitcnt lgkmcnt(1)
	v_mfma_f32_16x16x32_bf16 v[50:53], v[58:61], v[82:85], v[50:53]
	s_waitcnt lgkmcnt(0)
	v_mfma_f32_16x16x32_bf16 v[54:57], v[62:65], v[82:85], v[54:57]
	s_waitcnt vmcnt(3)
	s_barrier
	ds_read_b128 v[106:109], v219 offset:32768
	ds_read_b128 v[110:113], v219 offset:33024
	ds_read_b128 v[114:117], v219 offset:33280
	ds_read_b128 v[118:121], v219 offset:33536
	s_waitcnt lgkmcnt(3)
	v_mfma_f32_16x16x32_bf16 v[22:25], v[106:109], v[86:89], v[22:25]
	s_waitcnt lgkmcnt(2)
	v_mfma_f32_16x16x32_bf16 v[30:33], v[110:113], v[86:89], v[30:33]
	s_waitcnt lgkmcnt(1)
	v_mfma_f32_16x16x32_bf16 v[34:37], v[114:117], v[86:89], v[34:37]
	s_waitcnt lgkmcnt(0)
	v_mfma_f32_16x16x32_bf16 v[38:41], v[118:121], v[86:89], v[38:41]
	s_waitcnt vmcnt(2)
	s_barrier
	ds_read_b128 v[122:125], v219 offset:40960
	ds_read_b128 v[126:129], v219 offset:41216
	ds_read_b128 v[58:61], v219 offset:41472
	ds_read_b128 v[62:65], v219 offset:41728
	s_waitcnt lgkmcnt(3)
	v_mfma_f32_16x16x32_bf16 v[42:45], v[122:125], v[86:89], v[42:45]
	s_waitcnt lgkmcnt(2)
	v_mfma_f32_16x16x32_bf16 v[46:49], v[126:129], v[86:89], v[46:49]
	s_waitcnt lgkmcnt(1)
	v_mfma_f32_16x16x32_bf16 v[50:53], v[58:61], v[86:89], v[50:53]
	s_waitcnt lgkmcnt(0)
	v_mfma_f32_16x16x32_bf16 v[54:57], v[62:65], v[86:89], v[54:57]
	s_waitcnt vmcnt(1)
	s_barrier
	ds_read_b128 v[106:109], v219 offset:49152
	ds_read_b128 v[110:113], v219 offset:49408
	ds_read_b128 v[114:117], v219 offset:49664
	ds_read_b128 v[118:121], v219 offset:49920
	s_waitcnt lgkmcnt(3)
	v_mfma_f32_16x16x32_bf16 v[22:25], v[106:109], v[94:97], v[22:25]
	s_waitcnt lgkmcnt(2)
	v_mfma_f32_16x16x32_bf16 v[30:33], v[110:113], v[94:97], v[30:33]
	s_waitcnt lgkmcnt(1)
	v_mfma_f32_16x16x32_bf16 v[34:37], v[114:117], v[94:97], v[34:37]
	s_waitcnt lgkmcnt(0)
	v_mfma_f32_16x16x32_bf16 v[38:41], v[118:121], v[94:97], v[38:41]
	s_waitcnt vmcnt(0)
	s_barrier
	ds_read_b128 v[122:125], v219 offset:57344
	ds_read_b128 v[126:129], v219 offset:57600
	ds_read_b128 v[58:61], v219 offset:57856
	ds_read_b128 v[62:65], v219 offset:58112
	s_waitcnt lgkmcnt(3)
	v_mfma_f32_16x16x32_bf16 v[42:45], v[122:125], v[94:97], v[42:45]
	s_waitcnt lgkmcnt(2)
	v_mfma_f32_16x16x32_bf16 v[46:49], v[126:129], v[94:97], v[46:49]
	s_waitcnt lgkmcnt(1)
	v_mfma_f32_16x16x32_bf16 v[50:53], v[58:61], v[94:97], v[50:53]
	s_waitcnt lgkmcnt(0)
	v_mfma_f32_16x16x32_bf16 v[54:57], v[62:65], v[94:97], v[54:57]
	s_cmp_eq_u32 s73, 0
	s_cbranch_scc1 .Lrg_v_B_end
	s_waitcnt vmcnt(1)
	s_barrier
	ds_read_b128 v[106:109], v219 offset:0
	ds_read_b128 v[110:113], v219 offset:256
	ds_read_b128 v[114:117], v219 offset:512
	ds_read_b128 v[118:121], v219 offset:768
	s_waitcnt lgkmcnt(3)
	v_mfma_f32_16x16x32_bf16 v[22:25], v[106:109], v[102:105], v[22:25]
	s_waitcnt lgkmcnt(2)
	v_mfma_f32_16x16x32_bf16 v[30:33], v[110:113], v[102:105], v[30:33]
	s_waitcnt lgkmcnt(1)
	v_mfma_f32_16x16x32_bf16 v[34:37], v[114:117], v[102:105], v[34:37]
	s_waitcnt lgkmcnt(0)
	v_mfma_f32_16x16x32_bf16 v[38:41], v[118:121], v[102:105], v[38:41]
	s_waitcnt vmcnt(0)
	s_barrier
	ds_read_b128 v[122:125], v219 offset:8192
	ds_read_b128 v[126:129], v219 offset:8448
	ds_read_b128 v[58:61], v219 offset:8704
	ds_read_b128 v[62:65], v219 offset:8960
	s_waitcnt lgkmcnt(3)
	v_mfma_f32_16x16x32_bf16 v[42:45], v[122:125], v[102:105], v[42:45]
	s_waitcnt lgkmcnt(2)
	v_mfma_f32_16x16x32_bf16 v[46:49], v[126:129], v[102:105], v[46:49]
	s_waitcnt lgkmcnt(1)
	v_mfma_f32_16x16x32_bf16 v[50:53], v[58:61], v[102:105], v[50:53]
	s_waitcnt lgkmcnt(0)
	v_mfma_f32_16x16x32_bf16 v[54:57], v[62:65], v[102:105], v[54:57]
; #define LAS __attribute__((address_space(3)))
; template <bool LOCAL>
; __device__ __forceinline__ void attn_unit(const bf16_t* Q, const bf16_t* KT, const bf16_t* VT, bf16_t* O, LAS unsigned char* lds, int b, int h, int r, int w, int tq, int lane) {
;     ...
;     {
;         const LAS unsigned char* vl = lds + 65536 + g * 2048 + q * 16;
; #pragma unroll
;         for (int p = 0; p < 8; ++p)
; #pragma unroll
;             for (int df = 0; df < 8; ++df) o[df] = __builtin_amdgcn_mfma_f32_16x16x32_bf16(*(const LAS bf16x8*)(vl + p * 8192 + df * 256), pb[CP + p], o[df], 0, 0, 0);
;     }
; __global__ void __launch_bounds__(NTHREADS, 2) mega(Args args) {
;     ...
;                       for (int ci = tid; ci < 4096; ci += NTHREADS) { const int o = ci >> 7, wq = ci & 127;
;                           const u32x4 kv = *(const u32x4*)(KTp + ((size_t)((oc0 + o) * NH + h)) * 1024 + wq * 8);
;                           *(LAS u32x4*)(lds + o * 2048 + (wq & ~15) * 16 + ((wq & 15) ^ (o & 2)) * 16) = kv;
.Lrg_v_B_end:
.Lrg_v_done:
	s_barrier
	v_mov_b32_e32 v222, v234
	v_mov_b32_e32 v223, v235
	s_lshl_b32 s55, s57, 10
	s_add_i32 m0, s55, 0
	s_nop 0
	global_load_lds_dwordx4 v[222:223], off
	v_add_co_u32_e32 v222, vcc, 0x20000, v222
	s_nop 1
	v_addc_co_u32_e32 v223, vcc, 0, v223, vcc
	s_add_i32 m0, s55, 8192
	s_nop 0
	global_load_lds_dwordx4 v[222:223], off
	v_add_co_u32_e32 v222, vcc, 0x20000, v222
	s_nop 1
	v_addc_co_u32_e32 v223, vcc, 0, v223, vcc
	s_add_i32 m0, s55, 16384
	s_nop 0
	global_load_lds_dwordx4 v[222:223], off
	v_add_co_u32_e32 v222, vcc, 0x20000, v222
	s_nop 1
	v_addc_co_u32_e32 v223, vcc, 0, v223, vcc
	s_add_i32 m0, s55, 24576
	s_nop 0
	global_load_lds_dwordx4 v[222:223], off
	v_add_co_u32_e32 v222, vcc, 0x20000, v222
	s_nop 1
	v_addc_co_u32_e32 v223, vcc, 0, v223, vcc
	s_add_i32 m0, s55, 32768
	s_nop 0
	global_load_lds_dwordx4 v[222:223], off
	v_add_co_u32_e32 v222, vcc, 0x20000, v222
	s_nop 1
	v_addc_co_u32_e32 v223, vcc, 0, v223, vcc
	s_add_i32 m0, s55, 40960
	s_nop 0
	global_load_lds_dwordx4 v[222:223], off
	v_add_co_u32_e32 v222, vcc, 0x20000, v222
	s_nop 1
	v_addc_co_u32_e32 v223, vcc, 0, v223, vcc
	s_add_i32 m0, s55, 49152
	s_nop 0
	global_load_lds_dwordx4 v[222:223], off
	v_add_co_u32_e32 v222, vcc, 0x20000, v222
	s_nop 1
	v_addc_co_u32_e32 v223, vcc, 0, v223, vcc
	s_add_i32 m0, s55, 57344
	s_nop 0
	global_load_lds_dwordx4 v[222:223], off
	s_waitcnt lgkmcnt(0)
	s_add_i32 s48, s48, 2
	s_add_i32 s52, s52, 2
	s_add_i32 s51, s51, -2
	v_add_u32_e32 v162, 0x80, v162
	s_cmp_eq_u32 s48, 8
	ds_read_b128 v[200:203], v178
	ds_read_b128 v[204:207], v178 offset:256
	ds_read_b128 v[208:211], v178 offset:512
	ds_read_b128 v[212:215], v178 offset:768
	ds_read_b128 v[216:219], v178 offset:1024
	ds_read_b128 v[220:223], v178 offset:1280
	ds_read_b128 v[224:227], v178 offset:1536
	ds_read_b128 v[228:231], v178 offset:1792
	s_waitcnt lgkmcnt(7)
	v_mfma_f32_16x16x32_bf16 v[22:25], v[200:203], v[98:101], v[22:25]
	ds_read_b128 v[200:203], v178 offset:8192
	s_waitcnt lgkmcnt(7)
	v_mfma_f32_16x16x32_bf16 v[30:33], v[204:207], v[98:101], v[30:33]
	ds_read_b128 v[204:207], v178 offset:8448
	s_waitcnt lgkmcnt(7)
	v_mfma_f32_16x16x32_bf16 v[34:37], v[208:211], v[98:101], v[34:37]
	ds_read_b128 v[208:211], v178 offset:8704
	s_waitcnt lgkmcnt(7)
	v_mfma_f32_16x16x32_bf16 v[38:41], v[212:215], v[98:101], v[38:41]
	ds_read_b128 v[212:215], v178 offset:8960
	s_waitcnt lgkmcnt(7)
	v_mfma_f32_16x16x32_bf16 v[42:45], v[216:219], v[98:101], v[42:45]
	ds_read_b128 v[216:219], v178 offset:9216
	s_waitcnt lgkmcnt(7)
	v_mfma_f32_16x16x32_bf16 v[46:49], v[220:223], v[98:101], v[46:49]
	ds_read_b128 v[220:223], v178 offset:9472
	s_waitcnt lgkmcnt(7)
	v_mfma_f32_16x16x32_bf16 v[50:53], v[224:227], v[98:101], v[50:53]
	ds_read_b128 v[224:227], v178 offset:9728
	s_waitcnt lgkmcnt(7)
	v_mfma_f32_16x16x32_bf16 v[54:57], v[228:231], v[98:101], v[54:57]
	ds_read_b128 v[228:231], v178 offset:9984
	s_waitcnt lgkmcnt(7)
	v_mfma_f32_16x16x32_bf16 v[22:25], v[200:203], v[90:93], v[22:25]
	ds_read_b128 v[200:203], v178 offset:16384
	s_waitcnt lgkmcnt(7)
	v_mfma_f32_16x16x32_bf16 v[30:33], v[204:207], v[90:93], v[30:33]
	ds_read_b128 v[204:207], v178 offset:16640
	s_waitcnt lgkmcnt(7)
	v_mfma_f32_16x16x32_bf16 v[34:37], v[208:211], v[90:93], v[34:37]
	ds_read_b128 v[208:211], v178 offset:16896
	s_waitcnt lgkmcnt(7)
	v_mfma_f32_16x16x32_bf16 v[38:41], v[212:215], v[90:93], v[38:41]
	ds_read_b128 v[212:215], v178 offset:17152
	s_waitcnt lgkmcnt(7)
	v_mfma_f32_16x16x32_bf16 v[42:45], v[216:219], v[90:93], v[42:45]
	ds_read_b128 v[216:219], v178 offset:17408
	s_waitcnt lgkmcnt(7)
	v_mfma_f32_16x16x32_bf16 v[46:49], v[220:223], v[90:93], v[46:49]
	ds_read_b128 v[220:223], v178 offset:17664
	s_waitcnt lgkmcnt(7)
	v_mfma_f32_16x16x32_bf16 v[50:53], v[224:227], v[90:93], v[50:53]
	ds_read_b128 v[224:227], v178 offset:17920
	s_waitcnt lgkmcnt(7)
	v_mfma_f32_16x16x32_bf16 v[54:57], v[228:231], v[90:93], v[54:57]
	ds_read_b128 v[228:231], v178 offset:18176
	s_waitcnt lgkmcnt(7)
	v_mfma_f32_16x16x32_bf16 v[22:25], v[200:203], v[26:29], v[22:25]
	ds_read_b128 v[200:203], v178 offset:24576
	s_waitcnt lgkmcnt(7)
	v_mfma_f32_16x16x32_bf16 v[30:33], v[204:207], v[26:29], v[30:33]
	ds_read_b128 v[204:207], v178 offset:24832
	s_waitcnt lgkmcnt(7)
	v_mfma_f32_16x16x32_bf16 v[34:37], v[208:211], v[26:29], v[34:37]
	ds_read_b128 v[208:211], v178 offset:25088
	s_waitcnt lgkmcnt(7)
	v_mfma_f32_16x16x32_bf16 v[38:41], v[212:215], v[26:29], v[38:41]
	ds_read_b128 v[212:215], v178 offset:25344
	s_waitcnt lgkmcnt(7)
	v_mfma_f32_16x16x32_bf16 v[42:45], v[216:219], v[26:29], v[42:45]
	ds_read_b128 v[216:219], v178 offset:25600
	s_waitcnt lgkmcnt(7)
	v_mfma_f32_16x16x32_bf16 v[46:49], v[220:223], v[26:29], v[46:49]
	ds_read_b128 v[220:223], v178 offset:25856
	s_waitcnt lgkmcnt(7)
	v_mfma_f32_16x16x32_bf16 v[50:53], v[224:227], v[26:29], v[50:53]
	ds_read_b128 v[224:227], v178 offset:26112
	s_waitcnt lgkmcnt(7)
	v_mfma_f32_16x16x32_bf16 v[26:29], v[228:231], v[26:29], v[54:57]
	ds_read_b128 v[228:231], v178 offset:26368
	s_waitcnt lgkmcnt(7)
	v_mfma_f32_16x16x32_bf16 v[22:25], v[200:203], v[10:13], v[22:25]
	ds_read_b128 v[200:203], v178 offset:32768
	s_waitcnt lgkmcnt(7)
	v_mfma_f32_16x16x32_bf16 v[30:33], v[204:207], v[10:13], v[30:33]
	ds_read_b128 v[204:207], v178 offset:33024
	s_waitcnt lgkmcnt(7)
	v_mfma_f32_16x16x32_bf16 v[34:37], v[208:211], v[10:13], v[34:37]
	ds_read_b128 v[208:211], v178 offset:33280
	s_waitcnt lgkmcnt(7)
	v_mfma_f32_16x16x32_bf16 v[38:41], v[212:215], v[10:13], v[38:41]
	ds_read_b128 v[212:215], v178 offset:33536
	s_waitcnt lgkmcnt(7)
; #define LAS __attribute__((address_space(3)))
; __device__ __forceinline__ unsigned cvt_pk_bf16(float lo, float hi) { unsigned r; asm volatile("v_cvt_pk_bf16_f32 %0, %1, %2" : "=v"(r) : "v"(lo), "v"(hi)); return r; }
; template <bool LOCAL>
; __device__ __forceinline__ void attn_unit(const bf16_t* Q, const bf16_t* KT, const bf16_t* VT, bf16_t* O, LAS unsigned char* lds, int b, int h, int r, int w, int tq, int lane) {
;     ...
;     {
;         const LAS unsigned char* vl = lds + 65536 + g * 2048 + q * 16;
; #pragma unroll
;         for (int p = 0; p < 8; ++p)
; #pragma unroll
;             for (int df = 0; df < 8; ++df) o[df] = __builtin_amdgcn_mfma_f32_16x16x32_bf16(*(const LAS bf16x8*)(vl + p * 8192 + df * 256), pb[CP + p], o[df], 0, 0, 0);
;     }
;     const float inv = 1.f / sum;
;     bf16_t* op = O + (size_t)qrow * D + h * HD + 4 * g;
; #pragma unroll
;     for (int df = 0; df < 8; ++df) { u32x2 wv; wv.x = cvt_pk_bf16(o[df][0] * inv, o[df][1] * inv); wv.y = cvt_pk_bf16(o[df][2] * inv, o[df][3] * inv); *(u32x2*)(op + 16 * df) = wv; }
	v_mfma_f32_16x16x32_bf16 v[42:45], v[216:219], v[10:13], v[42:45]
	ds_read_b128 v[216:219], v178 offset:33792
	s_waitcnt lgkmcnt(7)
	v_mfma_f32_16x16x32_bf16 v[46:49], v[220:223], v[10:13], v[46:49]
	ds_read_b128 v[220:223], v178 offset:34048
	s_waitcnt lgkmcnt(7)
	v_mfma_f32_16x16x32_bf16 v[50:53], v[224:227], v[10:13], v[50:53]
	ds_read_b128 v[224:227], v178 offset:34304
	s_waitcnt lgkmcnt(7)
	v_mfma_f32_16x16x32_bf16 v[10:13], v[228:231], v[10:13], v[26:29]
	ds_read_b128 v[228:231], v178 offset:34560
	s_waitcnt lgkmcnt(7)
	v_mfma_f32_16x16x32_bf16 v[22:25], v[200:203], v[2:5], v[22:25]
	ds_read_b128 v[200:203], v178 offset:40960
	s_waitcnt lgkmcnt(7)
	v_mfma_f32_16x16x32_bf16 v[26:29], v[204:207], v[2:5], v[30:33]
	ds_read_b128 v[204:207], v178 offset:41216
	s_waitcnt lgkmcnt(7)
	v_mfma_f32_16x16x32_bf16 v[30:33], v[208:211], v[2:5], v[34:37]
	ds_read_b128 v[208:211], v178 offset:41472
	s_waitcnt lgkmcnt(7)
	v_mfma_f32_16x16x32_bf16 v[34:37], v[212:215], v[2:5], v[38:41]
	ds_read_b128 v[212:215], v178 offset:41728
	s_waitcnt lgkmcnt(7)
	v_mfma_f32_16x16x32_bf16 v[38:41], v[216:219], v[2:5], v[42:45]
	ds_read_b128 v[216:219], v178 offset:41984
	s_waitcnt lgkmcnt(7)
	v_mfma_f32_16x16x32_bf16 v[42:45], v[220:223], v[2:5], v[46:49]
	ds_read_b128 v[220:223], v178 offset:42240
	s_waitcnt lgkmcnt(7)
	v_mfma_f32_16x16x32_bf16 v[46:49], v[224:227], v[2:5], v[50:53]
	ds_read_b128 v[224:227], v178 offset:42496
	s_waitcnt lgkmcnt(7)
	v_mfma_f32_16x16x32_bf16 v[2:5], v[228:231], v[2:5], v[10:13]
	ds_read_b128 v[228:231], v178 offset:42752
	s_waitcnt lgkmcnt(7)
	v_mfma_f32_16x16x32_bf16 v[10:13], v[200:203], v[6:9], v[22:25]
	ds_read_b128 v[200:203], v178 offset:49152
	s_waitcnt lgkmcnt(7)
	v_mfma_f32_16x16x32_bf16 v[22:25], v[204:207], v[6:9], v[26:29]
	ds_read_b128 v[204:207], v178 offset:49408
	s_waitcnt lgkmcnt(7)
	v_mfma_f32_16x16x32_bf16 v[26:29], v[208:211], v[6:9], v[30:33]
	ds_read_b128 v[208:211], v178 offset:49664
	s_waitcnt lgkmcnt(7)
	v_mfma_f32_16x16x32_bf16 v[30:33], v[212:215], v[6:9], v[34:37]
	ds_read_b128 v[212:215], v178 offset:49920
	s_waitcnt lgkmcnt(7)
	v_mfma_f32_16x16x32_bf16 v[34:37], v[216:219], v[6:9], v[38:41]
	ds_read_b128 v[216:219], v178 offset:50176
	s_waitcnt lgkmcnt(7)
	v_mfma_f32_16x16x32_bf16 v[38:41], v[220:223], v[6:9], v[42:45]
	ds_read_b128 v[220:223], v178 offset:50432
	s_waitcnt lgkmcnt(7)
	v_mfma_f32_16x16x32_bf16 v[42:45], v[224:227], v[6:9], v[46:49]
	ds_read_b128 v[224:227], v178 offset:50688
	s_waitcnt lgkmcnt(7)
	v_mfma_f32_16x16x32_bf16 v[2:5], v[228:231], v[6:9], v[2:5]
	ds_read_b128 v[228:231], v178 offset:50944
	s_waitcnt lgkmcnt(7)
	v_mfma_f32_16x16x32_bf16 v[6:9], v[200:203], v[14:17], v[10:13]
	ds_read_b128 v[200:203], v178 offset:57344
	s_waitcnt lgkmcnt(7)
	v_mfma_f32_16x16x32_bf16 v[10:13], v[204:207], v[14:17], v[22:25]
	ds_read_b128 v[204:207], v178 offset:57600
	s_waitcnt lgkmcnt(7)
	v_mfma_f32_16x16x32_bf16 v[22:25], v[208:211], v[14:17], v[26:29]
	ds_read_b128 v[208:211], v178 offset:57856
	s_waitcnt lgkmcnt(7)
	v_mfma_f32_16x16x32_bf16 v[26:29], v[212:215], v[14:17], v[30:33]
	ds_read_b128 v[212:215], v178 offset:58112
	s_waitcnt lgkmcnt(7)
	v_mfma_f32_16x16x32_bf16 v[30:33], v[216:219], v[14:17], v[34:37]
	ds_read_b128 v[216:219], v178 offset:58368
	s_waitcnt lgkmcnt(7)
	v_mfma_f32_16x16x32_bf16 v[34:37], v[220:223], v[14:17], v[38:41]
	ds_read_b128 v[220:223], v178 offset:58624
	s_waitcnt lgkmcnt(7)
	v_mfma_f32_16x16x32_bf16 v[38:41], v[224:227], v[14:17], v[42:45]
	ds_read_b128 v[224:227], v178 offset:58880
	s_waitcnt lgkmcnt(7)
	v_mfma_f32_16x16x32_bf16 v[2:5], v[228:231], v[14:17], v[2:5]
	ds_read_b128 v[228:231], v178 offset:59136
	s_waitcnt lgkmcnt(7)
	v_mfma_f32_16x16x32_bf16 v[6:9], v[200:203], v[18:21], v[6:9]
	s_waitcnt lgkmcnt(6)
	v_mfma_f32_16x16x32_bf16 v[10:13], v[204:207], v[18:21], v[10:13]
	s_waitcnt lgkmcnt(5)
	v_mfma_f32_16x16x32_bf16 v[14:17], v[208:211], v[18:21], v[22:25]
	s_waitcnt lgkmcnt(4)
	v_mfma_f32_16x16x32_bf16 v[22:25], v[212:215], v[18:21], v[26:29]
	s_waitcnt lgkmcnt(3)
	v_mfma_f32_16x16x32_bf16 v[26:29], v[216:219], v[18:21], v[30:33]
	s_waitcnt lgkmcnt(2)
	v_mfma_f32_16x16x32_bf16 v[30:33], v[220:223], v[18:21], v[34:37]
	s_waitcnt lgkmcnt(1)
	v_mfma_f32_16x16x32_bf16 v[34:37], v[224:227], v[18:21], v[38:41]
	s_waitcnt lgkmcnt(0)
	v_mfma_f32_16x16x32_bf16 v[2:5], v[228:231], v[18:21], v[2:5]
	s_nop 7
	v_add_f32_e32 v18, v134, v135
	v_div_scale_f32 v19, s[4:5], v18, v18, 1.0
	v_rcp_f32_e32 v20, v19
	s_nop 0
	v_fma_f32 v21, -v19, v20, 1.0
	v_fmac_f32_e32 v20, v21, v20
	v_div_scale_f32 v21, vcc, 1.0, v18, 1.0
	v_mul_f32_e32 v38, v21, v20
	v_fma_f32 v39, -v19, v38, v21
	v_fmac_f32_e32 v38, v39, v20
	v_fma_f32 v19, -v19, v38, v21
	v_div_fmas_f32 v19, v19, v20, v38
	v_div_fixup_f32 v20, v19, v18, 1.0
	v_mul_f32_e32 v6, v20, v6
	v_mul_f32_e32 v7, v20, v7
	v_cvt_pk_bf16_f32 v6, v6, v7
	v_mul_f32_e32 v7, v20, v8
	v_lshl_add_u64 v[18:19], v[130:131], 1, v[160:161]
	v_mul_f32_e32 v8, v20, v9
	v_cvt_pk_bf16_f32 v7, v7, v8
	global_store_dwordx2 v[18:19], v[6:7], off
	v_mul_f32_e32 v6, v20, v10
	v_mul_f32_e32 v7, v20, v11
	v_cvt_pk_bf16_f32 v6, v6, v7
	v_mul_f32_e32 v7, v20, v12
	v_mul_f32_e32 v8, v20, v13
	v_cvt_pk_bf16_f32 v7, v7, v8
	global_store_dwordx2 v[18:19], v[6:7], off offset:32
	v_mul_f32_e32 v6, v20, v14
	v_mul_f32_e32 v7, v20, v15
	v_cvt_pk_bf16_f32 v6, v6, v7
	v_mul_f32_e32 v7, v20, v16
	v_mul_f32_e32 v8, v20, v17
	v_cvt_pk_bf16_f32 v7, v7, v8
	global_store_dwordx2 v[18:19], v[6:7], off offset:64
	v_mul_f32_e32 v6, v20, v22
	v_mul_f32_e32 v7, v20, v23
	v_cvt_pk_bf16_f32 v6, v6, v7
	v_mul_f32_e32 v7, v20, v24
	v_mul_f32_e32 v8, v20, v25
	v_cvt_pk_bf16_f32 v7, v7, v8
	global_store_dwordx2 v[18:19], v[6:7], off offset:96
	v_mul_f32_e32 v6, v20, v26
	v_mul_f32_e32 v7, v20, v27
	v_cvt_pk_bf16_f32 v6, v6, v7
	v_mul_f32_e32 v7, v20, v28
	v_mul_f32_e32 v8, v20, v29
	v_cvt_pk_bf16_f32 v7, v7, v8
	global_store_dwordx2 v[18:19], v[6:7], off offset:128
	v_mul_f32_e32 v6, v20, v30
	v_mul_f32_e32 v7, v20, v31
	v_cvt_pk_bf16_f32 v6, v6, v7
	v_mul_f32_e32 v7, v20, v32
	v_mul_f32_e32 v8, v20, v33
	v_cvt_pk_bf16_f32 v7, v7, v8
	global_store_dwordx2 v[18:19], v[6:7], off offset:160
	v_mul_f32_e32 v6, v20, v34
	v_mul_f32_e32 v7, v20, v35
	v_cvt_pk_bf16_f32 v6, v6, v7
	v_mul_f32_e32 v7, v20, v36
	v_mul_f32_e32 v2, v20, v2
	v_mul_f32_e32 v3, v20, v3
	v_mul_f32_e32 v8, v20, v37
	v_cvt_pk_bf16_f32 v7, v7, v8
	global_store_dwordx2 v[18:19], v[6:7], off offset:192
	v_cvt_pk_bf16_f32 v2, v2, v3
	v_mul_f32_e32 v3, v20, v4
	v_mul_f32_e32 v4, v20, v5
	v_cvt_pk_bf16_f32 v3, v3, v4
	global_store_dwordx2 v[18:19], v[2:3], off offset:224
	s_waitcnt vmcnt(0)
	s_barrier
	s_cbranch_scc1 .LBB9_802
; #define ATT_KLOAD(buf, p) do { const bf16_t* kp_ = kloc + (size_t)((p) * 8 * NH) * 1024; \
;         _Pragma("unroll") for (int f = 0; f < 2; ++f) _Pragma("unroll") for (int ks = 0; ks < 4; ++ks) ka[buf][f * 4 + ks] = *(const bf16x8*)(kp_ + f * 128 + ks * 256); } while (0)
; template <bool LOCAL>
; __device__ __forceinline__ void attn_unit(const bf16_t* Q, const bf16_t* KT, const bf16_t* VT, bf16_t* O, LAS unsigned char* lds, int b, int h, int r, int w, int tq, int lane) {
;     const int g = lane >> 4, q = lane & 15;
;     const int qrow = LOCAL ? (b * SEQ + r * GRID_W + 16 * w + q) : (ML + b * CTX + 16 * tq + q);
;     bf16x8 bq[4];
;     { const bf16_t* qp = Q + (size_t)qrow * D + h * HD + 8 * g;
; #pragma unroll
;       for (int ks = 0; ks < 4; ++ks) bq[ks] = *(const bf16x8*)(qp + 32 * ks); }
;     constexpr int NP = LOCAL ? 16 : 8, CP = LOCAL ? 8 : 0;
;     f32x4 s[2 * NP];
;     int rs = 0, ws = 0;
;     if (LOCAL) { rs = r - 4; rs = rs < 0 ? 0 : (rs > 24 ? 24 : rs); ws = 16 * w - 8; ws = ws < 0 ? 0 : (ws > 32 ? 32 : ws); }
;     const int rgl = b * SEQ + rs * GRID_W + ws;
;     if (LOCAL) {
;         const bf16_t* kloc = KT + ((size_t)(((rgl >> 3) + (q >> 2)) * NH + h)) * 1024 + (q & 3) * 32 + g * 8;
;         bf16x8 ka[2][8];
;     ...
;         ATT_KLOAD(0, 0);
; #pragma unroll
;         for (int p = 0; p < 8; ++p) {
;             __builtin_amdgcn_s_barrier();
;             if (p + 1 < 8) ATT_KLOAD((p + 1) & 1, p + 1);
;             __builtin_amdgcn_sched_barrier(0);
; #pragma unroll
;             for (int f = 0; f < 2; ++f) { f32x4 a = {0.f, 0.f, 0.f, 0.f};
; #pragma unroll
;                 for (int ks = 0; ks < 4; ++ks) a = __builtin_amdgcn_mfma_f32_16x16x32_bf16(ka[p & 1][f * 4 + ks], bq[ks], a, 0, 0, 0);
;                 s[2 * p + f] = a; }
.LBB9_674:
	v_ashrrev_i32_e32 v163, 31, v162
	v_lshlrev_b64 v[2:3], 12, v[162:163]
	s_add_i32 s4, s50, s48
	v_lshl_add_u64 v[2:3], v[158:159], 0, v[2:3]
	global_load_dwordx4 v[138:141], v[2:3], off
	global_load_dwordx4 v[134:137], v[2:3], off offset:64
	global_load_dwordx4 v[130:133], v[2:3], off offset:128
	global_load_dwordx4 v[62:65], v[2:3], off offset:192
	v_med3_i32 v2, s4, 4, 28
	v_lshlrev_b32_e32 v2, 6, v2
	v_add_u32_e32 v2, v2, v157
	v_add_u32_e32 v2, 0xffffff00, v2
	v_ashrrev_i32_e32 v194, 3, v2
	v_add_u32_e32 v2, v194, v168
	v_lshl_or_b32 v2, v2, 4, s72
	v_ashrrev_i32_e32 v3, 31, v2
	v_lshlrev_b64 v[2:3], 11, v[2:3]
	v_lshl_add_u64 v[70:71], v[146:147], 0, v[2:3]
	v_med3_i32 v232, s52, 4, 28
	v_add_u32_e32 v195, s51, v232
	s_and_b32 s54, s70, 3
	s_lshl_b32 s54, s54, 3
	s_add_i32 s54, s54, s48
	s_add_i32 s55, s54, -4
	s_max_i32 s55, s55, 0
	s_min_i32 s55, s55, 24
	s_add_i32 s73, s54, -3
	s_max_i32 s73, s73, 0
	s_min_i32 s73, s73, 24
	s_sub_i32 s73, s73, s55
	s_lshr_b32 s54, s57, 2
	s_mul_i32 s53, s73, s54
	s_ashr_i32 s54, s70, 6
	s_lshl_b32 s54, s54, 8
	s_lshl_b32 s55, s55, 3
	s_add_i32 s54, s54, s55
	s_add_i32 s54, s54, s57
	s_lshl_b32 s54, s54, 15
	s_lshl_b32 s55, s72, 11
	s_add_i32 s28, s54, s55
	s_mov_b32 s75, 0x200000
	s_lshl_b32 s54, s57, 10
	s_add_i32 s59, s54, 0x10000
	s_and_b32 s54, s57, 1
	s_lshl_b32 s54, s54, 1
	v_xor_b32_e32 v218, s54, v164
	v_lshlrev_b32_e32 v218, 4, v218
	v_add_u32_e32 v218, s28, v218
	ds_read_b64 v[220:221], v241 offset:192
	s_waitcnt lgkmcnt(0)
	v_add_co_u32_e32 v220, vcc, 0x21f00000, v220
	s_nop 1
	v_addc_co_u32_e32 v221, vcc, 0, v221, vcc
	v_add_co_u32_e32 v220, vcc, v220, v218
	s_nop 1
	v_addc_co_u32_e32 v221, vcc, 0, v221, vcc
	v_add_co_u32_e32 v226, vcc, 0x400, v220
	s_nop 1
	v_addc_co_u32_e32 v227, vcc, 0, v221, vcc
	s_and_b32 s55, s57, 3
	s_lshl_b32 s55, s55, 1
	s_add_i32 s55, s55, -1
	s_max_i32 s55, s55, 0
	s_min_i32 s55, s55, 4
	v_lshrrev_b32_e32 v219, 2, v166
	v_add_u32_e32 v219, s55, v219
	v_and_b32_e32 v224, 3, v166
	v_lshl_or_b32 v224, v224, 2, v165
	v_and_b32_e32 v225, 1, v219
	v_lshlrev_b32_e32 v225, 1, v225
	v_xor_b32_e32 v224, v224, v225
	v_lshlrev_b32_e32 v224, 4, v224
	v_lshl_add_u32 v219, v219, 10, v224
	v_add_u32_e32 v219, 0x10000, v219
	s_add_i32 m0, s59, 0
	s_nop 0
	global_load_lds_dwordx4 v[220:221], off
	s_add_i32 m0, s59, 8192
	s_nop 0
	global_load_lds_dwordx4 v[226:227], off
	s_add_i32 m0, s59, 16384
	v_add_co_u32_e32 v222, vcc, s6, v220
	s_nop 1
	v_addc_co_u32_e32 v223, vcc, 0, v221, vcc
	global_load_lds_dwordx4 v[222:223], off
	s_add_i32 m0, s59, 24576
	v_add_co_u32_e32 v222, vcc, s6, v226
	s_nop 1
	v_addc_co_u32_e32 v223, vcc, 0, v227, vcc
	global_load_lds_dwordx4 v[222:223], off
	s_add_i32 m0, s59, 32768
	v_add_co_u32_e32 v222, vcc, s7, v220
	s_nop 1
	v_addc_co_u32_e32 v223, vcc, 0, v221, vcc
	global_load_lds_dwordx4 v[222:223], off
	s_add_i32 m0, s59, 40960
	v_add_co_u32_e32 v222, vcc, s7, v226
	s_nop 1
	v_addc_co_u32_e32 v223, vcc, 0, v227, vcc
	global_load_lds_dwordx4 v[222:223], off
	s_add_i32 m0, s59, 49152
	v_add_co_u32_e32 v222, vcc, s2, v220
	s_nop 1
	v_addc_co_u32_e32 v223, vcc, 0, v221, vcc
	global_load_lds_dwordx4 v[222:223], off
	s_cmp_eq_u32 s53, 0
	s_cbranch_scc0 .Lrg_k_B
	s_waitcnt vmcnt(6)
	s_barrier
	s_add_i32 m0, s59, 57344
	v_add_co_u32_e32 v222, vcc, s2, v226
	s_nop 1
	v_addc_co_u32_e32 v223, vcc, 0, v227, vcc
	global_load_lds_dwordx4 v[222:223], off
	ds_read_b128 v[2:5], v219 offset:0
	ds_read_b128 v[6:9], v219 offset:256
	ds_read_b128 v[10:13], v219 offset:512
	ds_read_b128 v[14:17], v219 offset:768
	s_waitcnt lgkmcnt(3)
	v_mfma_f32_16x16x32_bf16 v[126:129], v[2:5], v[138:141], 0
	s_waitcnt lgkmcnt(2)
	v_mfma_f32_16x16x32_bf16 v[122:125], v[6:9], v[138:141], 0
	s_waitcnt lgkmcnt(1)
	v_mfma_f32_16x16x32_bf16 v[126:129], v[10:13], v[134:137], v[126:129]
	s_waitcnt lgkmcnt(0)
	v_mfma_f32_16x16x32_bf16 v[122:125], v[14:17], v[134:137], v[122:125]
	s_waitcnt vmcnt(6)
	s_barrier
	s_add_i32 m0, s59, 0
	v_add_co_u32_e32 v222, vcc, s60, v220
	s_nop 1
	v_addc_co_u32_e32 v223, vcc, 0, v221, vcc
	global_load_lds_dwordx4 v[222:223], off
	ds_read_b128 v[18:21], v219 offset:8192
	ds_read_b128 v[22:25], v219 offset:8448
	ds_read_b128 v[26:29], v219 offset:8704
	ds_read_b128 v[30:33], v219 offset:8960
	s_waitcnt lgkmcnt(3)
	v_mfma_f32_16x16x32_bf16 v[126:129], v[18:21], v[130:133], v[126:129]
	s_waitcnt lgkmcnt(2)
	v_mfma_f32_16x16x32_bf16 v[122:125], v[22:25], v[130:133], v[122:125]
	s_waitcnt lgkmcnt(1)
	v_mfma_f32_16x16x32_bf16 v[126:129], v[26:29], v[62:65], v[126:129]
	s_waitcnt lgkmcnt(0)
	v_mfma_f32_16x16x32_bf16 v[122:125], v[30:33], v[62:65], v[122:125]
	s_waitcnt vmcnt(6)
	s_barrier
	s_add_i32 m0, s59, 8192
	v_add_co_u32_e32 v222, vcc, s60, v226
	s_nop 1
	v_addc_co_u32_e32 v223, vcc, 0, v227, vcc
	global_load_lds_dwordx4 v[222:223], off
	ds_read_b128 v[2:5], v219 offset:16384
	ds_read_b128 v[6:9], v219 offset:16640
	ds_read_b128 v[10:13], v219 offset:16896
	ds_read_b128 v[14:17], v219 offset:17152
	s_waitcnt lgkmcnt(3)
	v_mfma_f32_16x16x32_bf16 v[118:121], v[2:5], v[138:141], 0
	s_waitcnt lgkmcnt(2)
	v_mfma_f32_16x16x32_bf16 v[114:117], v[6:9], v[138:141], 0
	s_waitcnt lgkmcnt(1)
	v_mfma_f32_16x16x32_bf16 v[118:121], v[10:13], v[134:137], v[118:121]
	s_waitcnt lgkmcnt(0)
	v_mfma_f32_16x16x32_bf16 v[114:117], v[14:17], v[134:137], v[114:117]
	s_waitcnt vmcnt(6)
	s_barrier
; #define ATT_KLOAD(buf, p) do { const bf16_t* kp_ = kloc + (size_t)((p) * 8 * NH) * 1024; \
;         _Pragma("unroll") for (int f = 0; f < 2; ++f) _Pragma("unroll") for (int ks = 0; ks < 4; ++ks) ka[buf][f * 4 + ks] = *(const bf16x8*)(kp_ + f * 128 + ks * 256); } while (0)
; template <bool LOCAL>
; __device__ __forceinline__ void attn_unit(const bf16_t* Q, const bf16_t* KT, const bf16_t* VT, bf16_t* O, LAS unsigned char* lds, int b, int h, int r, int w, int tq, int lane) {
;     ...
;     if (LOCAL) {
;         const bf16_t* kloc = KT + ((size_t)(((rgl >> 3) + (q >> 2)) * NH + h)) * 1024 + (q & 3) * 32 + g * 8;
;         bf16x8 ka[2][8];
;     ...
;         ATT_KLOAD(0, 0);
; #pragma unroll
;         for (int p = 0; p < 8; ++p) {
;             __builtin_amdgcn_s_barrier();
;             if (p + 1 < 8) ATT_KLOAD((p + 1) & 1, p + 1);
;             __builtin_amdgcn_sched_barrier(0);
; #pragma unroll
;             for (int f = 0; f < 2; ++f) { f32x4 a = {0.f, 0.f, 0.f, 0.f};
; #pragma unroll
;                 for (int ks = 0; ks < 4; ++ks) a = __builtin_amdgcn_mfma_f32_16x16x32_bf16(ka[p & 1][f * 4 + ks], bq[ks], a, 0, 0, 0);
;                 s[2 * p + f] = a; }
;             __builtin_amdgcn_sched_barrier(0);
;         }
	s_add_i32 m0, s59, 16384
	v_add_co_u32_e32 v222, vcc, s61, v220
	s_nop 1
	v_addc_co_u32_e32 v223, vcc, 0, v221, vcc
	global_load_lds_dwordx4 v[222:223], off
	ds_read_b128 v[18:21], v219 offset:24576
	ds_read_b128 v[22:25], v219 offset:24832
	ds_read_b128 v[26:29], v219 offset:25088
	ds_read_b128 v[30:33], v219 offset:25344
	s_waitcnt lgkmcnt(3)
	v_mfma_f32_16x16x32_bf16 v[118:121], v[18:21], v[130:133], v[118:121]
	s_waitcnt lgkmcnt(2)
	v_mfma_f32_16x16x32_bf16 v[114:117], v[22:25], v[130:133], v[114:117]
	s_waitcnt lgkmcnt(1)
	v_mfma_f32_16x16x32_bf16 v[118:121], v[26:29], v[62:65], v[118:121]
	s_waitcnt lgkmcnt(0)
	v_mfma_f32_16x16x32_bf16 v[114:117], v[30:33], v[62:65], v[114:117]
	s_waitcnt vmcnt(6)
	s_barrier
	s_add_i32 m0, s59, 24576
	v_add_co_u32_e32 v222, vcc, s61, v226
	s_nop 1
	v_addc_co_u32_e32 v223, vcc, 0, v227, vcc
	global_load_lds_dwordx4 v[222:223], off
	ds_read_b128 v[2:5], v219 offset:32768
	ds_read_b128 v[6:9], v219 offset:33024
	ds_read_b128 v[10:13], v219 offset:33280
	ds_read_b128 v[14:17], v219 offset:33536
	s_waitcnt lgkmcnt(3)
	v_mfma_f32_16x16x32_bf16 v[110:113], v[2:5], v[138:141], 0
	s_waitcnt lgkmcnt(2)
	v_mfma_f32_16x16x32_bf16 v[106:109], v[6:9], v[138:141], 0
	s_waitcnt lgkmcnt(1)
	v_mfma_f32_16x16x32_bf16 v[110:113], v[10:13], v[134:137], v[110:113]
	s_waitcnt lgkmcnt(0)
	v_mfma_f32_16x16x32_bf16 v[106:109], v[14:17], v[134:137], v[106:109]
	s_waitcnt vmcnt(6)
	s_barrier
	s_add_i32 m0, s59, 32768
	v_add_co_u32_e32 v222, vcc, s17, v220
	s_nop 1
	v_addc_co_u32_e32 v223, vcc, 0, v221, vcc
	global_load_lds_dwordx4 v[222:223], off
	ds_read_b128 v[18:21], v219 offset:40960
	ds_read_b128 v[22:25], v219 offset:41216
	ds_read_b128 v[26:29], v219 offset:41472
	ds_read_b128 v[30:33], v219 offset:41728
	s_waitcnt lgkmcnt(3)
	v_mfma_f32_16x16x32_bf16 v[110:113], v[18:21], v[130:133], v[110:113]
	s_waitcnt lgkmcnt(2)
	v_mfma_f32_16x16x32_bf16 v[106:109], v[22:25], v[130:133], v[106:109]
	s_waitcnt lgkmcnt(1)
	v_mfma_f32_16x16x32_bf16 v[110:113], v[26:29], v[62:65], v[110:113]
	s_waitcnt lgkmcnt(0)
	v_mfma_f32_16x16x32_bf16 v[106:109], v[30:33], v[62:65], v[106:109]
	s_waitcnt vmcnt(6)
	s_barrier
	s_add_i32 m0, s59, 40960
	v_add_co_u32_e32 v222, vcc, s17, v226
	s_nop 1
	v_addc_co_u32_e32 v223, vcc, 0, v227, vcc
	global_load_lds_dwordx4 v[222:223], off
	ds_read_b128 v[2:5], v219 offset:49152
	ds_read_b128 v[6:9], v219 offset:49408
	ds_read_b128 v[10:13], v219 offset:49664
	ds_read_b128 v[14:17], v219 offset:49920
	s_waitcnt lgkmcnt(3)
	v_mfma_f32_16x16x32_bf16 v[102:105], v[2:5], v[138:141], 0
	s_waitcnt lgkmcnt(2)
	v_mfma_f32_16x16x32_bf16 v[98:101], v[6:9], v[138:141], 0
	s_waitcnt lgkmcnt(1)
	v_mfma_f32_16x16x32_bf16 v[102:105], v[10:13], v[134:137], v[102:105]
	s_waitcnt lgkmcnt(0)
	v_mfma_f32_16x16x32_bf16 v[98:101], v[14:17], v[134:137], v[98:101]
	s_waitcnt vmcnt(6)
	s_barrier
	s_add_i32 m0, s59, 49152
	v_add_co_u32_e32 v222, vcc, s62, v220
	s_nop 1
	v_addc_co_u32_e32 v223, vcc, 0, v221, vcc
	global_load_lds_dwordx4 v[222:223], off
	ds_read_b128 v[18:21], v219 offset:57344
	ds_read_b128 v[22:25], v219 offset:57600
	ds_read_b128 v[26:29], v219 offset:57856
	ds_read_b128 v[30:33], v219 offset:58112
	s_waitcnt lgkmcnt(3)
	v_mfma_f32_16x16x32_bf16 v[102:105], v[18:21], v[130:133], v[102:105]
	s_waitcnt lgkmcnt(2)
	v_mfma_f32_16x16x32_bf16 v[98:101], v[22:25], v[130:133], v[98:101]
	s_waitcnt lgkmcnt(1)
	v_mfma_f32_16x16x32_bf16 v[102:105], v[26:29], v[62:65], v[102:105]
	s_waitcnt lgkmcnt(0)
	v_mfma_f32_16x16x32_bf16 v[98:101], v[30:33], v[62:65], v[98:101]
	s_waitcnt vmcnt(6)
	s_barrier
	s_add_i32 m0, s59, 57344
	v_add_co_u32_e32 v222, vcc, s62, v226
	s_nop 1
	v_addc_co_u32_e32 v223, vcc, 0, v227, vcc
	global_load_lds_dwordx4 v[222:223], off
	ds_read_b128 v[2:5], v219 offset:0
	ds_read_b128 v[6:9], v219 offset:256
	ds_read_b128 v[10:13], v219 offset:512
	ds_read_b128 v[14:17], v219 offset:768
	s_waitcnt lgkmcnt(3)
	v_mfma_f32_16x16x32_bf16 v[94:97], v[2:5], v[138:141], 0
	s_waitcnt lgkmcnt(2)
	v_mfma_f32_16x16x32_bf16 v[90:93], v[6:9], v[138:141], 0
	s_waitcnt lgkmcnt(1)
	v_mfma_f32_16x16x32_bf16 v[94:97], v[10:13], v[134:137], v[94:97]
	s_waitcnt lgkmcnt(0)
	v_mfma_f32_16x16x32_bf16 v[90:93], v[14:17], v[134:137], v[90:93]
	s_waitcnt vmcnt(6)
	s_barrier
	s_cmp_eq_u32 s73, 0
	s_cbranch_scc1 .Lrg_k_A_nd9
	s_add_i32 m0, s59, 0
	v_add_co_u32_e32 v222, vcc, s75, v220
	s_nop 1
	v_addc_co_u32_e32 v223, vcc, 0, v221, vcc
	global_load_lds_dwordx4 v[222:223], off
; #define ATT_KLOAD(buf, p) do { const bf16_t* kp_ = kloc + (size_t)((p) * 8 * NH) * 1024; \
;         _Pragma("unroll") for (int f = 0; f < 2; ++f) _Pragma("unroll") for (int ks = 0; ks < 4; ++ks) ka[buf][f * 4 + ks] = *(const bf16x8*)(kp_ + f * 128 + ks * 256); } while (0)
; template <bool LOCAL>
; __device__ __forceinline__ void attn_unit(const bf16_t* Q, const bf16_t* KT, const bf16_t* VT, bf16_t* O, LAS unsigned char* lds, int b, int h, int r, int w, int tq, int lane) {
;     ...
;     if (LOCAL) {
;         const bf16_t* kloc = KT + ((size_t)(((rgl >> 3) + (q >> 2)) * NH + h)) * 1024 + (q & 3) * 32 + g * 8;
;         bf16x8 ka[2][8];
;     ...
;         ATT_KLOAD(0, 0);
; #pragma unroll
;         for (int p = 0; p < 8; ++p) {
;             __builtin_amdgcn_s_barrier();
;             if (p + 1 < 8) ATT_KLOAD((p + 1) & 1, p + 1);
;             __builtin_amdgcn_sched_barrier(0);
; #pragma unroll
;             for (int f = 0; f < 2; ++f) { f32x4 a = {0.f, 0.f, 0.f, 0.f};
; #pragma unroll
;                 for (int ks = 0; ks < 4; ++ks) a = __builtin_amdgcn_mfma_f32_16x16x32_bf16(ka[p & 1][f * 4 + ks], bq[ks], a, 0, 0, 0);
;                 s[2 * p + f] = a; }
;             __builtin_amdgcn_sched_barrier(0);
;         }
.Lrg_k_A_nd9:
	ds_read_b128 v[18:21], v219 offset:8192
	ds_read_b128 v[22:25], v219 offset:8448
	ds_read_b128 v[26:29], v219 offset:8704
	ds_read_b128 v[30:33], v219 offset:8960
	s_waitcnt lgkmcnt(3)
	v_mfma_f32_16x16x32_bf16 v[94:97], v[18:21], v[130:133], v[94:97]
	s_waitcnt lgkmcnt(2)
	v_mfma_f32_16x16x32_bf16 v[90:93], v[22:25], v[130:133], v[90:93]
	s_waitcnt lgkmcnt(1)
	v_mfma_f32_16x16x32_bf16 v[94:97], v[26:29], v[62:65], v[94:97]
	s_waitcnt lgkmcnt(0)
	v_mfma_f32_16x16x32_bf16 v[90:93], v[30:33], v[62:65], v[90:93]
	s_waitcnt vmcnt(5)
	s_barrier
	s_cmp_eq_u32 s73, 0
	s_cbranch_scc1 .Lrg_k_A_nd10
	s_add_i32 m0, s59, 8192
	v_add_co_u32_e32 v222, vcc, s75, v226
	s_nop 1
	v_addc_co_u32_e32 v223, vcc, 0, v227, vcc
	global_load_lds_dwordx4 v[222:223], off
.Lrg_k_A_nd10:
	ds_read_b128 v[2:5], v219 offset:16384
	ds_read_b128 v[6:9], v219 offset:16640
	ds_read_b128 v[10:13], v219 offset:16896
	ds_read_b128 v[14:17], v219 offset:17152
	s_waitcnt lgkmcnt(3)
	v_mfma_f32_16x16x32_bf16 v[86:89], v[2:5], v[138:141], 0
	s_waitcnt lgkmcnt(2)
	v_mfma_f32_16x16x32_bf16 v[82:85], v[6:9], v[138:141], 0
	s_waitcnt lgkmcnt(1)
	v_mfma_f32_16x16x32_bf16 v[86:89], v[10:13], v[134:137], v[86:89]
	s_waitcnt lgkmcnt(0)
	v_mfma_f32_16x16x32_bf16 v[82:85], v[14:17], v[134:137], v[82:85]
	s_waitcnt vmcnt(4)
	s_barrier
	ds_read_b128 v[18:21], v219 offset:24576
	ds_read_b128 v[22:25], v219 offset:24832
	ds_read_b128 v[26:29], v219 offset:25088
	ds_read_b128 v[30:33], v219 offset:25344
	s_waitcnt lgkmcnt(3)
	v_mfma_f32_16x16x32_bf16 v[86:89], v[18:21], v[130:133], v[86:89]
	s_waitcnt lgkmcnt(2)
	v_mfma_f32_16x16x32_bf16 v[82:85], v[22:25], v[130:133], v[82:85]
	s_waitcnt lgkmcnt(1)
	v_mfma_f32_16x16x32_bf16 v[86:89], v[26:29], v[62:65], v[86:89]
	s_waitcnt lgkmcnt(0)
	v_mfma_f32_16x16x32_bf16 v[82:85], v[30:33], v[62:65], v[82:85]
	s_waitcnt vmcnt(3)
	s_barrier
	ds_read_b128 v[2:5], v219 offset:32768
	ds_read_b128 v[6:9], v219 offset:33024
	ds_read_b128 v[10:13], v219 offset:33280
	ds_read_b128 v[14:17], v219 offset:33536
	s_waitcnt lgkmcnt(3)
	v_mfma_f32_16x16x32_bf16 v[78:81], v[2:5], v[138:141], 0
	s_waitcnt lgkmcnt(2)
	v_mfma_f32_16x16x32_bf16 v[74:77], v[6:9], v[138:141], 0
	s_waitcnt lgkmcnt(1)
	v_mfma_f32_16x16x32_bf16 v[78:81], v[10:13], v[134:137], v[78:81]
	s_waitcnt lgkmcnt(0)
	v_mfma_f32_16x16x32_bf16 v[74:77], v[14:17], v[134:137], v[74:77]
	s_waitcnt vmcnt(2)
	s_barrier
	ds_read_b128 v[18:21], v219 offset:40960
	ds_read_b128 v[22:25], v219 offset:41216
	ds_read_b128 v[26:29], v219 offset:41472
	ds_read_b128 v[30:33], v219 offset:41728
	s_waitcnt lgkmcnt(3)
	v_mfma_f32_16x16x32_bf16 v[78:81], v[18:21], v[130:133], v[78:81]
	s_waitcnt lgkmcnt(2)
	v_mfma_f32_16x16x32_bf16 v[74:77], v[22:25], v[130:133], v[74:77]
	s_waitcnt lgkmcnt(1)
	v_mfma_f32_16x16x32_bf16 v[78:81], v[26:29], v[62:65], v[78:81]
	s_waitcnt lgkmcnt(0)
	v_mfma_f32_16x16x32_bf16 v[74:77], v[30:33], v[62:65], v[74:77]
	s_waitcnt vmcnt(1)
	s_barrier
	ds_read_b128 v[2:5], v219 offset:49152
	ds_read_b128 v[6:9], v219 offset:49408
	ds_read_b128 v[10:13], v219 offset:49664
	ds_read_b128 v[14:17], v219 offset:49920
	s_waitcnt lgkmcnt(3)
	v_mfma_f32_16x16x32_bf16 v[70:73], v[2:5], v[138:141], 0
	s_waitcnt lgkmcnt(2)
	v_mfma_f32_16x16x32_bf16 v[66:69], v[6:9], v[138:141], 0
	s_waitcnt lgkmcnt(1)
	v_mfma_f32_16x16x32_bf16 v[70:73], v[10:13], v[134:137], v[70:73]
	s_waitcnt lgkmcnt(0)
	v_mfma_f32_16x16x32_bf16 v[66:69], v[14:17], v[134:137], v[66:69]
	s_waitcnt vmcnt(0)
	s_barrier
	ds_read_b128 v[18:21], v219 offset:57344
	ds_read_b128 v[22:25], v219 offset:57600
	ds_read_b128 v[26:29], v219 offset:57856
	ds_read_b128 v[30:33], v219 offset:58112
	s_waitcnt lgkmcnt(3)
	v_mfma_f32_16x16x32_bf16 v[70:73], v[18:21], v[130:133], v[70:73]
	s_waitcnt lgkmcnt(2)
	v_mfma_f32_16x16x32_bf16 v[66:69], v[22:25], v[130:133], v[66:69]
	s_waitcnt lgkmcnt(1)
	v_mfma_f32_16x16x32_bf16 v[70:73], v[26:29], v[62:65], v[70:73]
	s_waitcnt lgkmcnt(0)
	v_mfma_f32_16x16x32_bf16 v[66:69], v[30:33], v[62:65], v[66:69]
	s_cmp_eq_u32 s73, 0
	s_cbranch_scc1 .Lrg_k_A_end
	s_waitcnt vmcnt(1)
	s_barrier
	s_waitcnt vmcnt(0)
	s_barrier

; #define ATT_KLOAD(buf, p) do { const bf16_t* kp_ = kloc + (size_t)((p) * 8 * NH) * 1024; \
;         _Pragma("unroll") for (int f = 0; f < 2; ++f) _Pragma("unroll") for (int ks = 0; ks < 4; ++ks) ka[buf][f * 4 + ks] = *(const bf16x8*)(kp_ + f * 128 + ks * 256); } while (0)
; template <bool LOCAL>
; __device__ __forceinline__ void attn_unit(const bf16_t* Q, const bf16_t* KT, const bf16_t* VT, bf16_t* O, LAS unsigned char* lds, int b, int h, int r, int w, int tq, int lane) {
;     ...
;     if (LOCAL) {
;         const bf16_t* kloc = KT + ((size_t)(((rgl >> 3) + (q >> 2)) * NH + h)) * 1024 + (q & 3) * 32 + g * 8;
;         bf16x8 ka[2][8];
;     ...
;         ATT_KLOAD(0, 0);
; #pragma unroll
;         for (int p = 0; p < 8; ++p) {
;             __builtin_amdgcn_s_barrier();
;             if (p + 1 < 8) ATT_KLOAD((p + 1) & 1, p + 1);
;             __builtin_amdgcn_sched_barrier(0);
; #pragma unroll
;             for (int f = 0; f < 2; ++f) { f32x4 a = {0.f, 0.f, 0.f, 0.f};
; #pragma unroll
;                 for (int ks = 0; ks < 4; ++ks) a = __builtin_amdgcn_mfma_f32_16x16x32_bf16(ka[p & 1][f * 4 + ks], bq[ks], a, 0, 0, 0);
;                 s[2 * p + f] = a; }
;             __builtin_amdgcn_sched_barrier(0);
;         }
.Lrg_k_B:
	s_waitcnt vmcnt(6)
	s_barrier
	s_add_i32 m0, s59, 57344
	v_add_co_u32_e32 v222, vcc, s2, v226
	s_nop 1
	v_addc_co_u32_e32 v223, vcc, 0, v227, vcc
	global_load_lds_dwordx4 v[222:223], off
	s_waitcnt vmcnt(6)
	s_barrier
	s_add_i32 m0, s59, 0
	v_add_co_u32_e32 v222, vcc, s60, v220
	s_nop 1
	v_addc_co_u32_e32 v223, vcc, 0, v221, vcc
	global_load_lds_dwordx4 v[222:223], off
	s_waitcnt vmcnt(6)
	s_barrier
	s_add_i32 m0, s59, 8192
	v_add_co_u32_e32 v222, vcc, s60, v226
	s_nop 1
	v_addc_co_u32_e32 v223, vcc, 0, v227, vcc
	global_load_lds_dwordx4 v[222:223], off
	ds_read_b128 v[2:5], v219 offset:16384
	ds_read_b128 v[6:9], v219 offset:16640
	ds_read_b128 v[10:13], v219 offset:16896
	ds_read_b128 v[14:17], v219 offset:17152
	s_waitcnt lgkmcnt(3)
	v_mfma_f32_16x16x32_bf16 v[126:129], v[2:5], v[138:141], 0
	s_waitcnt lgkmcnt(2)
	v_mfma_f32_16x16x32_bf16 v[122:125], v[6:9], v[138:141], 0
	s_waitcnt lgkmcnt(1)
	v_mfma_f32_16x16x32_bf16 v[126:129], v[10:13], v[134:137], v[126:129]
	s_waitcnt lgkmcnt(0)
	v_mfma_f32_16x16x32_bf16 v[122:125], v[14:17], v[134:137], v[122:125]
	s_waitcnt vmcnt(6)
	s_barrier
	s_add_i32 m0, s59, 16384
	v_add_co_u32_e32 v222, vcc, s61, v220
	s_nop 1
	v_addc_co_u32_e32 v223, vcc, 0, v221, vcc
	global_load_lds_dwordx4 v[222:223], off
	ds_read_b128 v[18:21], v219 offset:24576
	ds_read_b128 v[22:25], v219 offset:24832
	ds_read_b128 v[26:29], v219 offset:25088
	ds_read_b128 v[30:33], v219 offset:25344
	s_waitcnt lgkmcnt(3)
	v_mfma_f32_16x16x32_bf16 v[126:129], v[18:21], v[130:133], v[126:129]
	s_waitcnt lgkmcnt(2)
	v_mfma_f32_16x16x32_bf16 v[122:125], v[22:25], v[130:133], v[122:125]
	s_waitcnt lgkmcnt(1)
	v_mfma_f32_16x16x32_bf16 v[126:129], v[26:29], v[62:65], v[126:129]
	s_waitcnt lgkmcnt(0)
	v_mfma_f32_16x16x32_bf16 v[122:125], v[30:33], v[62:65], v[122:125]
	s_waitcnt vmcnt(6)
	s_barrier
	s_add_i32 m0, s59, 24576
	v_add_co_u32_e32 v222, vcc, s61, v226
	s_nop 1
	v_addc_co_u32_e32 v223, vcc, 0, v227, vcc
	global_load_lds_dwordx4 v[222:223], off
	ds_read_b128 v[2:5], v219 offset:32768
	ds_read_b128 v[6:9], v219 offset:33024
	ds_read_b128 v[10:13], v219 offset:33280
	ds_read_b128 v[14:17], v219 offset:33536
	s_waitcnt lgkmcnt(3)
	v_mfma_f32_16x16x32_bf16 v[118:121], v[2:5], v[138:141], 0
	s_waitcnt lgkmcnt(2)
	v_mfma_f32_16x16x32_bf16 v[114:117], v[6:9], v[138:141], 0
	s_waitcnt lgkmcnt(1)
	v_mfma_f32_16x16x32_bf16 v[118:121], v[10:13], v[134:137], v[118:121]
	s_waitcnt lgkmcnt(0)
	v_mfma_f32_16x16x32_bf16 v[114:117], v[14:17], v[134:137], v[114:117]
	s_waitcnt vmcnt(6)
	s_barrier
	s_add_i32 m0, s59, 32768
	v_add_co_u32_e32 v222, vcc, s17, v220
	s_nop 1
	v_addc_co_u32_e32 v223, vcc, 0, v221, vcc
	global_load_lds_dwordx4 v[222:223], off
	ds_read_b128 v[18:21], v219 offset:40960
	ds_read_b128 v[22:25], v219 offset:41216
	ds_read_b128 v[26:29], v219 offset:41472
	ds_read_b128 v[30:33], v219 offset:41728
	s_waitcnt lgkmcnt(3)
	v_mfma_f32_16x16x32_bf16 v[118:121], v[18:21], v[130:133], v[118:121]
	s_waitcnt lgkmcnt(2)
	v_mfma_f32_16x16x32_bf16 v[114:117], v[22:25], v[130:133], v[114:117]
	s_waitcnt lgkmcnt(1)
	v_mfma_f32_16x16x32_bf16 v[118:121], v[26:29], v[62:65], v[118:121]
	s_waitcnt lgkmcnt(0)
	v_mfma_f32_16x16x32_bf16 v[114:117], v[30:33], v[62:65], v[114:117]
	s_waitcnt vmcnt(6)
	s_barrier
	s_add_i32 m0, s59, 40960
	v_add_co_u32_e32 v222, vcc, s17, v226
	s_nop 1
	v_addc_co_u32_e32 v223, vcc, 0, v227, vcc
	global_load_lds_dwordx4 v[222:223], off
	ds_read_b128 v[2:5], v219 offset:49152
	ds_read_b128 v[6:9], v219 offset:49408
	ds_read_b128 v[10:13], v219 offset:49664
	ds_read_b128 v[14:17], v219 offset:49920
	s_waitcnt lgkmcnt(3)
	v_mfma_f32_16x16x32_bf16 v[110:113], v[2:5], v[138:141], 0
	s_waitcnt lgkmcnt(2)
	v_mfma_f32_16x16x32_bf16 v[106:109], v[6:9], v[138:141], 0
	s_waitcnt lgkmcnt(1)
	v_mfma_f32_16x16x32_bf16 v[110:113], v[10:13], v[134:137], v[110:113]
	s_waitcnt lgkmcnt(0)
	v_mfma_f32_16x16x32_bf16 v[106:109], v[14:17], v[134:137], v[106:109]
	s_waitcnt vmcnt(6)
	s_barrier
	s_add_i32 m0, s59, 49152
	v_add_co_u32_e32 v222, vcc, s62, v220
	s_nop 1
	v_addc_co_u32_e32 v223, vcc, 0, v221, vcc
	global_load_lds_dwordx4 v[222:223], off
	ds_read_b128 v[18:21], v219 offset:57344
	ds_read_b128 v[22:25], v219 offset:57600
	ds_read_b128 v[26:29], v219 offset:57856
	ds_read_b128 v[30:33], v219 offset:58112
	s_waitcnt lgkmcnt(3)
	v_mfma_f32_16x16x32_bf16 v[110:113], v[18:21], v[130:133], v[110:113]
	s_waitcnt lgkmcnt(2)
	v_mfma_f32_16x16x32_bf16 v[106:109], v[22:25], v[130:133], v[106:109]
	s_waitcnt lgkmcnt(1)
	v_mfma_f32_16x16x32_bf16 v[110:113], v[26:29], v[62:65], v[110:113]
	s_waitcnt lgkmcnt(0)
	v_mfma_f32_16x16x32_bf16 v[106:109], v[30:33], v[62:65], v[106:109]
	s_waitcnt vmcnt(6)
	s_barrier
	s_add_i32 m0, s59, 57344
	v_add_co_u32_e32 v222, vcc, s62, v226
	s_nop 1
	v_addc_co_u32_e32 v223, vcc, 0, v227, vcc
	global_load_lds_dwordx4 v[222:223], off
	ds_read_b128 v[2:5], v219 offset:0
	ds_read_b128 v[6:9], v219 offset:256
	ds_read_b128 v[10:13], v219 offset:512
	ds_read_b128 v[14:17], v219 offset:768
	s_waitcnt lgkmcnt(3)
	v_mfma_f32_16x16x32_bf16 v[102:105], v[2:5], v[138:141], 0
	s_waitcnt lgkmcnt(2)
	v_mfma_f32_16x16x32_bf16 v[98:101], v[6:9], v[138:141], 0
	s_waitcnt lgkmcnt(1)
	v_mfma_f32_16x16x32_bf16 v[102:105], v[10:13], v[134:137], v[102:105]
	s_waitcnt lgkmcnt(0)
	v_mfma_f32_16x16x32_bf16 v[98:101], v[14:17], v[134:137], v[98:101]
	s_waitcnt vmcnt(6)
	s_barrier
	s_cmp_eq_u32 s73, 0
	s_cbranch_scc1 .Lrg_k_B_nd9
	s_add_i32 m0, s59, 0
	v_add_co_u32_e32 v222, vcc, s75, v220
	s_nop 1
	v_addc_co_u32_e32 v223, vcc, 0, v221, vcc
	global_load_lds_dwordx4 v[222:223], off
; #define ATT_KLOAD(buf, p) do { const bf16_t* kp_ = kloc + (size_t)((p) * 8 * NH) * 1024; \
;         _Pragma("unroll") for (int f = 0; f < 2; ++f) _Pragma("unroll") for (int ks = 0; ks < 4; ++ks) ka[buf][f * 4 + ks] = *(const bf16x8*)(kp_ + f * 128 + ks * 256); } while (0)
; template <bool LOCAL>
; __device__ __forceinline__ void attn_unit(const bf16_t* Q, const bf16_t* KT, const bf16_t* VT, bf16_t* O, LAS unsigned char* lds, int b, int h, int r, int w, int tq, int lane) {
;     ...
;     if (LOCAL) {
;         const bf16_t* kloc = KT + ((size_t)(((rgl >> 3) + (q >> 2)) * NH + h)) * 1024 + (q & 3) * 32 + g * 8;
;         bf16x8 ka[2][8];
;     ...
;         ATT_KLOAD(0, 0);
; #pragma unroll
;         for (int p = 0; p < 8; ++p) {
;             __builtin_amdgcn_s_barrier();
;             if (p + 1 < 8) ATT_KLOAD((p + 1) & 1, p + 1);
;             __builtin_amdgcn_sched_barrier(0);
; #pragma unroll
;             for (int f = 0; f < 2; ++f) { f32x4 a = {0.f, 0.f, 0.f, 0.f};
; #pragma unroll
;                 for (int ks = 0; ks < 4; ++ks) a = __builtin_amdgcn_mfma_f32_16x16x32_bf16(ka[p & 1][f * 4 + ks], bq[ks], a, 0, 0, 0);
;                 s[2 * p + f] = a; }
;             __builtin_amdgcn_sched_barrier(0);
;         }
.Lrg_k_B_nd9:
	ds_read_b128 v[18:21], v219 offset:8192
	ds_read_b128 v[22:25], v219 offset:8448
	ds_read_b128 v[26:29], v219 offset:8704
	ds_read_b128 v[30:33], v219 offset:8960
	s_waitcnt lgkmcnt(3)
	v_mfma_f32_16x16x32_bf16 v[102:105], v[18:21], v[130:133], v[102:105]
	s_waitcnt lgkmcnt(2)
	v_mfma_f32_16x16x32_bf16 v[98:101], v[22:25], v[130:133], v[98:101]
	s_waitcnt lgkmcnt(1)
	v_mfma_f32_16x16x32_bf16 v[102:105], v[26:29], v[62:65], v[102:105]
	s_waitcnt lgkmcnt(0)
	v_mfma_f32_16x16x32_bf16 v[98:101], v[30:33], v[62:65], v[98:101]
	s_waitcnt vmcnt(5)
	s_barrier
	s_cmp_eq_u32 s73, 0
	s_cbranch_scc1 .Lrg_k_B_nd10
	s_add_i32 m0, s59, 8192
	v_add_co_u32_e32 v222, vcc, s75, v226
	s_nop 1
	v_addc_co_u32_e32 v223, vcc, 0, v227, vcc
	global_load_lds_dwordx4 v[222:223], off
.Lrg_k_B_nd10:
	ds_read_b128 v[2:5], v219 offset:16384
	ds_read_b128 v[6:9], v219 offset:16640
	ds_read_b128 v[10:13], v219 offset:16896
	ds_read_b128 v[14:17], v219 offset:17152
	s_waitcnt lgkmcnt(3)
	v_mfma_f32_16x16x32_bf16 v[94:97], v[2:5], v[138:141], 0
	s_waitcnt lgkmcnt(2)
	v_mfma_f32_16x16x32_bf16 v[90:93], v[6:9], v[138:141], 0
	s_waitcnt lgkmcnt(1)
	v_mfma_f32_16x16x32_bf16 v[94:97], v[10:13], v[134:137], v[94:97]
	s_waitcnt lgkmcnt(0)
	v_mfma_f32_16x16x32_bf16 v[90:93], v[14:17], v[134:137], v[90:93]
	s_waitcnt vmcnt(4)
	s_barrier
	ds_read_b128 v[18:21], v219 offset:24576
	ds_read_b128 v[22:25], v219 offset:24832
	ds_read_b128 v[26:29], v219 offset:25088
	ds_read_b128 v[30:33], v219 offset:25344
	s_waitcnt lgkmcnt(3)
	v_mfma_f32_16x16x32_bf16 v[94:97], v[18:21], v[130:133], v[94:97]
	s_waitcnt lgkmcnt(2)
	v_mfma_f32_16x16x32_bf16 v[90:93], v[22:25], v[130:133], v[90:93]
	s_waitcnt lgkmcnt(1)
	v_mfma_f32_16x16x32_bf16 v[94:97], v[26:29], v[62:65], v[94:97]
	s_waitcnt lgkmcnt(0)
	v_mfma_f32_16x16x32_bf16 v[90:93], v[30:33], v[62:65], v[90:93]
	s_waitcnt vmcnt(3)
	s_barrier
	ds_read_b128 v[2:5], v219 offset:32768
	ds_read_b128 v[6:9], v219 offset:33024
	ds_read_b128 v[10:13], v219 offset:33280
	ds_read_b128 v[14:17], v219 offset:33536
	s_waitcnt lgkmcnt(3)
	v_mfma_f32_16x16x32_bf16 v[86:89], v[2:5], v[138:141], 0
	s_waitcnt lgkmcnt(2)
	v_mfma_f32_16x16x32_bf16 v[82:85], v[6:9], v[138:141], 0
	s_waitcnt lgkmcnt(1)
	v_mfma_f32_16x16x32_bf16 v[86:89], v[10:13], v[134:137], v[86:89]
	s_waitcnt lgkmcnt(0)
	v_mfma_f32_16x16x32_bf16 v[82:85], v[14:17], v[134:137], v[82:85]
	s_waitcnt vmcnt(2)
	s_barrier
	ds_read_b128 v[18:21], v219 offset:40960
	ds_read_b128 v[22:25], v219 offset:41216
	ds_read_b128 v[26:29], v219 offset:41472
	ds_read_b128 v[30:33], v219 offset:41728
	s_waitcnt lgkmcnt(3)
	v_mfma_f32_16x16x32_bf16 v[86:89], v[18:21], v[130:133], v[86:89]
	s_waitcnt lgkmcnt(2)
	v_mfma_f32_16x16x32_bf16 v[82:85], v[22:25], v[130:133], v[82:85]
	s_waitcnt lgkmcnt(1)
	v_mfma_f32_16x16x32_bf16 v[86:89], v[26:29], v[62:65], v[86:89]
	s_waitcnt lgkmcnt(0)
	v_mfma_f32_16x16x32_bf16 v[82:85], v[30:33], v[62:65], v[82:85]
	s_waitcnt vmcnt(1)
	s_barrier
	ds_read_b128 v[2:5], v219 offset:49152
	ds_read_b128 v[6:9], v219 offset:49408
	ds_read_b128 v[10:13], v219 offset:49664
	ds_read_b128 v[14:17], v219 offset:49920
	s_waitcnt lgkmcnt(3)
	v_mfma_f32_16x16x32_bf16 v[78:81], v[2:5], v[138:141], 0
	s_waitcnt lgkmcnt(2)
	v_mfma_f32_16x16x32_bf16 v[74:77], v[6:9], v[138:141], 0
	s_waitcnt lgkmcnt(1)
	v_mfma_f32_16x16x32_bf16 v[78:81], v[10:13], v[134:137], v[78:81]
	s_waitcnt lgkmcnt(0)
	v_mfma_f32_16x16x32_bf16 v[74:77], v[14:17], v[134:137], v[74:77]
	s_waitcnt vmcnt(0)
	s_barrier
	ds_read_b128 v[18:21], v219 offset:57344
	ds_read_b128 v[22:25], v219 offset:57600
	ds_read_b128 v[26:29], v219 offset:57856
	ds_read_b128 v[30:33], v219 offset:58112
	s_waitcnt lgkmcnt(3)
	v_mfma_f32_16x16x32_bf16 v[78:81], v[18:21], v[130:133], v[78:81]
	s_waitcnt lgkmcnt(2)
	v_mfma_f32_16x16x32_bf16 v[74:77], v[22:25], v[130:133], v[74:77]
	s_waitcnt lgkmcnt(1)
	v_mfma_f32_16x16x32_bf16 v[78:81], v[26:29], v[62:65], v[78:81]
	s_waitcnt lgkmcnt(0)
	v_mfma_f32_16x16x32_bf16 v[74:77], v[30:33], v[62:65], v[74:77]
	s_cmp_eq_u32 s73, 0
	s_cbranch_scc1 .Lrg_k_B_end
	s_waitcnt vmcnt(1)
	s_barrier
	ds_read_b128 v[2:5], v219 offset:0
	ds_read_b128 v[6:9], v219 offset:256
	ds_read_b128 v[10:13], v219 offset:512
	ds_read_b128 v[14:17], v219 offset:768
	s_waitcnt lgkmcnt(3)
	v_mfma_f32_16x16x32_bf16 v[70:73], v[2:5], v[138:141], 0
	s_waitcnt lgkmcnt(2)
	v_mfma_f32_16x16x32_bf16 v[66:69], v[6:9], v[138:141], 0
	s_waitcnt lgkmcnt(1)
	v_mfma_f32_16x16x32_bf16 v[70:73], v[10:13], v[134:137], v[70:73]
	s_waitcnt lgkmcnt(0)
	v_mfma_f32_16x16x32_bf16 v[66:69], v[14:17], v[134:137], v[66:69]
	s_waitcnt vmcnt(0)
	s_barrier
	ds_read_b128 v[18:21], v219 offset:8192
	ds_read_b128 v[22:25], v219 offset:8448
	ds_read_b128 v[26:29], v219 offset:8704
	ds_read_b128 v[30:33], v219 offset:8960
	s_waitcnt lgkmcnt(3)
	v_mfma_f32_16x16x32_bf16 v[70:73], v[18:21], v[130:133], v[70:73]
	s_waitcnt lgkmcnt(2)
	v_mfma_f32_16x16x32_bf16 v[66:69], v[22:25], v[130:133], v[66:69]
	s_waitcnt lgkmcnt(1)
	v_mfma_f32_16x16x32_bf16 v[70:73], v[26:29], v[62:65], v[70:73]
	s_waitcnt lgkmcnt(0)
	v_mfma_f32_16x16x32_bf16 v[66:69], v[30:33], v[62:65], v[66:69]
; #define LAS __attribute__((address_space(3)))
; template <bool LOCAL>
; __device__ __forceinline__ void attn_unit(const bf16_t* Q, const bf16_t* KT, const bf16_t* VT, bf16_t* O, LAS unsigned char* lds, int b, int h, int r, int w, int tq, int lane) {
;     ...
;     {
;         const LAS unsigned char* kl = lds + (q >> 2) * 2048 + (((q & 3) * 4 + g) ^ ((q >> 2) & 2)) * 16;
; #pragma unroll
;         for (int p = 0; p < 8; ++p)
; #pragma unroll
;             for (int f = 0; f < 2; ++f) { f32x4 a = {0.f, 0.f, 0.f, 0.f};
; #pragma unroll
;                 for (int ks = 0; ks < 4; ++ks) a = __builtin_amdgcn_mfma_f32_16x16x32_bf16(*(const LAS bf16x8*)(kl + p * 8192 + ks * 512 + f * 256), bq[ks], a, 0, 0, 0);
;                 s[2 * (CP + p) + f] = a; }
;     }
; __global__ void __launch_bounds__(NTHREADS, 2) mega(Args args) {
;     ...
;                           const u32x4 vv = *(const u32x4*)(VTp + ((size_t)((oc0 + o) * NH + h)) * 1024 + wq * 8);
;                           *(LAS u32x4*)(lds + 65536 + o * 2048 + wq * 16) = vv; }
.Lrg_k_B_end:
.Lrg_k_done:
	s_barrier
	v_mov_b32_e32 v222, v236
	v_mov_b32_e32 v223, v237
	s_lshl_b32 s55, s57, 10
	s_add_i32 m0, s55, 65536
	s_nop 0
	global_load_lds_dwordx4 v[222:223], off
	v_add_co_u32_e32 v222, vcc, 0x20000, v222
	s_nop 1
	v_addc_co_u32_e32 v223, vcc, 0, v223, vcc
	s_add_i32 m0, s55, 73728
	s_nop 0
	global_load_lds_dwordx4 v[222:223], off
	v_add_co_u32_e32 v222, vcc, 0x20000, v222
	s_nop 1
	v_addc_co_u32_e32 v223, vcc, 0, v223, vcc
	s_add_i32 m0, s55, 81920
	s_nop 0
	global_load_lds_dwordx4 v[222:223], off
	v_add_co_u32_e32 v222, vcc, 0x20000, v222
	s_nop 1
	v_addc_co_u32_e32 v223, vcc, 0, v223, vcc
	s_add_i32 m0, s55, 90112
	s_nop 0
	global_load_lds_dwordx4 v[222:223], off
	v_add_co_u32_e32 v222, vcc, 0x20000, v222
	s_nop 1
	v_addc_co_u32_e32 v223, vcc, 0, v223, vcc
	s_add_i32 m0, s55, 98304
	s_nop 0
	global_load_lds_dwordx4 v[222:223], off
	v_add_co_u32_e32 v222, vcc, 0x20000, v222
	s_nop 1
	v_addc_co_u32_e32 v223, vcc, 0, v223, vcc
	s_add_i32 m0, s55, 106496
	s_nop 0
	global_load_lds_dwordx4 v[222:223], off
	v_add_co_u32_e32 v222, vcc, 0x20000, v222
	s_nop 1
	v_addc_co_u32_e32 v223, vcc, 0, v223, vcc
	s_add_i32 m0, s55, 114688
	s_nop 0
	global_load_lds_dwordx4 v[222:223], off
	v_add_co_u32_e32 v222, vcc, 0x20000, v222
	s_nop 1
	v_addc_co_u32_e32 v223, vcc, 0, v223, vcc
	s_add_i32 m0, s55, 122880
	s_nop 0
	global_load_lds_dwordx4 v[222:223], off
	s_nop 5
	s_waitcnt lgkmcnt(0)
	s_movk_i32 s4, 0x7c
	ds_read_b128 v[200:203], v169
	ds_read_b128 v[204:207], v169 offset:512
	ds_read_b128 v[208:211], v169 offset:1024
	ds_read_b128 v[212:215], v169 offset:1536
	ds_read_b128 v[216:219], v169 offset:256
	ds_read_b128 v[220:223], v169 offset:768
	ds_read_b128 v[224:227], v169 offset:1280
	ds_read_b128 v[228:231], v169 offset:1792
	s_waitcnt lgkmcnt(7)
	v_mfma_f32_16x16x32_bf16 v[2:5], v[200:203], v[138:141], 0
	ds_read_b128 v[200:203], v169 offset:8192
	s_waitcnt lgkmcnt(7)
	v_mfma_f32_16x16x32_bf16 v[2:5], v[204:207], v[134:137], v[2:5]
	ds_read_b128 v[204:207], v169 offset:8704
	s_waitcnt lgkmcnt(7)
	v_mfma_f32_16x16x32_bf16 v[2:5], v[208:211], v[130:133], v[2:5]
	ds_read_b128 v[208:211], v169 offset:9216
	s_waitcnt lgkmcnt(7)
	v_mfma_f32_16x16x32_bf16 v[2:5], v[212:215], v[62:65], v[2:5]
	ds_read_b128 v[212:215], v169 offset:9728
	s_waitcnt lgkmcnt(7)
	v_mfma_f32_16x16x32_bf16 v[6:9], v[216:219], v[138:141], 0
	ds_read_b128 v[216:219], v169 offset:8448
	s_waitcnt lgkmcnt(7)
	v_mfma_f32_16x16x32_bf16 v[6:9], v[220:223], v[134:137], v[6:9]
	ds_read_b128 v[220:223], v169 offset:8960
	s_waitcnt lgkmcnt(7)
	v_mfma_f32_16x16x32_bf16 v[6:9], v[224:227], v[130:133], v[6:9]
	ds_read_b128 v[224:227], v169 offset:9472
	s_waitcnt lgkmcnt(7)
	v_mfma_f32_16x16x32_bf16 v[10:13], v[228:231], v[62:65], v[6:9]
	ds_read_b128 v[228:231], v169 offset:9984
	s_waitcnt lgkmcnt(7)
	v_mfma_f32_16x16x32_bf16 v[6:9], v[200:203], v[138:141], 0
	ds_read_b128 v[200:203], v169 offset:16384
	s_waitcnt lgkmcnt(7)
	v_mfma_f32_16x16x32_bf16 v[6:9], v[204:207], v[134:137], v[6:9]
	ds_read_b128 v[204:207], v169 offset:16896
	s_waitcnt lgkmcnt(7)
	v_mfma_f32_16x16x32_bf16 v[6:9], v[208:211], v[130:133], v[6:9]
	ds_read_b128 v[208:211], v169 offset:17408
	s_waitcnt lgkmcnt(7)
	v_mfma_f32_16x16x32_bf16 v[6:9], v[212:215], v[62:65], v[6:9]
	ds_read_b128 v[212:215], v169 offset:17920
	s_waitcnt lgkmcnt(7)
	v_mfma_f32_16x16x32_bf16 v[14:17], v[216:219], v[138:141], 0
	ds_read_b128 v[216:219], v169 offset:16640
	s_waitcnt lgkmcnt(7)
	v_mfma_f32_16x16x32_bf16 v[14:17], v[220:223], v[134:137], v[14:17]
	ds_read_b128 v[220:223], v169 offset:17152
	s_waitcnt lgkmcnt(7)
	v_mfma_f32_16x16x32_bf16 v[14:17], v[224:227], v[130:133], v[14:17]
	ds_read_b128 v[224:227], v169 offset:17664
	s_waitcnt lgkmcnt(7)
	v_mfma_f32_16x16x32_bf16 v[18:21], v[228:231], v[62:65], v[14:17]
	ds_read_b128 v[228:231], v169 offset:18176
	s_waitcnt lgkmcnt(7)
	v_mfma_f32_16x16x32_bf16 v[14:17], v[200:203], v[138:141], 0
	ds_read_b128 v[200:203], v169 offset:24576
	s_waitcnt lgkmcnt(7)
	v_mfma_f32_16x16x32_bf16 v[14:17], v[204:207], v[134:137], v[14:17]
	ds_read_b128 v[204:207], v169 offset:25088
	s_waitcnt lgkmcnt(7)
	v_mfma_f32_16x16x32_bf16 v[14:17], v[208:211], v[130:133], v[14:17]
	ds_read_b128 v[208:211], v169 offset:25600
	s_waitcnt lgkmcnt(7)
	v_mfma_f32_16x16x32_bf16 v[14:17], v[212:215], v[62:65], v[14:17]
	ds_read_b128 v[212:215], v169 offset:26112
	s_waitcnt lgkmcnt(7)
	v_mfma_f32_16x16x32_bf16 v[22:25], v[216:219], v[138:141], 0
	ds_read_b128 v[216:219], v169 offset:24832
	s_waitcnt lgkmcnt(7)
	v_mfma_f32_16x16x32_bf16 v[22:25], v[220:223], v[134:137], v[22:25]
	ds_read_b128 v[220:223], v169 offset:25344
	s_waitcnt lgkmcnt(7)
	v_mfma_f32_16x16x32_bf16 v[22:25], v[224:227], v[130:133], v[22:25]
	ds_read_b128 v[224:227], v169 offset:25856
	s_waitcnt lgkmcnt(7)
	v_mfma_f32_16x16x32_bf16 v[26:29], v[228:231], v[62:65], v[22:25]
	ds_read_b128 v[228:231], v169 offset:26368
	s_waitcnt lgkmcnt(7)
	v_mfma_f32_16x16x32_bf16 v[22:25], v[200:203], v[138:141], 0
	ds_read_b128 v[200:203], v169 offset:32768
	s_waitcnt lgkmcnt(7)
; #define LAS __attribute__((address_space(3)))
; template <bool LOCAL>
; __device__ __forceinline__ void attn_unit(const bf16_t* Q, const bf16_t* KT, const bf16_t* VT, bf16_t* O, LAS unsigned char* lds, int b, int h, int r, int w, int tq, int lane) {
;     ...
;     {
;         const LAS unsigned char* kl = lds + (q >> 2) * 2048 + (((q & 3) * 4 + g) ^ ((q >> 2) & 2)) * 16;
; #pragma unroll
;         for (int p = 0; p < 8; ++p)
; #pragma unroll
;             for (int f = 0; f < 2; ++f) { f32x4 a = {0.f, 0.f, 0.f, 0.f};
; #pragma unroll
;                 for (int ks = 0; ks < 4; ++ks) a = __builtin_amdgcn_mfma_f32_16x16x32_bf16(*(const LAS bf16x8*)(kl + p * 8192 + ks * 512 + f * 256), bq[ks], a, 0, 0, 0);
;                 s[2 * (CP + p) + f] = a; }
;     }
;     if (LOCAL) {
;         const int c = 16 * w + q; int cs = c - 8; cs = cs < 0 ? 0 : (cs > 48 ? 48 : cs);
;         const LAS float* rp = (const LAS float*)(lds + LDS_MISC + 1024);
; #pragma unroll
;         for (int p = 0; p < 8; ++p) { const int ro = (rs + p - r + 7) * 31;
; #pragma unroll
;             for (int f = 0; f < 2; ++f)
; #pragma unroll
;                 for (int j = 0; j < 4; ++j) { const int kc = ws + 8 * g + 4 * f + j; const bool valid = (kc >= cs) && (kc < cs + 16);
;                     int rel = kc - c + 15; rel = rel < 0 ? 0 : (rel > 30 ? 30 : rel);
;                     const float bias = rp[ro + rel];
;                     s[p * 2 + f][j] = valid ? s[p * 2 + f][j] + bias : -INFINITY; } }
	v_mfma_f32_16x16x32_bf16 v[22:25], v[204:207], v[134:137], v[22:25]
	ds_read_b128 v[204:207], v169 offset:33280
	s_waitcnt lgkmcnt(7)
	v_mfma_f32_16x16x32_bf16 v[22:25], v[208:211], v[130:133], v[22:25]
	ds_read_b128 v[208:211], v169 offset:33792
	s_waitcnt lgkmcnt(7)
	v_mfma_f32_16x16x32_bf16 v[22:25], v[212:215], v[62:65], v[22:25]
	ds_read_b128 v[212:215], v169 offset:34304
	s_waitcnt lgkmcnt(7)
	v_mfma_f32_16x16x32_bf16 v[30:33], v[216:219], v[138:141], 0
	ds_read_b128 v[216:219], v169 offset:33024
	s_waitcnt lgkmcnt(7)
	v_mfma_f32_16x16x32_bf16 v[30:33], v[220:223], v[134:137], v[30:33]
	ds_read_b128 v[220:223], v169 offset:33536
	s_waitcnt lgkmcnt(7)
	v_mfma_f32_16x16x32_bf16 v[30:33], v[224:227], v[130:133], v[30:33]
	ds_read_b128 v[224:227], v169 offset:34048
	s_waitcnt lgkmcnt(7)
	v_mfma_f32_16x16x32_bf16 v[34:37], v[228:231], v[62:65], v[30:33]
	ds_read_b128 v[228:231], v169 offset:34560
	s_waitcnt lgkmcnt(7)
	v_mfma_f32_16x16x32_bf16 v[30:33], v[200:203], v[138:141], 0
	ds_read_b128 v[200:203], v169 offset:40960
	s_waitcnt lgkmcnt(7)
	v_mfma_f32_16x16x32_bf16 v[30:33], v[204:207], v[134:137], v[30:33]
	ds_read_b128 v[204:207], v169 offset:41472
	s_waitcnt lgkmcnt(7)
	v_mfma_f32_16x16x32_bf16 v[30:33], v[208:211], v[130:133], v[30:33]
	ds_read_b128 v[208:211], v169 offset:41984
	s_waitcnt lgkmcnt(7)
	v_mfma_f32_16x16x32_bf16 v[30:33], v[212:215], v[62:65], v[30:33]
	ds_read_b128 v[212:215], v169 offset:42496
	s_waitcnt lgkmcnt(7)
	v_mfma_f32_16x16x32_bf16 v[38:41], v[216:219], v[138:141], 0
	ds_read_b128 v[216:219], v169 offset:41216
	s_waitcnt lgkmcnt(7)
	v_mfma_f32_16x16x32_bf16 v[38:41], v[220:223], v[134:137], v[38:41]
	ds_read_b128 v[220:223], v169 offset:41728
	s_waitcnt lgkmcnt(7)
	v_mfma_f32_16x16x32_bf16 v[38:41], v[224:227], v[130:133], v[38:41]
	ds_read_b128 v[224:227], v169 offset:42240
	s_waitcnt lgkmcnt(7)
	v_mfma_f32_16x16x32_bf16 v[42:45], v[228:231], v[62:65], v[38:41]
	ds_read_b128 v[228:231], v169 offset:42752
	s_waitcnt lgkmcnt(7)
	v_mfma_f32_16x16x32_bf16 v[38:41], v[200:203], v[138:141], 0
	ds_read_b128 v[200:203], v169 offset:49152
	s_waitcnt lgkmcnt(7)
	v_mfma_f32_16x16x32_bf16 v[38:41], v[204:207], v[134:137], v[38:41]
	ds_read_b128 v[204:207], v169 offset:49664
	s_waitcnt lgkmcnt(7)
	v_mfma_f32_16x16x32_bf16 v[38:41], v[208:211], v[130:133], v[38:41]
	ds_read_b128 v[208:211], v169 offset:50176
	s_waitcnt lgkmcnt(7)
	v_mfma_f32_16x16x32_bf16 v[38:41], v[212:215], v[62:65], v[38:41]
	ds_read_b128 v[212:215], v169 offset:50688
	s_waitcnt lgkmcnt(7)
	v_mfma_f32_16x16x32_bf16 v[46:49], v[216:219], v[138:141], 0
	ds_read_b128 v[216:219], v169 offset:49408
	s_waitcnt lgkmcnt(7)
	v_mfma_f32_16x16x32_bf16 v[46:49], v[220:223], v[134:137], v[46:49]
	ds_read_b128 v[220:223], v169 offset:49920
	s_waitcnt lgkmcnt(7)
	v_mfma_f32_16x16x32_bf16 v[46:49], v[224:227], v[130:133], v[46:49]
	ds_read_b128 v[224:227], v169 offset:50432
	s_waitcnt lgkmcnt(7)
	v_mfma_f32_16x16x32_bf16 v[50:53], v[228:231], v[62:65], v[46:49]
	ds_read_b128 v[228:231], v169 offset:50944
	s_waitcnt lgkmcnt(7)
	v_mfma_f32_16x16x32_bf16 v[46:49], v[200:203], v[138:141], 0
	ds_read_b128 v[200:203], v169 offset:57344
	s_waitcnt lgkmcnt(7)
	v_mfma_f32_16x16x32_bf16 v[46:49], v[204:207], v[134:137], v[46:49]
	ds_read_b128 v[204:207], v169 offset:57856
	s_waitcnt lgkmcnt(7)
	v_mfma_f32_16x16x32_bf16 v[46:49], v[208:211], v[130:133], v[46:49]
	ds_read_b128 v[208:211], v169 offset:58368
	s_waitcnt lgkmcnt(7)
	v_mfma_f32_16x16x32_bf16 v[46:49], v[212:215], v[62:65], v[46:49]
	ds_read_b128 v[212:215], v169 offset:58880
	s_waitcnt lgkmcnt(7)
	v_mfma_f32_16x16x32_bf16 v[54:57], v[216:219], v[138:141], 0
	ds_read_b128 v[216:219], v169 offset:57600
	s_waitcnt lgkmcnt(7)
	v_mfma_f32_16x16x32_bf16 v[54:57], v[220:223], v[134:137], v[54:57]
	ds_read_b128 v[220:223], v169 offset:58112
	s_waitcnt lgkmcnt(7)
	v_mfma_f32_16x16x32_bf16 v[54:57], v[224:227], v[130:133], v[54:57]
	ds_read_b128 v[224:227], v169 offset:58624
	s_waitcnt lgkmcnt(7)
	v_mfma_f32_16x16x32_bf16 v[58:61], v[228:231], v[62:65], v[54:57]
	ds_read_b128 v[228:231], v169 offset:59136
	s_waitcnt lgkmcnt(7)
	v_mfma_f32_16x16x32_bf16 v[54:57], v[200:203], v[138:141], 0
	s_waitcnt lgkmcnt(6)
	v_mfma_f32_16x16x32_bf16 v[54:57], v[204:207], v[134:137], v[54:57]
	s_waitcnt lgkmcnt(5)
	v_mfma_f32_16x16x32_bf16 v[54:57], v[208:211], v[130:133], v[54:57]
	s_waitcnt lgkmcnt(4)
	v_mfma_f32_16x16x32_bf16 v[54:57], v[212:215], v[62:65], v[54:57]
	s_waitcnt lgkmcnt(3)
	v_mfma_f32_16x16x32_bf16 v[138:141], v[216:219], v[138:141], 0
	s_waitcnt lgkmcnt(2)
	v_mfma_f32_16x16x32_bf16 v[134:137], v[220:223], v[134:137], v[138:141]
	s_waitcnt lgkmcnt(1)
	v_mfma_f32_16x16x32_bf16 v[130:133], v[224:227], v[130:133], v[134:137]
	s_waitcnt lgkmcnt(0)
	v_mfma_f32_16x16x32_bf16 v[62:65], v[228:231], v[62:65], v[130:133]
	s_nop 7
	s_nop 2
	v_mul_lo_u32 v130, v195, s4
	v_add_u32_e32 v130, 0, v130
	v_add_u32_e32 v135, 0x20400, v130
	v_mov_b32_e32 v132, 0xff800000
	v_lshl_add_u32 v130, v170, 2, v135
	v_mov_b32_e32 v133, 0xff800000
	s_and_saveexec_b64 s[34:35], s[36:37]
	s_cbranch_execz .LBB9_676
	ds_read_b32 v131, v130 offset:928
	s_waitcnt lgkmcnt(0)
	v_add_f32_e32 v133, v126, v131

; #define LAS __attribute__((address_space(3)))
; template <bool LOCAL>
; __device__ __forceinline__ void attn_unit(const bf16_t* Q, const bf16_t* KT, const bf16_t* VT, bf16_t* O, LAS unsigned char* lds, int b, int h, int r, int w, int tq, int lane) {
;     const int g = lane >> 4, q = lane & 15;
;     const int qrow = LOCAL ? (b * SEQ + r * GRID_W + 16 * w + q) : (ML + b * CTX + 16 * tq + q);
;     bf16x8 bq[4];
;     { const bf16_t* qp = Q + (size_t)qrow * D + h * HD + 8 * g;
; #pragma unroll
;       for (int ks = 0; ks < 4; ++ks) bq[ks] = *(const bf16x8*)(qp + 32 * ks); }
;     constexpr int NP = LOCAL ? 16 : 8, CP = LOCAL ? 8 : 0;
;     f32x4 s[2 * NP];
;     int rs = 0, ws = 0;
;     if (LOCAL) { rs = r - 4; rs = rs < 0 ? 0 : (rs > 24 ? 24 : rs); ws = 16 * w - 8; ws = ws < 0 ? 0 : (ws > 32 ? 32 : ws); }
;     const int rgl = b * SEQ + rs * GRID_W + ws;
;     if (LOCAL) {
;         const bf16_t* kloc = KT + ((size_t)(((rgl >> 3) + (q >> 2)) * NH + h)) * 1024 + (q & 3) * 32 + g * 8;
;         bf16x8 ka[2][8];
;     ...
;         ATT_KLOAD(0, 0);
; #pragma unroll
;         for (int p = 0; p < 8; ++p) {
;             __builtin_amdgcn_s_barrier();
;             if (p + 1 < 8) ATT_KLOAD((p + 1) & 1, p + 1);
;             __builtin_amdgcn_sched_barrier(0);
; #pragma unroll
;             for (int f = 0; f < 2; ++f) { f32x4 a = {0.f, 0.f, 0.f, 0.f};
; #pragma unroll
;                 for (int ks = 0; ks < 4; ++ks) a = __builtin_amdgcn_mfma_f32_16x16x32_bf16(ka[p & 1][f * 4 + ks], bq[ks], a, 0, 0, 0);
;                 s[2 * p + f] = a; }
;             __builtin_amdgcn_sched_barrier(0);
;         }
;     ...
;     }
;     {
;         const LAS unsigned char* kl = lds + (q >> 2) * 2048 + (((q & 3) * 4 + g) ^ ((q >> 2) & 2)) * 16;
; #pragma unroll
;         for (int p = 0; p < 8; ++p)
; #pragma unroll
;             for (int f = 0; f < 2; ++f) { f32x4 a = {0.f, 0.f, 0.f, 0.f};
; #pragma unroll
;                 for (int ks = 0; ks < 4; ++ks) a = __builtin_amdgcn_mfma_f32_16x16x32_bf16(*(const LAS bf16x8*)(kl + p * 8192 + ks * 512 + f * 256), bq[ks], a, 0, 0, 0);
;                 s[2 * (CP + p) + f] = a; }
;     }
; __global__ void __launch_bounds__(NTHREADS, 2) mega(Args args) {
;     ...
;                     if (!lastL && wave < 4) attn_unit<false>(Qb, KTp, VTp, Ob, lds, b, h, 0, 0, 4 * qr + wave, lane);
.LBB9_802:
	s_and_b64 vcc, exec, s[24:25]
	s_cbranch_vccz .LBB9_658
	s_and_b32 s4, s70, 3
	s_lshl_b32 s4, s4, 6
	s_add_i32 s71, s71, s4
	v_add_u32_e32 v2, s71, v179
	v_ashrrev_i32_e32 v3, 31, v2
	v_lshlrev_b64 v[78:79], 12, v[2:3]
	v_lshl_add_u64 v[2:3], s[96:97], 0, v[78:79]
	s_lshl_b32 s48, s33, 1
	v_lshl_add_u64 v[2:3], v[2:3], 0, s[48:49]
	v_lshl_add_u64 v[2:3], v[2:3], 0, v[186:187]
	global_load_dwordx4 v[42:45], v[2:3], off
	global_load_dwordx4 v[38:41], v[2:3], off offset:64
	global_load_dwordx4 v[34:37], v[2:3], off offset:128
	global_load_dwordx4 v[30:33], v[2:3], off offset:192
	s_waitcnt lgkmcnt(0)
	v_mov_b32_e32 v157, v187
	ds_read_b128 v[200:203], v180
	ds_read_b128 v[204:207], v180 offset:512
	ds_read_b128 v[208:211], v180 offset:1024
	ds_read_b128 v[212:215], v180 offset:1536
	ds_read_b128 v[216:219], v180 offset:256
	ds_read_b128 v[220:223], v180 offset:768
	ds_read_b128 v[224:227], v180 offset:1280
	ds_read_b128 v[228:231], v180 offset:1792
	s_waitcnt vmcnt(3) lgkmcnt(7)
	v_mfma_f32_16x16x32_bf16 v[2:5], v[200:203], v[42:45], 0
	ds_read_b128 v[200:203], v180 offset:8192
	s_waitcnt vmcnt(2) lgkmcnt(7)
	v_mfma_f32_16x16x32_bf16 v[2:5], v[204:207], v[38:41], v[2:5]
	ds_read_b128 v[204:207], v180 offset:8704
	s_waitcnt vmcnt(1) lgkmcnt(7)
	v_mfma_f32_16x16x32_bf16 v[2:5], v[208:211], v[34:37], v[2:5]
	ds_read_b128 v[208:211], v180 offset:9216
	s_waitcnt vmcnt(0) lgkmcnt(7)
	v_mfma_f32_16x16x32_bf16 v[2:5], v[212:215], v[30:33], v[2:5]
	ds_read_b128 v[212:215], v180 offset:9728
	s_waitcnt lgkmcnt(7)
	v_mfma_f32_16x16x32_bf16 v[6:9], v[216:219], v[42:45], 0
	ds_read_b128 v[216:219], v180 offset:8448
	s_waitcnt lgkmcnt(7)
	v_mfma_f32_16x16x32_bf16 v[6:9], v[220:223], v[38:41], v[6:9]
	ds_read_b128 v[220:223], v180 offset:8960
	s_waitcnt lgkmcnt(7)
	v_mfma_f32_16x16x32_bf16 v[6:9], v[224:227], v[34:37], v[6:9]
	ds_read_b128 v[224:227], v180 offset:9472
	s_waitcnt lgkmcnt(7)
	v_mfma_f32_16x16x32_bf16 v[6:9], v[228:231], v[30:33], v[6:9]
	ds_read_b128 v[228:231], v180 offset:9984
	s_waitcnt lgkmcnt(7)
	v_mfma_f32_16x16x32_bf16 v[10:13], v[200:203], v[42:45], 0
	ds_read_b128 v[200:203], v180 offset:16384
	s_waitcnt lgkmcnt(7)
	v_mfma_f32_16x16x32_bf16 v[10:13], v[204:207], v[38:41], v[10:13]
	ds_read_b128 v[204:207], v180 offset:16896
	s_waitcnt lgkmcnt(7)
	v_mfma_f32_16x16x32_bf16 v[10:13], v[208:211], v[34:37], v[10:13]
	ds_read_b128 v[208:211], v180 offset:17408
	s_waitcnt lgkmcnt(7)
	v_mfma_f32_16x16x32_bf16 v[10:13], v[212:215], v[30:33], v[10:13]
	ds_read_b128 v[212:215], v180 offset:17920
	s_waitcnt lgkmcnt(7)
	v_mfma_f32_16x16x32_bf16 v[14:17], v[216:219], v[42:45], 0
	ds_read_b128 v[216:219], v180 offset:16640
	s_waitcnt lgkmcnt(7)
	v_mfma_f32_16x16x32_bf16 v[14:17], v[220:223], v[38:41], v[14:17]
	ds_read_b128 v[220:223], v180 offset:17152
	s_waitcnt lgkmcnt(7)
	v_mfma_f32_16x16x32_bf16 v[14:17], v[224:227], v[34:37], v[14:17]
	ds_read_b128 v[224:227], v180 offset:17664
	s_waitcnt lgkmcnt(7)
	v_mfma_f32_16x16x32_bf16 v[14:17], v[228:231], v[30:33], v[14:17]
	ds_read_b128 v[228:231], v180 offset:18176
	s_waitcnt lgkmcnt(7)
	v_mfma_f32_16x16x32_bf16 v[18:21], v[200:203], v[42:45], 0
	ds_read_b128 v[200:203], v180 offset:24576
	s_waitcnt lgkmcnt(7)
	v_mfma_f32_16x16x32_bf16 v[18:21], v[204:207], v[38:41], v[18:21]
	ds_read_b128 v[204:207], v180 offset:25088
	s_waitcnt lgkmcnt(7)
	v_mfma_f32_16x16x32_bf16 v[18:21], v[208:211], v[34:37], v[18:21]
	ds_read_b128 v[208:211], v180 offset:25600
	s_waitcnt lgkmcnt(7)
	v_mfma_f32_16x16x32_bf16 v[18:21], v[212:215], v[30:33], v[18:21]
	ds_read_b128 v[212:215], v180 offset:26112
	s_waitcnt lgkmcnt(7)
	v_mfma_f32_16x16x32_bf16 v[22:25], v[216:219], v[42:45], 0
	ds_read_b128 v[216:219], v180 offset:24832
	s_waitcnt lgkmcnt(7)
	v_mfma_f32_16x16x32_bf16 v[22:25], v[220:223], v[38:41], v[22:25]
	ds_read_b128 v[220:223], v180 offset:25344
	s_waitcnt lgkmcnt(7)
	v_mfma_f32_16x16x32_bf16 v[22:25], v[224:227], v[34:37], v[22:25]
	ds_read_b128 v[224:227], v180 offset:25856
	s_waitcnt lgkmcnt(7)
	v_mfma_f32_16x16x32_bf16 v[22:25], v[228:231], v[30:33], v[22:25]
	ds_read_b128 v[228:231], v180 offset:26368
	s_waitcnt lgkmcnt(7)
	v_mfma_f32_16x16x32_bf16 v[26:29], v[200:203], v[42:45], 0
	ds_read_b128 v[200:203], v180 offset:32768
	s_waitcnt lgkmcnt(7)
	v_mfma_f32_16x16x32_bf16 v[26:29], v[204:207], v[38:41], v[26:29]
	ds_read_b128 v[204:207], v180 offset:33280
	s_waitcnt lgkmcnt(7)
	v_mfma_f32_16x16x32_bf16 v[26:29], v[208:211], v[34:37], v[26:29]
	ds_read_b128 v[208:211], v180 offset:33792
	s_waitcnt lgkmcnt(7)
	v_mfma_f32_16x16x32_bf16 v[26:29], v[212:215], v[30:33], v[26:29]
	ds_read_b128 v[212:215], v180 offset:34304
	s_waitcnt lgkmcnt(7)
	v_mfma_f32_16x16x32_bf16 v[46:49], v[216:219], v[42:45], 0
	ds_read_b128 v[216:219], v180 offset:33024
	s_waitcnt lgkmcnt(7)
	v_mfma_f32_16x16x32_bf16 v[46:49], v[220:223], v[38:41], v[46:49]
	ds_read_b128 v[220:223], v180 offset:33536
	s_waitcnt lgkmcnt(7)
	v_mfma_f32_16x16x32_bf16 v[46:49], v[224:227], v[34:37], v[46:49]
	ds_read_b128 v[224:227], v180 offset:34048
	s_waitcnt lgkmcnt(7)
	v_mfma_f32_16x16x32_bf16 v[54:57], v[228:231], v[30:33], v[46:49]
	ds_read_b128 v[228:231], v180 offset:34560
	s_waitcnt lgkmcnt(7)
	v_mfma_f32_16x16x32_bf16 v[46:49], v[200:203], v[42:45], 0
	ds_read_b128 v[200:203], v180 offset:40960
	s_waitcnt lgkmcnt(7)
	v_mfma_f32_16x16x32_bf16 v[46:49], v[204:207], v[38:41], v[46:49]
	ds_read_b128 v[204:207], v180 offset:41472
	s_waitcnt lgkmcnt(7)
	v_mfma_f32_16x16x32_bf16 v[46:49], v[208:211], v[34:37], v[46:49]
	ds_read_b128 v[208:211], v180 offset:41984
	s_waitcnt lgkmcnt(7)
; #define LAS __attribute__((address_space(3)))
; template <bool LOCAL>
; __device__ __forceinline__ void attn_unit(const bf16_t* Q, const bf16_t* KT, const bf16_t* VT, bf16_t* O, LAS unsigned char* lds, int b, int h, int r, int w, int tq, int lane) {
;     ...
;     {
;         const LAS unsigned char* kl = lds + (q >> 2) * 2048 + (((q & 3) * 4 + g) ^ ((q >> 2) & 2)) * 16;
; #pragma unroll
;         for (int p = 0; p < 8; ++p)
; #pragma unroll
;             for (int f = 0; f < 2; ++f) { f32x4 a = {0.f, 0.f, 0.f, 0.f};
; #pragma unroll
;                 for (int ks = 0; ks < 4; ++ks) a = __builtin_amdgcn_mfma_f32_16x16x32_bf16(*(const LAS bf16x8*)(kl + p * 8192 + ks * 512 + f * 256), bq[ks], a, 0, 0, 0);
;                 s[2 * (CP + p) + f] = a; }
;     }
;     if (LOCAL) {
;         const int c = 16 * w + q; int cs = c - 8; cs = cs < 0 ? 0 : (cs > 48 ? 48 : cs);
;         const LAS float* rp = (const LAS float*)(lds + LDS_MISC + 1024);
; #pragma unroll
;         for (int p = 0; p < 8; ++p) { const int ro = (rs + p - r + 7) * 31;
; #pragma unroll
;             for (int f = 0; f < 2; ++f)
; #pragma unroll
;                 for (int j = 0; j < 4; ++j) { const int kc = ws + 8 * g + 4 * f + j; const bool valid = (kc >= cs) && (kc < cs + 16);
;                     int rel = kc - c + 15; rel = rel < 0 ? 0 : (rel > 30 ? 30 : rel);
;                     const float bias = rp[ro + rel];
;                     s[p * 2 + f][j] = valid ? s[p * 2 + f][j] + bias : -INFINITY; } }
;     }
;     float mx = -INFINITY;
; #pragma unroll
;     for (int i = 0; i < 2 * NP; ++i) mx = fmaxf(mx, fmaxf(fmaxf(s[i][0], s[i][1]), fmaxf(s[i][2], s[i][3])));
;     mx = fmaxf(mx, __shfl_xor(mx, 16)); mx = fmaxf(mx, __shfl_xor(mx, 32));
	v_mfma_f32_16x16x32_bf16 v[46:49], v[212:215], v[30:33], v[46:49]
	ds_read_b128 v[212:215], v180 offset:42496
	s_waitcnt lgkmcnt(7)
	v_mfma_f32_16x16x32_bf16 v[50:53], v[216:219], v[42:45], 0
	ds_read_b128 v[216:219], v180 offset:41216
	s_waitcnt lgkmcnt(7)
	v_mfma_f32_16x16x32_bf16 v[50:53], v[220:223], v[38:41], v[50:53]
	ds_read_b128 v[220:223], v180 offset:41728
	s_waitcnt lgkmcnt(7)
	v_mfma_f32_16x16x32_bf16 v[50:53], v[224:227], v[34:37], v[50:53]
	ds_read_b128 v[224:227], v180 offset:42240
	s_waitcnt lgkmcnt(7)
	v_mfma_f32_16x16x32_bf16 v[66:69], v[228:231], v[30:33], v[50:53]
	ds_read_b128 v[228:231], v180 offset:42752
	s_waitcnt lgkmcnt(7)
	v_mfma_f32_16x16x32_bf16 v[50:53], v[200:203], v[42:45], 0
	ds_read_b128 v[200:203], v180 offset:49152
	s_waitcnt lgkmcnt(7)
	v_mfma_f32_16x16x32_bf16 v[50:53], v[204:207], v[38:41], v[50:53]
	ds_read_b128 v[204:207], v180 offset:49664
	s_waitcnt lgkmcnt(7)
	v_mfma_f32_16x16x32_bf16 v[50:53], v[208:211], v[34:37], v[50:53]
	ds_read_b128 v[208:211], v180 offset:50176
	s_waitcnt lgkmcnt(7)
	v_mfma_f32_16x16x32_bf16 v[50:53], v[212:215], v[30:33], v[50:53]
	ds_read_b128 v[212:215], v180 offset:50688
	s_waitcnt lgkmcnt(7)
	v_mfma_f32_16x16x32_bf16 v[58:61], v[216:219], v[42:45], 0
	ds_read_b128 v[216:219], v180 offset:49408
	s_waitcnt lgkmcnt(7)
	v_mfma_f32_16x16x32_bf16 v[58:61], v[220:223], v[38:41], v[58:61]
	ds_read_b128 v[220:223], v180 offset:49920
	s_waitcnt lgkmcnt(7)
	v_mfma_f32_16x16x32_bf16 v[58:61], v[224:227], v[34:37], v[58:61]
	ds_read_b128 v[224:227], v180 offset:50432
	s_waitcnt lgkmcnt(7)
	v_mfma_f32_16x16x32_bf16 v[70:73], v[228:231], v[30:33], v[58:61]
	ds_read_b128 v[228:231], v180 offset:50944
	s_waitcnt lgkmcnt(7)
	v_mfma_f32_16x16x32_bf16 v[58:61], v[200:203], v[42:45], 0
	ds_read_b128 v[200:203], v180 offset:57344
	s_waitcnt lgkmcnt(7)
	v_mfma_f32_16x16x32_bf16 v[58:61], v[204:207], v[38:41], v[58:61]
	ds_read_b128 v[204:207], v180 offset:57856
	s_waitcnt lgkmcnt(7)
	v_mfma_f32_16x16x32_bf16 v[58:61], v[208:211], v[34:37], v[58:61]
	ds_read_b128 v[208:211], v180 offset:58368
	s_waitcnt lgkmcnt(7)
	v_mfma_f32_16x16x32_bf16 v[58:61], v[212:215], v[30:33], v[58:61]
	ds_read_b128 v[212:215], v180 offset:58880
	s_waitcnt lgkmcnt(7)
	v_mfma_f32_16x16x32_bf16 v[62:65], v[216:219], v[42:45], 0
	ds_read_b128 v[216:219], v180 offset:57600
	s_waitcnt lgkmcnt(7)
	v_mfma_f32_16x16x32_bf16 v[62:65], v[220:223], v[38:41], v[62:65]
	ds_read_b128 v[220:223], v180 offset:58112
	s_waitcnt lgkmcnt(7)
	v_mfma_f32_16x16x32_bf16 v[62:65], v[224:227], v[34:37], v[62:65]
	ds_read_b128 v[224:227], v180 offset:58624
	s_waitcnt lgkmcnt(7)
	v_mfma_f32_16x16x32_bf16 v[74:77], v[228:231], v[30:33], v[62:65]
	ds_read_b128 v[228:231], v180 offset:59136
	s_waitcnt lgkmcnt(7)
	v_mfma_f32_16x16x32_bf16 v[62:65], v[200:203], v[42:45], 0
	s_waitcnt lgkmcnt(6)
	v_mfma_f32_16x16x32_bf16 v[62:65], v[204:207], v[38:41], v[62:65]
	s_waitcnt lgkmcnt(5)
	v_mfma_f32_16x16x32_bf16 v[62:65], v[208:211], v[34:37], v[62:65]
	s_waitcnt lgkmcnt(4)
	v_mfma_f32_16x16x32_bf16 v[62:65], v[212:215], v[30:33], v[62:65]
	s_waitcnt lgkmcnt(3)
	v_mfma_f32_16x16x32_bf16 v[42:45], v[216:219], v[42:45], 0
	s_waitcnt lgkmcnt(2)
	v_mfma_f32_16x16x32_bf16 v[38:41], v[220:223], v[38:41], v[42:45]
	s_waitcnt lgkmcnt(1)
	v_mfma_f32_16x16x32_bf16 v[34:37], v[224:227], v[34:37], v[38:41]
	s_waitcnt lgkmcnt(0)
	v_mfma_f32_16x16x32_bf16 v[30:33], v[228:231], v[30:33], v[34:37]
	s_nop 7
	s_nop 2
	v_max_f32_e32 v34, v5, v5
	v_max_f32_e32 v35, v4, v4
	v_max_f32_e32 v34, v35, v34
	v_max_f32_e32 v35, v9, v9
	v_max_f32_e32 v36, v8, v8
	v_max_f32_e32 v35, v36, v35
	v_max3_f32 v34, v2, v3, v34
	v_max3_f32 v35, v6, v7, v35
	v_max3_f32 v34, v34, s16, v35
	v_max_f32_e32 v35, v13, v13
	v_max_f32_e32 v36, v12, v12
	v_max_f32_e32 v35, v36, v35
	v_max_f32_e32 v36, v17, v17
	v_max_f32_e32 v37, v16, v16
	v_max_f32_e32 v36, v37, v36
	v_max3_f32 v35, v10, v11, v35
	v_max3_f32 v36, v14, v15, v36
	v_max3_f32 v34, v34, v35, v36
	v_max_f32_e32 v35, v21, v21
	v_max_f32_e32 v36, v20, v20
	v_max_f32_e32 v35, v36, v35
	v_max_f32_e32 v36, v25, v25
	v_max_f32_e32 v37, v24, v24
	v_max_f32_e32 v36, v37, v36
	v_max3_f32 v35, v18, v19, v35
	v_max3_f32 v36, v22, v23, v36
	v_max3_f32 v34, v34, v35, v36
	v_max_f32_e32 v35, v29, v29
	v_max_f32_e32 v36, v28, v28
	v_max_f32_e32 v35, v36, v35
	v_max_f32_e32 v36, v57, v57
	v_max_f32_e32 v37, v56, v56
	v_max_f32_e32 v36, v37, v36
	v_max3_f32 v35, v26, v27, v35
	v_max3_f32 v36, v54, v55, v36
	v_max3_f32 v34, v34, v35, v36
	v_max_f32_e32 v35, v49, v49
	v_max_f32_e32 v36, v48, v48
	v_max_f32_e32 v35, v36, v35
	v_max_f32_e32 v36, v69, v69
	v_max_f32_e32 v37, v68, v68
	v_max_f32_e32 v36, v37, v36
	v_max3_f32 v35, v46, v47, v35
	v_max3_f32 v36, v66, v67, v36
	v_max3_f32 v34, v34, v35, v36
	v_max_f32_e32 v35, v53, v53
	v_max_f32_e32 v36, v52, v52
	v_max_f32_e32 v35, v36, v35
	v_max_f32_e32 v36, v73, v73
	v_max_f32_e32 v37, v72, v72
	v_max_f32_e32 v36, v37, v36
	v_max3_f32 v35, v50, v51, v35
	v_max3_f32 v36, v70, v71, v36
	v_max3_f32 v34, v34, v35, v36
	v_max_f32_e32 v35, v61, v61
	v_max_f32_e32 v36, v60, v60
	v_max_f32_e32 v35, v36, v35
	v_max_f32_e32 v36, v77, v77
	v_max_f32_e32 v37, v76, v76
	v_max_f32_e32 v36, v37, v36
	v_max3_f32 v35, v58, v59, v35
	v_max3_f32 v36, v74, v75, v36
	v_max3_f32 v34, v34, v35, v36
	v_max_f32_e32 v35, v65, v65
	v_max_f32_e32 v36, v64, v64
	v_max_f32_e32 v35, v36, v35
	v_max_f32_e32 v36, v33, v33
	v_max_f32_e32 v37, v32, v32
	v_max_f32_e32 v36, v37, v36
	v_max3_f32 v35, v62, v63, v35
	v_max3_f32 v36, v30, v31, v36
	v_max3_f32 v34, v34, v35, v36
	ds_bpermute_b32 v35, v181, v34
	s_waitcnt lgkmcnt(0)
; __device__ __forceinline__ unsigned cvt_pk_bf16(float lo, float hi) { unsigned r; asm volatile("v_cvt_pk_bf16_f32 %0, %1, %2" : "=v"(r) : "v"(lo), "v"(hi)); return r; }
; __device__ __forceinline__ float fast_exp2(float x) { return __builtin_amdgcn_exp2f(x); }
; template <bool LOCAL>
; __device__ __forceinline__ void attn_unit(const bf16_t* Q, const bf16_t* KT, const bf16_t* VT, bf16_t* O, LAS unsigned char* lds, int b, int h, int r, int w, int tq, int lane) {
;     ...
;     mx = fmaxf(mx, __shfl_xor(mx, 16)); mx = fmaxf(mx, __shfl_xor(mx, 32));
;     float sum = 0.f; const float mxl = mx * 1.4426950408889634f;
;     bf16x8 pb[NP];
; #pragma unroll
;     for (int p = 0; p < NP; ++p) { float e[8];
; #pragma unroll
;         for (int f = 0; f < 2; ++f)
; #pragma unroll
;             for (int j = 0; j < 4; ++j) { e[4 * f + j] = fast_exp2(fmaf(s[2 * p + f][j], 1.4426950408889634f, -mxl)); sum += e[4 * f + j]; }
;         u32x4 pw; pw.x = cvt_pk_bf16(e[0], e[1]); pw.y = cvt_pk_bf16(e[2], e[3]); pw.z = cvt_pk_bf16(e[4], e[5]); pw.w = cvt_pk_bf16(e[6], e[7]);
;         pb[p] = __builtin_bit_cast(bf16x8, pw); }
;     sum += __shfl_xor(sum, 16); sum += __shfl_xor(sum, 32);
	v_max_f32_e32 v35, v35, v35
	v_max_f32_e32 v34, v34, v35
	ds_bpermute_b32 v35, v182, v34
	s_waitcnt lgkmcnt(0)
	v_max_f32_e32 v35, v35, v35
	v_max_f32_e32 v34, v34, v35
	v_mul_f32_e32 v42, 0xbfb8aa3b, v34
	v_fmamk_f32 v2, v2, 0x3fb8aa3b, v42
	v_exp_f32_e32 v2, v2
	v_fmamk_f32 v3, v3, 0x3fb8aa3b, v42
	v_exp_f32_e32 v3, v3
	v_fmamk_f32 v4, v4, 0x3fb8aa3b, v42
	v_exp_f32_e32 v4, v4
	v_fmamk_f32 v5, v5, 0x3fb8aa3b, v42
	v_exp_f32_e32 v5, v5
	v_fmamk_f32 v6, v6, 0x3fb8aa3b, v42
	v_add_f32_e32 v34, 0, v2
	v_exp_f32_e32 v6, v6
	v_fmamk_f32 v7, v7, 0x3fb8aa3b, v42
	v_add_f32_e32 v34, v3, v34
	v_exp_f32_e32 v7, v7
	v_fmamk_f32 v8, v8, 0x3fb8aa3b, v42
	v_add_f32_e32 v34, v4, v34
	v_exp_f32_e32 v8, v8
	v_fmamk_f32 v9, v9, 0x3fb8aa3b, v42
	v_add_f32_e32 v34, v5, v34
	v_exp_f32_e32 v9, v9
	v_cvt_pk_bf16_f32 v38, v2, v3
	v_fmamk_f32 v2, v10, 0x3fb8aa3b, v42
	v_add_f32_e32 v34, v6, v34
	v_cvt_pk_bf16_f32 v39, v4, v5
	v_exp_f32_e32 v2, v2
	v_fmamk_f32 v4, v11, 0x3fb8aa3b, v42
	v_add_f32_e32 v34, v7, v34
	v_exp_f32_e32 v4, v4
	v_fmamk_f32 v5, v12, 0x3fb8aa3b, v42
	v_add_f32_e32 v34, v8, v34
	v_cvt_pk_bf16_f32 v40, v6, v7
	v_exp_f32_e32 v5, v5
	v_fmamk_f32 v6, v13, 0x3fb8aa3b, v42
	v_add_f32_e32 v34, v9, v34
	v_exp_f32_e32 v6, v6
	v_fmamk_f32 v7, v14, 0x3fb8aa3b, v42
	v_cvt_pk_bf16_f32 v41, v8, v9
	v_add_f32_e32 v3, v2, v34
	v_exp_f32_e32 v7, v7
	v_fmamk_f32 v8, v15, 0x3fb8aa3b, v42
	v_add_f32_e32 v3, v4, v3
	v_exp_f32_e32 v8, v8
	v_fmamk_f32 v9, v16, 0x3fb8aa3b, v42
	v_add_f32_e32 v3, v5, v3
	v_exp_f32_e32 v9, v9
	v_fmamk_f32 v10, v17, 0x3fb8aa3b, v42
	v_add_f32_e32 v3, v6, v3
	v_exp_f32_e32 v10, v10
	v_cvt_pk_bf16_f32 v34, v2, v4
	v_fmamk_f32 v2, v18, 0x3fb8aa3b, v42
	v_add_f32_e32 v3, v7, v3
	v_exp_f32_e32 v2, v2
	v_fmamk_f32 v4, v19, 0x3fb8aa3b, v42
	v_add_f32_e32 v3, v8, v3
	v_cvt_pk_bf16_f32 v35, v5, v6
	v_exp_f32_e32 v4, v4
	v_fmamk_f32 v5, v20, 0x3fb8aa3b, v42
	v_add_f32_e32 v3, v9, v3
	v_exp_f32_e32 v5, v5
	v_fmamk_f32 v6, v21, 0x3fb8aa3b, v42
	v_add_f32_e32 v3, v10, v3
	v_cvt_pk_bf16_f32 v36, v7, v8
	v_exp_f32_e32 v6, v6
	v_fmamk_f32 v7, v22, 0x3fb8aa3b, v42
	v_add_f32_e32 v3, v2, v3
	v_exp_f32_e32 v7, v7
	v_fmamk_f32 v8, v23, 0x3fb8aa3b, v42
	v_cvt_pk_bf16_f32 v37, v9, v10
	v_add_f32_e32 v3, v4, v3
	v_exp_f32_e32 v8, v8
	v_fmamk_f32 v9, v24, 0x3fb8aa3b, v42
	v_add_f32_e32 v3, v5, v3
	v_exp_f32_e32 v9, v9
	v_fmamk_f32 v10, v25, 0x3fb8aa3b, v42
	v_add_f32_e32 v3, v6, v3
	v_exp_f32_e32 v10, v10
	v_cvt_pk_bf16_f32 v22, v2, v4
	v_fmamk_f32 v2, v26, 0x3fb8aa3b, v42
	v_add_f32_e32 v3, v7, v3
	v_exp_f32_e32 v2, v2
	v_fmamk_f32 v4, v27, 0x3fb8aa3b, v42
	v_add_f32_e32 v3, v8, v3
	v_cvt_pk_bf16_f32 v23, v5, v6
	v_exp_f32_e32 v4, v4
	v_fmamk_f32 v5, v28, 0x3fb8aa3b, v42
	v_add_f32_e32 v3, v9, v3
	v_exp_f32_e32 v5, v5
	v_fmamk_f32 v6, v29, 0x3fb8aa3b, v42
	v_add_f32_e32 v3, v10, v3
	v_cvt_pk_bf16_f32 v24, v7, v8
	v_exp_f32_e32 v6, v6
	v_fmamk_f32 v7, v54, 0x3fb8aa3b, v42
	v_add_f32_e32 v3, v2, v3
	v_exp_f32_e32 v7, v7
	v_fmamk_f32 v8, v55, 0x3fb8aa3b, v42
	v_cvt_pk_bf16_f32 v25, v9, v10
	v_add_f32_e32 v3, v4, v3
	v_exp_f32_e32 v8, v8
	v_fmamk_f32 v9, v56, 0x3fb8aa3b, v42
	v_add_f32_e32 v3, v5, v3
	v_exp_f32_e32 v9, v9
	v_fmamk_f32 v10, v57, 0x3fb8aa3b, v42
	v_add_f32_e32 v3, v6, v3
	v_exp_f32_e32 v10, v10
	v_cvt_pk_bf16_f32 v18, v2, v4
	v_fmamk_f32 v2, v46, 0x3fb8aa3b, v42
	v_add_f32_e32 v3, v7, v3
	v_exp_f32_e32 v2, v2
	v_fmamk_f32 v4, v47, 0x3fb8aa3b, v42
	v_add_f32_e32 v3, v8, v3
	v_cvt_pk_bf16_f32 v19, v5, v6
	v_exp_f32_e32 v4, v4
	v_fmamk_f32 v5, v48, 0x3fb8aa3b, v42
	v_add_f32_e32 v3, v9, v3
	v_exp_f32_e32 v5, v5
	v_fmamk_f32 v6, v49, 0x3fb8aa3b, v42
	v_add_f32_e32 v3, v10, v3
	v_cvt_pk_bf16_f32 v20, v7, v8
	v_exp_f32_e32 v6, v6
	v_fmamk_f32 v7, v66, 0x3fb8aa3b, v42
	v_add_f32_e32 v3, v2, v3
	v_exp_f32_e32 v7, v7
	v_fmamk_f32 v8, v67, 0x3fb8aa3b, v42
	v_cvt_pk_bf16_f32 v21, v9, v10
	v_add_f32_e32 v3, v4, v3
	v_exp_f32_e32 v8, v8
	v_fmamk_f32 v9, v68, 0x3fb8aa3b, v42
	v_add_f32_e32 v3, v5, v3
	v_exp_f32_e32 v9, v9
	v_fmamk_f32 v10, v69, 0x3fb8aa3b, v42
	v_add_f32_e32 v3, v6, v3
	v_exp_f32_e32 v10, v10
	v_cvt_pk_bf16_f32 v14, v2, v4
	v_fmamk_f32 v2, v50, 0x3fb8aa3b, v42
	v_add_f32_e32 v3, v7, v3
	v_exp_f32_e32 v2, v2
	v_fmamk_f32 v4, v51, 0x3fb8aa3b, v42
	v_add_f32_e32 v3, v8, v3
	v_cvt_pk_bf16_f32 v15, v5, v6
	v_exp_f32_e32 v4, v4
	v_fmamk_f32 v5, v52, 0x3fb8aa3b, v42
	v_add_f32_e32 v3, v9, v3
	v_exp_f32_e32 v5, v5
	v_fmamk_f32 v6, v53, 0x3fb8aa3b, v42
	v_add_f32_e32 v3, v10, v3
	v_cvt_pk_bf16_f32 v16, v7, v8
	v_exp_f32_e32 v6, v6
	v_fmamk_f32 v7, v70, 0x3fb8aa3b, v42
	v_add_f32_e32 v3, v2, v3
	v_exp_f32_e32 v7, v7
	v_fmamk_f32 v8, v71, 0x3fb8aa3b, v42
	v_cvt_pk_bf16_f32 v17, v9, v10
	v_add_f32_e32 v3, v4, v3
	v_exp_f32_e32 v8, v8
	v_fmamk_f32 v9, v72, 0x3fb8aa3b, v42
	v_add_f32_e32 v3, v5, v3
	v_exp_f32_e32 v9, v9
	v_fmamk_f32 v10, v73, 0x3fb8aa3b, v42
	v_add_f32_e32 v3, v6, v3
	v_exp_f32_e32 v13, v10
	v_cvt_pk_bf16_f32 v10, v2, v4
	v_fmamk_f32 v2, v58, 0x3fb8aa3b, v42
	v_add_f32_e32 v3, v7, v3
	v_exp_f32_e32 v2, v2
	v_fmamk_f32 v4, v59, 0x3fb8aa3b, v42
	v_add_f32_e32 v3, v8, v3
	v_cvt_pk_bf16_f32 v11, v5, v6
	v_exp_f32_e32 v4, v4
	v_fmamk_f32 v5, v60, 0x3fb8aa3b, v42
	v_add_f32_e32 v3, v9, v3
	v_exp_f32_e32 v5, v5
	v_fmamk_f32 v6, v61, 0x3fb8aa3b, v42
	v_add_f32_e32 v3, v13, v3
	v_cvt_pk_bf16_f32 v12, v7, v8
	v_exp_f32_e32 v7, v6
	v_fmamk_f32 v6, v74, 0x3fb8aa3b, v42
	v_add_f32_e32 v3, v2, v3
	v_exp_f32_e32 v8, v6
	v_fmamk_f32 v6, v75, 0x3fb8aa3b, v42
	v_cvt_pk_bf16_f32 v13, v9, v13
	v_add_f32_e32 v3, v4, v3
	v_exp_f32_e32 v9, v6
	v_fmamk_f32 v6, v76, 0x3fb8aa3b, v42
	v_add_f32_e32 v3, v5, v3
	v_exp_f32_e32 v26, v6
	v_fmamk_f32 v6, v77, 0x3fb8aa3b, v42
	v_add_f32_e32 v3, v7, v3
	v_exp_f32_e32 v27, v6
	v_cvt_pk_bf16_f32 v6, v2, v4
	v_fmamk_f32 v2, v62, 0x3fb8aa3b, v42
	v_add_f32_e32 v3, v8, v3
	v_exp_f32_e32 v2, v2
	v_fmamk_f32 v4, v63, 0x3fb8aa3b, v42
	v_add_f32_e32 v3, v9, v3
	v_cvt_pk_bf16_f32 v7, v5, v7
	v_exp_f32_e32 v4, v4
	v_fmamk_f32 v5, v64, 0x3fb8aa3b, v42
	v_add_f32_e32 v3, v26, v3
	v_cvt_pk_bf16_f32 v8, v8, v9
	v_cvt_pk_bf16_f32 v9, v26, v27
	v_exp_f32_e32 v5, v5
	v_fmamk_f32 v26, v65, 0x3fb8aa3b, v42
	v_add_f32_e32 v3, v27, v3
	v_exp_f32_e32 v26, v26
	v_fmamk_f32 v27, v30, 0x3fb8aa3b, v42
	v_add_f32_e32 v3, v2, v3
	v_exp_f32_e32 v27, v27
	v_fmamk_f32 v28, v31, 0x3fb8aa3b, v42
	v_add_f32_e32 v3, v4, v3
	v_exp_f32_e32 v28, v28
	v_fmamk_f32 v29, v32, 0x3fb8aa3b, v42
	v_add_f32_e32 v3, v5, v3
	v_exp_f32_e32 v29, v29
	v_fmac_f32_e32 v42, 0x3fb8aa3b, v33
	v_add_f32_e32 v3, v26, v3
	v_exp_f32_e32 v30, v42
	v_add_f32_e32 v3, v27, v3
	v_add_f32_e32 v3, v28, v3
	v_add_f32_e32 v3, v29, v3
	v_add_f32_e32 v31, v30, v3
	v_cvt_pk_bf16_f32 v2, v2, v4
	v_cvt_pk_bf16_f32 v3, v5, v26
	ds_bpermute_b32 v26, v181, v31
	v_cvt_pk_bf16_f32 v4, v27, v28
	v_cvt_pk_bf16_f32 v5, v29, v30
	s_waitcnt lgkmcnt(0)
; #define LAS __attribute__((address_space(3)))
; template <bool LOCAL>
; __device__ __forceinline__ void attn_unit(const bf16_t* Q, const bf16_t* KT, const bf16_t* VT, bf16_t* O, LAS unsigned char* lds, int b, int h, int r, int w, int tq, int lane) {
;     ...
;     {
;         const LAS unsigned char* vl = lds + 65536 + g * 2048 + q * 16;
; #pragma unroll
;         for (int p = 0; p < 8; ++p)
; #pragma unroll
;             for (int df = 0; df < 8; ++df) o[df] = __builtin_amdgcn_mfma_f32_16x16x32_bf16(*(const LAS bf16x8*)(vl + p * 8192 + df * 256), pb[CP + p], o[df], 0, 0, 0);
;     }
	v_add_f32_e32 v26, v31, v26
	ds_bpermute_b32 v27, v182, v26
	ds_read_b128 v[200:203], v178
	ds_read_b128 v[204:207], v178 offset:256
	ds_read_b128 v[208:211], v178 offset:512
	ds_read_b128 v[212:215], v178 offset:768
	ds_read_b128 v[216:219], v178 offset:1024
	ds_read_b128 v[220:223], v178 offset:1280
	ds_read_b128 v[224:227], v178 offset:1536
	ds_read_b128 v[228:231], v178 offset:1792
	s_waitcnt lgkmcnt(7)
	v_mfma_f32_16x16x32_bf16 v[28:31], v[200:203], v[38:41], 0
	ds_read_b128 v[200:203], v178 offset:8192
	s_waitcnt lgkmcnt(7)
	v_mfma_f32_16x16x32_bf16 v[42:45], v[204:207], v[38:41], 0
	ds_read_b128 v[204:207], v178 offset:8448
	s_waitcnt lgkmcnt(7)
	v_mfma_f32_16x16x32_bf16 v[46:49], v[208:211], v[38:41], 0
	ds_read_b128 v[208:211], v178 offset:8704
	s_waitcnt lgkmcnt(7)
	v_mfma_f32_16x16x32_bf16 v[50:53], v[212:215], v[38:41], 0
	ds_read_b128 v[212:215], v178 offset:8960
	s_waitcnt lgkmcnt(7)
	v_mfma_f32_16x16x32_bf16 v[54:57], v[216:219], v[38:41], 0
	ds_read_b128 v[216:219], v178 offset:9216
	s_waitcnt lgkmcnt(7)
	v_mfma_f32_16x16x32_bf16 v[58:61], v[220:223], v[38:41], 0
	ds_read_b128 v[220:223], v178 offset:9472
	s_waitcnt lgkmcnt(7)
	v_mfma_f32_16x16x32_bf16 v[62:65], v[224:227], v[38:41], 0
	ds_read_b128 v[224:227], v178 offset:9728
	s_waitcnt lgkmcnt(7)
	v_mfma_f32_16x16x32_bf16 v[38:41], v[228:231], v[38:41], 0
	ds_read_b128 v[228:231], v178 offset:9984
	s_waitcnt lgkmcnt(7)
	v_mfma_f32_16x16x32_bf16 v[28:31], v[200:203], v[34:37], v[28:31]
	ds_read_b128 v[200:203], v178 offset:16384
	s_waitcnt lgkmcnt(7)
	v_mfma_f32_16x16x32_bf16 v[42:45], v[204:207], v[34:37], v[42:45]
	ds_read_b128 v[204:207], v178 offset:16640
	s_waitcnt lgkmcnt(7)
	v_mfma_f32_16x16x32_bf16 v[46:49], v[208:211], v[34:37], v[46:49]
	ds_read_b128 v[208:211], v178 offset:16896
	s_waitcnt lgkmcnt(7)
	v_mfma_f32_16x16x32_bf16 v[50:53], v[212:215], v[34:37], v[50:53]
	ds_read_b128 v[212:215], v178 offset:17152
	s_waitcnt lgkmcnt(7)
	v_mfma_f32_16x16x32_bf16 v[54:57], v[216:219], v[34:37], v[54:57]
	ds_read_b128 v[216:219], v178 offset:17408
	s_waitcnt lgkmcnt(7)
	v_mfma_f32_16x16x32_bf16 v[58:61], v[220:223], v[34:37], v[58:61]
	ds_read_b128 v[220:223], v178 offset:17664
	s_waitcnt lgkmcnt(7)
	v_mfma_f32_16x16x32_bf16 v[62:65], v[224:227], v[34:37], v[62:65]
	ds_read_b128 v[224:227], v178 offset:17920
	s_waitcnt lgkmcnt(7)
	v_mfma_f32_16x16x32_bf16 v[32:35], v[228:231], v[34:37], v[38:41]
	ds_read_b128 v[228:231], v178 offset:18176
	s_waitcnt lgkmcnt(7)
	v_mfma_f32_16x16x32_bf16 v[28:31], v[200:203], v[22:25], v[28:31]
	ds_read_b128 v[200:203], v178 offset:24576
	s_waitcnt lgkmcnt(7)
	v_mfma_f32_16x16x32_bf16 v[36:39], v[204:207], v[22:25], v[42:45]
	ds_read_b128 v[204:207], v178 offset:24832
	s_waitcnt lgkmcnt(7)
	v_mfma_f32_16x16x32_bf16 v[40:43], v[208:211], v[22:25], v[46:49]
	ds_read_b128 v[208:211], v178 offset:25088
	s_waitcnt lgkmcnt(7)
	v_mfma_f32_16x16x32_bf16 v[44:47], v[212:215], v[22:25], v[50:53]
	ds_read_b128 v[212:215], v178 offset:25344
	s_waitcnt lgkmcnt(7)
	v_mfma_f32_16x16x32_bf16 v[48:51], v[216:219], v[22:25], v[54:57]
	ds_read_b128 v[216:219], v178 offset:25600
	s_waitcnt lgkmcnt(7)
	v_mfma_f32_16x16x32_bf16 v[52:55], v[220:223], v[22:25], v[58:61]
	ds_read_b128 v[220:223], v178 offset:25856
	s_waitcnt lgkmcnt(7)
	v_mfma_f32_16x16x32_bf16 v[56:59], v[224:227], v[22:25], v[62:65]
	ds_read_b128 v[224:227], v178 offset:26112
	s_waitcnt lgkmcnt(7)
	v_mfma_f32_16x16x32_bf16 v[22:25], v[228:231], v[22:25], v[32:35]
	ds_read_b128 v[228:231], v178 offset:26368
	s_waitcnt lgkmcnt(7)
	v_mfma_f32_16x16x32_bf16 v[28:31], v[200:203], v[18:21], v[28:31]
	ds_read_b128 v[200:203], v178 offset:32768
	s_waitcnt lgkmcnt(7)
	v_mfma_f32_16x16x32_bf16 v[32:35], v[204:207], v[18:21], v[36:39]
	ds_read_b128 v[204:207], v178 offset:33024
	s_waitcnt lgkmcnt(7)
	v_mfma_f32_16x16x32_bf16 v[36:39], v[208:211], v[18:21], v[40:43]
	ds_read_b128 v[208:211], v178 offset:33280
	s_waitcnt lgkmcnt(7)
	v_mfma_f32_16x16x32_bf16 v[40:43], v[212:215], v[18:21], v[44:47]
	ds_read_b128 v[212:215], v178 offset:33536
	s_waitcnt lgkmcnt(7)
	v_mfma_f32_16x16x32_bf16 v[44:47], v[216:219], v[18:21], v[48:51]
	ds_read_b128 v[216:219], v178 offset:33792
	s_waitcnt lgkmcnt(7)
	v_mfma_f32_16x16x32_bf16 v[48:51], v[220:223], v[18:21], v[52:55]
	ds_read_b128 v[220:223], v178 offset:34048
	s_waitcnt lgkmcnt(7)
	v_mfma_f32_16x16x32_bf16 v[52:55], v[224:227], v[18:21], v[56:59]
	ds_read_b128 v[224:227], v178 offset:34304
	s_waitcnt lgkmcnt(7)
	v_mfma_f32_16x16x32_bf16 v[18:21], v[228:231], v[18:21], v[22:25]
	ds_read_b128 v[228:231], v178 offset:34560
	s_waitcnt lgkmcnt(7)
	v_mfma_f32_16x16x32_bf16 v[22:25], v[200:203], v[14:17], v[28:31]
	ds_read_b128 v[200:203], v178 offset:40960
	s_waitcnt lgkmcnt(7)
	v_mfma_f32_16x16x32_bf16 v[28:31], v[204:207], v[14:17], v[32:35]
	ds_read_b128 v[204:207], v178 offset:41216
	s_waitcnt lgkmcnt(7)
	v_mfma_f32_16x16x32_bf16 v[32:35], v[208:211], v[14:17], v[36:39]
	ds_read_b128 v[208:211], v178 offset:41472
	s_waitcnt lgkmcnt(7)
	v_mfma_f32_16x16x32_bf16 v[36:39], v[212:215], v[14:17], v[40:43]
	ds_read_b128 v[212:215], v178 offset:41728
	s_waitcnt lgkmcnt(7)
	v_mfma_f32_16x16x32_bf16 v[40:43], v[216:219], v[14:17], v[44:47]
	ds_read_b128 v[216:219], v178 offset:41984
	s_waitcnt lgkmcnt(7)
	v_mfma_f32_16x16x32_bf16 v[44:47], v[220:223], v[14:17], v[48:51]
	ds_read_b128 v[220:223], v178 offset:42240
	s_waitcnt lgkmcnt(7)
; #define LAS __attribute__((address_space(3)))
; __device__ __forceinline__ unsigned cvt_pk_bf16(float lo, float hi) { unsigned r; asm volatile("v_cvt_pk_bf16_f32 %0, %1, %2" : "=v"(r) : "v"(lo), "v"(hi)); return r; }
; template <bool LOCAL>
; __device__ __forceinline__ void attn_unit(const bf16_t* Q, const bf16_t* KT, const bf16_t* VT, bf16_t* O, LAS unsigned char* lds, int b, int h, int r, int w, int tq, int lane) {
;     ...
;     {
;         const LAS unsigned char* vl = lds + 65536 + g * 2048 + q * 16;
; #pragma unroll
;         for (int p = 0; p < 8; ++p)
; #pragma unroll
;             for (int df = 0; df < 8; ++df) o[df] = __builtin_amdgcn_mfma_f32_16x16x32_bf16(*(const LAS bf16x8*)(vl + p * 8192 + df * 256), pb[CP + p], o[df], 0, 0, 0);
;     }
;     const float inv = 1.f / sum;
;     bf16_t* op = O + (size_t)qrow * D + h * HD + 4 * g;
; #pragma unroll
;     for (int df = 0; df < 8; ++df) { u32x2 wv; wv.x = cvt_pk_bf16(o[df][0] * inv, o[df][1] * inv); wv.y = cvt_pk_bf16(o[df][2] * inv, o[df][3] * inv); *(u32x2*)(op + 16 * df) = wv; }
	v_mfma_f32_16x16x32_bf16 v[48:51], v[224:227], v[14:17], v[52:55]
	ds_read_b128 v[224:227], v178 offset:42496
	s_waitcnt lgkmcnt(7)
	v_mfma_f32_16x16x32_bf16 v[14:17], v[228:231], v[14:17], v[18:21]
	ds_read_b128 v[228:231], v178 offset:42752
	s_waitcnt lgkmcnt(7)
	v_mfma_f32_16x16x32_bf16 v[18:21], v[200:203], v[10:13], v[22:25]
	ds_read_b128 v[200:203], v178 offset:49152
	s_waitcnt lgkmcnt(7)
	v_mfma_f32_16x16x32_bf16 v[22:25], v[204:207], v[10:13], v[28:31]
	ds_read_b128 v[204:207], v178 offset:49408
	s_waitcnt lgkmcnt(7)
	v_mfma_f32_16x16x32_bf16 v[28:31], v[208:211], v[10:13], v[32:35]
	ds_read_b128 v[208:211], v178 offset:49664
	s_waitcnt lgkmcnt(7)
	v_mfma_f32_16x16x32_bf16 v[32:35], v[212:215], v[10:13], v[36:39]
	ds_read_b128 v[212:215], v178 offset:49920
	s_waitcnt lgkmcnt(7)
	v_mfma_f32_16x16x32_bf16 v[36:39], v[216:219], v[10:13], v[40:43]
	ds_read_b128 v[216:219], v178 offset:50176
	s_waitcnt lgkmcnt(7)
	v_mfma_f32_16x16x32_bf16 v[40:43], v[220:223], v[10:13], v[44:47]
	ds_read_b128 v[220:223], v178 offset:50432
	s_waitcnt lgkmcnt(7)
	v_mfma_f32_16x16x32_bf16 v[44:47], v[224:227], v[10:13], v[48:51]
	ds_read_b128 v[224:227], v178 offset:50688
	s_waitcnt lgkmcnt(7)
	v_mfma_f32_16x16x32_bf16 v[10:13], v[228:231], v[10:13], v[14:17]
	ds_read_b128 v[228:231], v178 offset:50944
	s_waitcnt lgkmcnt(7)
	v_mfma_f32_16x16x32_bf16 v[14:17], v[200:203], v[6:9], v[18:21]
	ds_read_b128 v[200:203], v178 offset:57344
	s_waitcnt lgkmcnt(7)
	v_mfma_f32_16x16x32_bf16 v[18:21], v[204:207], v[6:9], v[22:25]
	ds_read_b128 v[204:207], v178 offset:57600
	s_waitcnt lgkmcnt(7)
	v_mfma_f32_16x16x32_bf16 v[22:25], v[208:211], v[6:9], v[28:31]
	ds_read_b128 v[208:211], v178 offset:57856
	s_waitcnt lgkmcnt(7)
	v_mfma_f32_16x16x32_bf16 v[28:31], v[212:215], v[6:9], v[32:35]
	ds_read_b128 v[212:215], v178 offset:58112
	s_waitcnt lgkmcnt(7)
	v_mfma_f32_16x16x32_bf16 v[32:35], v[216:219], v[6:9], v[36:39]
	ds_read_b128 v[216:219], v178 offset:58368
	s_waitcnt lgkmcnt(7)
	v_mfma_f32_16x16x32_bf16 v[36:39], v[220:223], v[6:9], v[40:43]
	ds_read_b128 v[220:223], v178 offset:58624
	s_waitcnt lgkmcnt(7)
	v_mfma_f32_16x16x32_bf16 v[40:43], v[224:227], v[6:9], v[44:47]
	ds_read_b128 v[224:227], v178 offset:58880
	s_waitcnt lgkmcnt(7)
	v_mfma_f32_16x16x32_bf16 v[6:9], v[228:231], v[6:9], v[10:13]
	ds_read_b128 v[228:231], v178 offset:59136
	s_waitcnt lgkmcnt(7)
	v_mfma_f32_16x16x32_bf16 v[10:13], v[200:203], v[2:5], v[14:17]
	s_waitcnt lgkmcnt(6)
	v_mfma_f32_16x16x32_bf16 v[14:17], v[204:207], v[2:5], v[18:21]
	s_waitcnt lgkmcnt(5)
	v_mfma_f32_16x16x32_bf16 v[18:21], v[208:211], v[2:5], v[22:25]
	s_waitcnt lgkmcnt(4)
	v_mfma_f32_16x16x32_bf16 v[22:25], v[212:215], v[2:5], v[28:31]
	s_waitcnt lgkmcnt(3)
	v_mfma_f32_16x16x32_bf16 v[28:31], v[216:219], v[2:5], v[32:35]
	s_waitcnt lgkmcnt(2)
	v_mfma_f32_16x16x32_bf16 v[32:35], v[220:223], v[2:5], v[36:39]
	s_waitcnt lgkmcnt(1)
	v_mfma_f32_16x16x32_bf16 v[36:39], v[224:227], v[2:5], v[40:43]
	s_waitcnt lgkmcnt(0)
	v_mfma_f32_16x16x32_bf16 v[2:5], v[228:231], v[2:5], v[6:9]
	s_nop 7
	s_nop 2
	v_add_f32_e32 v6, v26, v27
	v_div_scale_f32 v7, s[4:5], v6, v6, 1.0
	v_rcp_f32_e32 v8, v7
	s_nop 0
	v_fma_f32 v9, -v7, v8, 1.0
	v_fmac_f32_e32 v8, v9, v8
	v_div_scale_f32 v9, vcc, 1.0, v6, 1.0
	v_mul_f32_e32 v26, v9, v8
	v_fma_f32 v27, -v7, v26, v9
	v_fmac_f32_e32 v26, v27, v8
	v_fma_f32 v7, -v7, v26, v9
	v_div_fmas_f32 v7, v7, v8, v26
	v_div_fixup_f32 v26, v7, v6, 1.0
	v_lshl_add_u64 v[6:7], s[92:93], 0, v[78:79]
	v_mul_f32_e32 v8, v26, v10
	v_mul_f32_e32 v9, v26, v11
	v_lshl_add_u64 v[6:7], v[6:7], 0, s[48:49]
	v_cvt_pk_bf16_f32 v8, v8, v9
	v_mul_f32_e32 v9, v26, v12
	v_lshl_add_u64 v[6:7], v[6:7], 0, v[156:157]
	v_mul_f32_e32 v10, v26, v13
	v_cvt_pk_bf16_f32 v9, v9, v10
	global_store_dwordx2 v[6:7], v[8:9], off
	v_mul_f32_e32 v8, v26, v14
	v_mul_f32_e32 v9, v26, v15
	v_cvt_pk_bf16_f32 v8, v8, v9
	v_mul_f32_e32 v9, v26, v16
	v_mul_f32_e32 v10, v26, v17
	v_cvt_pk_bf16_f32 v9, v9, v10
	global_store_dwordx2 v[6:7], v[8:9], off offset:32
	v_mul_f32_e32 v8, v26, v18
	v_mul_f32_e32 v9, v26, v19
	v_cvt_pk_bf16_f32 v8, v8, v9
	v_mul_f32_e32 v9, v26, v20
	v_mul_f32_e32 v10, v26, v21
	v_cvt_pk_bf16_f32 v9, v9, v10
	global_store_dwordx2 v[6:7], v[8:9], off offset:64
	v_mul_f32_e32 v8, v26, v22
	v_mul_f32_e32 v9, v26, v23
	v_cvt_pk_bf16_f32 v8, v8, v9
	v_mul_f32_e32 v9, v26, v24
	v_mul_f32_e32 v10, v26, v25
	v_cvt_pk_bf16_f32 v9, v9, v10
	global_store_dwordx2 v[6:7], v[8:9], off offset:96
	v_mul_f32_e32 v8, v26, v28
	v_mul_f32_e32 v9, v26, v29
	v_cvt_pk_bf16_f32 v8, v8, v9
	v_mul_f32_e32 v9, v26, v30
	v_mul_f32_e32 v10, v26, v31
	v_cvt_pk_bf16_f32 v9, v9, v10
	global_store_dwordx2 v[6:7], v[8:9], off offset:128
	v_mul_f32_e32 v8, v26, v32
	v_mul_f32_e32 v9, v26, v33
	v_cvt_pk_bf16_f32 v8, v8, v9
	v_mul_f32_e32 v9, v26, v34
	v_mul_f32_e32 v10, v26, v35
	v_cvt_pk_bf16_f32 v9, v9, v10
	global_store_dwordx2 v[6:7], v[8:9], off offset:160
	v_mul_f32_e32 v8, v26, v36
	v_mul_f32_e32 v9, v26, v37
	v_cvt_pk_bf16_f32 v8, v8, v9
	v_mul_f32_e32 v9, v26, v38
	v_mul_f32_e32 v2, v26, v2
	v_mul_f32_e32 v3, v26, v3
	v_mul_f32_e32 v10, v26, v39
	v_cvt_pk_bf16_f32 v9, v9, v10
	global_store_dwordx2 v[6:7], v[8:9], off offset:192
	v_cvt_pk_bf16_f32 v2, v2, v3
	v_mul_f32_e32 v3, v26, v4
	v_mul_f32_e32 v4, v26, v5
	v_cvt_pk_bf16_f32 v3, v3, v4
	global_store_dwordx2 v[6:7], v[2:3], off offset:224
	s_branch .LBB9_658
